# K-loop post-MMA barrier moved one MFMA earlier; grid-barrier XCD leader releases before its own L1/L2 invalidate
# speedup vs baseline: 1.0008x; 1.0008x over previous
; __device__ __forceinline__ unsigned xb_ld(unsigned* p)              { return __hip_atomic_load(p, __ATOMIC_RELAXED, __HIP_MEMORY_SCOPE_AGENT); }
; __device__ __forceinline__ unsigned xb_add(unsigned* p, unsigned v) { return __hip_atomic_fetch_add(p, v, __ATOMIC_RELAXED, __HIP_MEMORY_SCOPE_AGENT); }
; #define XB_SPIN(cond, bar) do { unsigned _sp = 0; while (cond) { __builtin_amdgcn_s_sleep(1); \
;     if ((++_sp & 255u) == 0u) { if (xb_ld(&(bar)[XB_TMO])) break; if (_sp > XB_SPIN_CAP) { atomicAdd(&(bar)[XB_TMO], 1u); break; } } } } while (0)
; __device__ __forceinline__ void xcd_barrier(const XcdBarrier& b) {
;     ...
;             __builtin_amdgcn_fence(__ATOMIC_RELEASE, "agent");
;             asm volatile("s_waitcnt vmcnt(0)" ::: "memory");
;             const unsigned og = xb_add(&bar[XB_TOP], 1u);
;             const unsigned tg = og / nx;
;             if (og + 1u == (tg + 1u) * nx) xb_add(&bar[XB_TOPGEN], 1u);
;             else XB_SPIN(xb_ld(&bar[XB_TOPGEN]) == tg, bar);
;             __builtin_amdgcn_fence(__ATOMIC_ACQUIRE, "agent");
;             xb_add(&bar[XB_XGEN(b.x)], 1u);
;             asm volatile("s_waitcnt vmcnt(0)" ::: "memory");
.LBB0_118:
	s_or_b64 exec, exec, s[18:19]
	v_readlane_b32 s0, v252, 26
	v_readlane_b32 s1, v252, 27
	v_mov_b32_e32 v1, 1
	s_nop 3
	global_atomic_add v131, v1, s[0:1]
	buffer_inv sc1
	s_waitcnt vmcnt(0)

; #define PG8_STAGE(bufoff, gbase, voff) do { _Pragma("unroll") for (int _i = 0; _i < 2; ++_i) \
;         __builtin_amdgcn_global_load_lds((const unsigned*)((const char*)(gbase) + (voff)[_i]), (LAS unsigned*)(lds + (bufoff) + ldsw + _i * 8192), 16, 0, 0); } while (0)
; #define PG8_LDA(dst, b, h) do { _Pragma("unroll") for (int m = 0; m < 4; ++m) _Pragma("unroll") for (int k = 0; k < 2; ++k) dst[m][k] = *(const LAS bf16x8*)(lds + PG8_SA(b, h) + aoff + m * 2048 + k * 1024); } while (0)
; #define PG8_LDB(dst, b, h) do { _Pragma("unroll") for (int n = 0; n < 2; ++n) _Pragma("unroll") for (int k = 0; k < 2; ++k) dst[n][k] = *(const LAS bf16x8*)(lds + PG8_SB(b, h) + boff + n * 2048 + k * 1024); } while (0)
; #define PG8_MMA(ai, bj, At, Bt) do { __builtin_amdgcn_s_setprio(1); _Pragma("unroll") for (int m = 0; m < 4; ++m) _Pragma("unroll") for (int n = 0; n < 2; ++n) _Pragma("unroll") for (int k = 0; k < 2; ++k) \
;         acc[ai][bj][m][n] = __builtin_amdgcn_mfma_f32_16x16x32_bf16(Bt[n][k], At[m][k], acc[ai][bj][m][n], 0, 0, 0); __builtin_amdgcn_s_setprio(0); } while (0)
; #define PG8_WAIT_V(n) asm volatile("s_waitcnt vmcnt(" #n ")" ::: "memory")
; #define PG8_WAIT_L(n) asm volatile("s_waitcnt lgkmcnt(" #n ")" ::: "memory")
; #define PG8_BAR __builtin_amdgcn_s_barrier()
; #define PG8_SCHED __builtin_amdgcn_sched_barrier(0)
; template <class Epi, bool ALIGN_EPI = true, bool SP2 = true>
; __device__ __forceinline__ void gemm_phase(LAS unsigned char* lds, const Gemm g, const StaticOrder& S, const Epi& E, unsigned long long& tacc, const int tmode) {
;     ...
;             const bool last = (t == nt - 2);
;             const char* a1 = cA + (size_t)(t + 1) * kstepA;
;             const char* a2 = last ? nA : cA + (size_t)(t + 2) * kstepA; const char* b2 = last ? nB : cB + (size_t)(t + 2) * kstepB;
;             const char* a3 = a2 + kstepA; const char* b3 = b2 + kstepB;
;             if constexpr (SP2) {
;             PG8_LDB(B0, 0, 0); PG8_LDB(B1, 0, 1); PG8_SCHED; PG8_LDA(At, 0, 0); PG8_STAGE(PG8_SA(1, 1), a1 + hstepA, voffA);
;             PG8_WAIT_V(8); PG8_WAIT_L(0); PG8_BAR; PG8_MMA(0, 0, At, B0); PG8_MMA(0, 1, At, B1); PG8_BAR; PG8_SCHED;
;             PG8_LDA(At, 0, 1); PG8_STAGE(PG8_SB(0, 0), b2, voffB); PG8_STAGE(PG8_SB(0, 1), b2 + hstepB, voffB); PG8_STAGE(PG8_SA(0, 0), a2, voffA);
.LBB0_133:
	s_add_u32 s0, s22, 0xfff84000
	s_addc_u32 s1, s23, -1
	s_cmp_eq_u32 s56, 28
	s_cselect_b32 s34, s50, s0
	s_cselect_b32 s35, s25, s1
	s_cselect_b32 s38, s51, s54
	s_cselect_b32 s39, s21, s55
	s_add_u32 s30, s34, 0x4000
	s_addc_u32 s31, s35, 0
	s_add_i32 s0, 0, 0x10000
	v_add_u32_e32 v141, s0, v139
	s_add_i32 s33, 0, 0x14000
	ds_read_b128 v[134:137], v141
	ds_read_b128 v[142:145], v141 offset:1024
	ds_read_b128 v[146:149], v141 offset:2048
	ds_read_b128 v[150:153], v141 offset:3072
	v_add_u32_e32 v141, s33, v139
	ds_read_b128 v[154:157], v141
	ds_read_b128 v[158:161], v141 offset:1024
	ds_read_b128 v[162:165], v141 offset:2048
	ds_read_b128 v[166:169], v141 offset:3072
	v_lshl_add_u64 v[190:191], s[22:23], 0, v[130:131]
	s_add_i32 m0, s10, 0xc000
	ds_read_b128 v[170:173], v140
	ds_read_b128 v[174:177], v140 offset:1024
	ds_read_b128 v[178:181], v140 offset:2048
	ds_read_b128 v[182:185], v140 offset:3072
	ds_read_b128 v[186:189], v140 offset:4096
	ds_read_b128 v[194:197], v140 offset:5120
	ds_read_b128 v[206:209], v140 offset:6144
	ds_read_b128 v[210:213], v140 offset:7168
	global_load_lds_dwordx4 v[190:191], off
	v_lshl_add_u64 v[190:191], s[22:23], 0, v[132:133]
	s_add_i32 m0, s10, 0xe000
	s_nop 0
	global_load_lds_dwordx4 v[190:191], off
	s_waitcnt vmcnt(8)
	s_waitcnt lgkmcnt(0)
	s_barrier
	s_setprio 1
	s_waitcnt lgkmcnt(0)
	v_mfma_f32_16x16x32_bf16 v[126:129], v[134:137], v[170:173], v[126:129]
	v_mfma_f32_16x16x32_bf16 v[122:125], v[146:149], v[170:173], v[122:125]
	v_mfma_f32_16x16x32_bf16 v[110:113], v[134:137], v[178:181], v[110:113]
	v_mfma_f32_16x16x32_bf16 v[106:109], v[146:149], v[178:181], v[106:109]
	v_mfma_f32_16x16x32_bf16 v[94:97], v[134:137], v[186:189], v[94:97]
	v_mfma_f32_16x16x32_bf16 v[90:93], v[146:149], v[186:189], v[90:93]
	v_mfma_f32_16x16x32_bf16 v[78:81], v[134:137], v[206:209], v[78:81]
	v_mfma_f32_16x16x32_bf16 v[74:77], v[146:149], v[206:209], v[74:77]
	v_mfma_f32_16x16x32_bf16 v[126:129], v[142:145], v[174:177], v[126:129]
	v_mfma_f32_16x16x32_bf16 v[122:125], v[150:153], v[174:177], v[122:125]
	v_mfma_f32_16x16x32_bf16 v[110:113], v[142:145], v[182:185], v[110:113]
	v_mfma_f32_16x16x32_bf16 v[106:109], v[150:153], v[182:185], v[106:109]
	v_mfma_f32_16x16x32_bf16 v[94:97], v[142:145], v[194:197], v[94:97]
	v_mfma_f32_16x16x32_bf16 v[90:93], v[150:153], v[194:197], v[90:93]
	v_mfma_f32_16x16x32_bf16 v[78:81], v[142:145], v[210:213], v[78:81]
	v_mfma_f32_16x16x32_bf16 v[74:77], v[150:153], v[210:213], v[74:77]
	s_setprio 0
	s_setprio 1
	v_mfma_f32_16x16x32_bf16 v[118:121], v[154:157], v[170:173], v[118:121]
	v_mfma_f32_16x16x32_bf16 v[114:117], v[162:165], v[170:173], v[114:117]
	v_mfma_f32_16x16x32_bf16 v[102:105], v[154:157], v[178:181], v[102:105]
	v_mfma_f32_16x16x32_bf16 v[98:101], v[162:165], v[178:181], v[98:101]
	v_mfma_f32_16x16x32_bf16 v[86:89], v[154:157], v[186:189], v[86:89]
	v_mfma_f32_16x16x32_bf16 v[82:85], v[162:165], v[186:189], v[82:85]
	v_mfma_f32_16x16x32_bf16 v[70:73], v[154:157], v[206:209], v[70:73]
	v_mfma_f32_16x16x32_bf16 v[66:69], v[162:165], v[206:209], v[66:69]
	v_mfma_f32_16x16x32_bf16 v[118:121], v[158:161], v[174:177], v[118:121]
	v_mfma_f32_16x16x32_bf16 v[114:117], v[166:169], v[174:177], v[114:117]
	v_mfma_f32_16x16x32_bf16 v[102:105], v[158:161], v[182:185], v[102:105]
	v_mfma_f32_16x16x32_bf16 v[98:101], v[166:169], v[182:185], v[98:101]
	v_mfma_f32_16x16x32_bf16 v[86:89], v[158:161], v[194:197], v[86:89]
	v_mfma_f32_16x16x32_bf16 v[82:85], v[166:169], v[194:197], v[82:85]
	v_mfma_f32_16x16x32_bf16 v[70:73], v[158:161], v[210:213], v[70:73]
	s_barrier
	v_mfma_f32_16x16x32_bf16 v[66:69], v[166:169], v[210:213], v[66:69]
	s_setprio 0
	s_add_i32 s0, s0, s2
	v_lshl_add_u64 v[190:191], s[38:39], 0, v[130:131]
	s_mov_b32 m0, s0
	ds_read_b128 v[170:173], v140 offset:16384
	ds_read_b128 v[174:177], v140 offset:17408
	ds_read_b128 v[178:181], v140 offset:18432
	ds_read_b128 v[182:185], v140 offset:19456
	ds_read_b128 v[186:189], v140 offset:20480
	ds_read_b128 v[194:197], v140 offset:21504
	ds_read_b128 v[206:209], v140 offset:22528
	ds_read_b128 v[210:213], v140 offset:23552
	global_load_lds_dwordx4 v[190:191], off
	s_add_i32 m0, s0, 0x2000
	s_add_u32 s0, s38, 0x80000
	v_lshl_add_u64 v[190:191], s[38:39], 0, v[132:133]
	s_addc_u32 s1, s39, 0
	s_add_i32 s33, s33, s2
	global_load_lds_dwordx4 v[190:191], off
	v_lshl_add_u64 v[190:191], s[0:1], 0, v[130:131]
	s_mov_b32 m0, s33
	s_nop 0
	global_load_lds_dwordx4 v[190:191], off
	v_lshl_add_u64 v[190:191], s[0:1], 0, v[132:133]
	s_add_i32 m0, s33, 0x2000
	s_nop 0
	global_load_lds_dwordx4 v[190:191], off
	v_lshl_add_u64 v[190:191], s[34:35], 0, v[130:131]
	s_mov_b32 m0, s10
	s_nop 0
	global_load_lds_dwordx4 v[190:191], off
	v_lshl_add_u64 v[190:191], s[34:35], 0, v[132:133]
	s_mov_b32 m0, s40
	s_nop 0
	global_load_lds_dwordx4 v[190:191], off
	s_waitcnt vmcnt(8)
	s_waitcnt lgkmcnt(0)
	s_barrier
; #define PG8_STAGE(bufoff, gbase, voff) do { _Pragma("unroll") for (int _i = 0; _i < 2; ++_i) \
;         __builtin_amdgcn_global_load_lds((const unsigned*)((const char*)(gbase) + (voff)[_i]), (LAS unsigned*)(lds + (bufoff) + ldsw + _i * 8192), 16, 0, 0); } while (0)
; #define PG8_LDA(dst, b, h) do { _Pragma("unroll") for (int m = 0; m < 4; ++m) _Pragma("unroll") for (int k = 0; k < 2; ++k) dst[m][k] = *(const LAS bf16x8*)(lds + PG8_SA(b, h) + aoff + m * 2048 + k * 1024); } while (0)
; #define PG8_LDB(dst, b, h) do { _Pragma("unroll") for (int n = 0; n < 2; ++n) _Pragma("unroll") for (int k = 0; k < 2; ++k) dst[n][k] = *(const LAS bf16x8*)(lds + PG8_SB(b, h) + boff + n * 2048 + k * 1024); } while (0)
; #define PG8_MMA(ai, bj, At, Bt) do { __builtin_amdgcn_s_setprio(1); _Pragma("unroll") for (int m = 0; m < 4; ++m) _Pragma("unroll") for (int n = 0; n < 2; ++n) _Pragma("unroll") for (int k = 0; k < 2; ++k) \
;         acc[ai][bj][m][n] = __builtin_amdgcn_mfma_f32_16x16x32_bf16(Bt[n][k], At[m][k], acc[ai][bj][m][n], 0, 0, 0); __builtin_amdgcn_s_setprio(0); } while (0)
; #define PG8_WAIT_V(n) asm volatile("s_waitcnt vmcnt(" #n ")" ::: "memory")
; #define PG8_WAIT_L(n) asm volatile("s_waitcnt lgkmcnt(" #n ")" ::: "memory")
; #define PG8_BAR __builtin_amdgcn_s_barrier()
; #define PG8_SCHED __builtin_amdgcn_sched_barrier(0)
; template <class Epi, bool ALIGN_EPI = true, bool SP2 = true>
; __device__ __forceinline__ void gemm_phase(LAS unsigned char* lds, const Gemm g, const StaticOrder& S, const Epi& E, unsigned long long& tacc, const int tmode) {
;     ...
;             PG8_WAIT_V(8); PG8_WAIT_L(0); PG8_BAR; PG8_MMA(1, 0, At, B0); PG8_MMA(1, 1, At, B1); PG8_BAR; PG8_SCHED;
;             PG8_LDB(B0, 1, 0); PG8_LDB(B1, 1, 1); PG8_SCHED; PG8_LDA(At, 1, 0); PG8_STAGE(PG8_SA(0, 1), a2 + hstepA, voffA);
;             PG8_WAIT_V(8); PG8_WAIT_L(0); PG8_BAR; PG8_MMA(0, 0, At, B0); PG8_MMA(0, 1, At, B1); PG8_BAR; PG8_SCHED;
	s_setprio 1
	s_waitcnt lgkmcnt(0)
	v_mfma_f32_16x16x32_bf16 v[62:65], v[134:137], v[170:173], v[62:65]
	v_mfma_f32_16x16x32_bf16 v[58:61], v[146:149], v[170:173], v[58:61]
	v_mfma_f32_16x16x32_bf16 v[46:49], v[134:137], v[178:181], v[46:49]
	v_mfma_f32_16x16x32_bf16 v[42:45], v[146:149], v[178:181], v[42:45]
	v_mfma_f32_16x16x32_bf16 v[30:33], v[134:137], v[186:189], v[30:33]
	v_mfma_f32_16x16x32_bf16 v[26:29], v[146:149], v[186:189], v[26:29]
	v_mfma_f32_16x16x32_bf16 v[14:17], v[134:137], v[206:209], v[14:17]
	v_mfma_f32_16x16x32_bf16 v[10:13], v[146:149], v[206:209], v[10:13]
	v_mfma_f32_16x16x32_bf16 v[62:65], v[142:145], v[174:177], v[62:65]
	v_mfma_f32_16x16x32_bf16 v[58:61], v[150:153], v[174:177], v[58:61]
	v_mfma_f32_16x16x32_bf16 v[46:49], v[142:145], v[182:185], v[46:49]
	v_mfma_f32_16x16x32_bf16 v[42:45], v[150:153], v[182:185], v[42:45]
	v_mfma_f32_16x16x32_bf16 v[30:33], v[142:145], v[194:197], v[30:33]
	v_mfma_f32_16x16x32_bf16 v[26:29], v[150:153], v[194:197], v[26:29]
	v_mfma_f32_16x16x32_bf16 v[14:17], v[142:145], v[210:213], v[14:17]
	v_mfma_f32_16x16x32_bf16 v[10:13], v[150:153], v[210:213], v[10:13]
	s_setprio 0
	s_setprio 1
	v_mfma_f32_16x16x32_bf16 v[54:57], v[154:157], v[170:173], v[54:57]
	v_mfma_f32_16x16x32_bf16 v[50:53], v[162:165], v[170:173], v[50:53]
	v_mfma_f32_16x16x32_bf16 v[38:41], v[154:157], v[178:181], v[38:41]
	v_mfma_f32_16x16x32_bf16 v[34:37], v[162:165], v[178:181], v[34:37]
	v_mfma_f32_16x16x32_bf16 v[22:25], v[154:157], v[186:189], v[22:25]
	v_mfma_f32_16x16x32_bf16 v[18:21], v[162:165], v[186:189], v[18:21]
	v_mfma_f32_16x16x32_bf16 v[6:9], v[154:157], v[206:209], v[6:9]
	v_mfma_f32_16x16x32_bf16 v[2:5], v[162:165], v[206:209], v[2:5]
	v_mfma_f32_16x16x32_bf16 v[54:57], v[158:161], v[174:177], v[54:57]
	v_mfma_f32_16x16x32_bf16 v[50:53], v[166:169], v[174:177], v[50:53]
	v_mfma_f32_16x16x32_bf16 v[38:41], v[158:161], v[182:185], v[38:41]
	v_mfma_f32_16x16x32_bf16 v[34:37], v[166:169], v[182:185], v[34:37]
	v_mfma_f32_16x16x32_bf16 v[22:25], v[158:161], v[194:197], v[22:25]
	v_mfma_f32_16x16x32_bf16 v[18:21], v[166:169], v[194:197], v[18:21]
	v_mfma_f32_16x16x32_bf16 v[6:9], v[158:161], v[210:213], v[6:9]
	s_barrier
	v_mfma_f32_16x16x32_bf16 v[2:5], v[166:169], v[210:213], v[2:5]
	s_setprio 0
	s_add_i32 s33, 0, 0x18000
	v_add_u32_e32 v141, s33, v139
	s_add_i32 s57, 0, 0x1c000
	ds_read_b128 v[134:137], v141
	ds_read_b128 v[142:145], v141 offset:1024
	ds_read_b128 v[146:149], v141 offset:2048
	ds_read_b128 v[150:153], v141 offset:3072
	v_add_u32_e32 v141, s57, v139
	ds_read_b128 v[154:157], v141
	ds_read_b128 v[158:161], v141 offset:1024
	ds_read_b128 v[162:165], v141 offset:2048
	ds_read_b128 v[166:169], v141 offset:3072
	s_add_u32 s0, s34, 0x80000
	s_addc_u32 s1, s35, 0
	s_mov_b32 m0, s41
	v_lshl_add_u64 v[190:191], s[0:1], 0, v[130:131]
	ds_read_b128 v[170:173], v140 offset:32768
	ds_read_b128 v[174:177], v140 offset:33792
	ds_read_b128 v[178:181], v140 offset:34816
	ds_read_b128 v[182:185], v140 offset:35840
	ds_read_b128 v[186:189], v140 offset:36864
	ds_read_b128 v[194:197], v140 offset:37888
	ds_read_b128 v[206:209], v140 offset:38912
	ds_read_b128 v[210:213], v140 offset:39936
	global_load_lds_dwordx4 v[190:191], off
	v_lshl_add_u64 v[190:191], s[0:1], 0, v[132:133]
	s_mov_b32 m0, s42
	s_nop 0
	global_load_lds_dwordx4 v[190:191], off
	s_waitcnt vmcnt(8)
	s_waitcnt lgkmcnt(0)
	s_barrier
	s_setprio 1
	s_waitcnt lgkmcnt(0)
	v_mfma_f32_16x16x32_bf16 v[126:129], v[134:137], v[170:173], v[126:129]
	v_mfma_f32_16x16x32_bf16 v[122:125], v[146:149], v[170:173], v[122:125]
	v_mfma_f32_16x16x32_bf16 v[110:113], v[134:137], v[178:181], v[110:113]
	v_mfma_f32_16x16x32_bf16 v[106:109], v[146:149], v[178:181], v[106:109]
	v_mfma_f32_16x16x32_bf16 v[94:97], v[134:137], v[186:189], v[94:97]
	v_mfma_f32_16x16x32_bf16 v[90:93], v[146:149], v[186:189], v[90:93]
	v_mfma_f32_16x16x32_bf16 v[78:81], v[134:137], v[206:209], v[78:81]
	v_mfma_f32_16x16x32_bf16 v[74:77], v[146:149], v[206:209], v[74:77]
	v_mfma_f32_16x16x32_bf16 v[126:129], v[142:145], v[174:177], v[126:129]
	v_mfma_f32_16x16x32_bf16 v[122:125], v[150:153], v[174:177], v[122:125]
	v_mfma_f32_16x16x32_bf16 v[110:113], v[142:145], v[182:185], v[110:113]
	v_mfma_f32_16x16x32_bf16 v[106:109], v[150:153], v[182:185], v[106:109]
	v_mfma_f32_16x16x32_bf16 v[94:97], v[142:145], v[194:197], v[94:97]
	v_mfma_f32_16x16x32_bf16 v[90:93], v[150:153], v[194:197], v[90:93]
	v_mfma_f32_16x16x32_bf16 v[78:81], v[142:145], v[210:213], v[78:81]
	v_mfma_f32_16x16x32_bf16 v[74:77], v[150:153], v[210:213], v[74:77]
	s_setprio 0
	s_setprio 1
	v_mfma_f32_16x16x32_bf16 v[118:121], v[154:157], v[170:173], v[118:121]
	v_mfma_f32_16x16x32_bf16 v[114:117], v[162:165], v[170:173], v[114:117]
	v_mfma_f32_16x16x32_bf16 v[102:105], v[154:157], v[178:181], v[102:105]
	v_mfma_f32_16x16x32_bf16 v[98:101], v[162:165], v[178:181], v[98:101]
	v_mfma_f32_16x16x32_bf16 v[86:89], v[154:157], v[186:189], v[86:89]
	v_mfma_f32_16x16x32_bf16 v[82:85], v[162:165], v[186:189], v[82:85]
	v_mfma_f32_16x16x32_bf16 v[70:73], v[154:157], v[206:209], v[70:73]
	v_mfma_f32_16x16x32_bf16 v[66:69], v[162:165], v[206:209], v[66:69]
	v_mfma_f32_16x16x32_bf16 v[118:121], v[158:161], v[174:177], v[118:121]
	v_mfma_f32_16x16x32_bf16 v[114:117], v[166:169], v[174:177], v[114:117]
	v_mfma_f32_16x16x32_bf16 v[102:105], v[158:161], v[182:185], v[102:105]
	v_mfma_f32_16x16x32_bf16 v[98:101], v[166:169], v[182:185], v[98:101]
	v_mfma_f32_16x16x32_bf16 v[86:89], v[158:161], v[194:197], v[86:89]
	v_mfma_f32_16x16x32_bf16 v[82:85], v[166:169], v[194:197], v[82:85]
	v_mfma_f32_16x16x32_bf16 v[70:73], v[158:161], v[210:213], v[70:73]
	s_barrier
; #define PG8_STAGE(bufoff, gbase, voff) do { _Pragma("unroll") for (int _i = 0; _i < 2; ++_i) \
;         __builtin_amdgcn_global_load_lds((const unsigned*)((const char*)(gbase) + (voff)[_i]), (LAS unsigned*)(lds + (bufoff) + ldsw + _i * 8192), 16, 0, 0); } while (0)
; #define PG8_LDA(dst, b, h) do { _Pragma("unroll") for (int m = 0; m < 4; ++m) _Pragma("unroll") for (int k = 0; k < 2; ++k) dst[m][k] = *(const LAS bf16x8*)(lds + PG8_SA(b, h) + aoff + m * 2048 + k * 1024); } while (0)
; #define PG8_MMA(ai, bj, At, Bt) do { __builtin_amdgcn_s_setprio(1); _Pragma("unroll") for (int m = 0; m < 4; ++m) _Pragma("unroll") for (int n = 0; n < 2; ++n) _Pragma("unroll") for (int k = 0; k < 2; ++k) \
;         acc[ai][bj][m][n] = __builtin_amdgcn_mfma_f32_16x16x32_bf16(Bt[n][k], At[m][k], acc[ai][bj][m][n], 0, 0, 0); __builtin_amdgcn_s_setprio(0); } while (0)
; #define PG8_WAIT_V(n) asm volatile("s_waitcnt vmcnt(" #n ")" ::: "memory")
; #define PG8_WAIT_L(n) asm volatile("s_waitcnt lgkmcnt(" #n ")" ::: "memory")
; #define PG8_BAR __builtin_amdgcn_s_barrier()
; #define PG8_SCHED __builtin_amdgcn_sched_barrier(0)
; template <class Epi, bool ALIGN_EPI = true, bool SP2 = true>
; __device__ __forceinline__ void gemm_phase(LAS unsigned char* lds, const Gemm g, const StaticOrder& S, const Epi& E, unsigned long long& tacc, const int tmode) {
;     ...
;             PG8_WAIT_V(8); PG8_WAIT_L(0); PG8_BAR; PG8_MMA(0, 0, At, B0); PG8_MMA(0, 1, At, B1); PG8_BAR; PG8_SCHED;
;             PG8_LDA(At, 1, 1); PG8_STAGE(PG8_SB(1, 0), b3, voffB); PG8_STAGE(PG8_SB(1, 1), b3 + hstepB, voffB); PG8_STAGE(PG8_SA(1, 0), a3, voffA);
;             PG8_WAIT_V(8); PG8_WAIT_L(0); PG8_BAR; PG8_MMA(1, 0, At, B0); PG8_MMA(1, 1, At, B1); PG8_BAR; PG8_SCHED;
	v_mfma_f32_16x16x32_bf16 v[66:69], v[166:169], v[210:213], v[66:69]
	s_setprio 0
	s_add_u32 s0, s38, 0x4000
	s_addc_u32 s1, s39, 0
	s_add_i32 s33, s33, s2
	v_lshl_add_u64 v[190:191], s[0:1], 0, v[130:131]
	s_mov_b32 m0, s33
	ds_read_b128 v[170:173], v140 offset:49152
	ds_read_b128 v[174:177], v140 offset:50176
	ds_read_b128 v[178:181], v140 offset:51200
	ds_read_b128 v[182:185], v140 offset:52224
	ds_read_b128 v[186:189], v140 offset:53248
	ds_read_b128 v[194:197], v140 offset:54272
	ds_read_b128 v[206:209], v140 offset:55296
	ds_read_b128 v[210:213], v140 offset:56320
	global_load_lds_dwordx4 v[190:191], off
	s_add_i32 m0, s33, 0x2000
	v_lshl_add_u64 v[190:191], s[0:1], 0, v[132:133]
	s_add_u32 s0, s38, 0x84000
	s_addc_u32 s1, s39, 0
	s_add_i32 s33, s57, s2
	global_load_lds_dwordx4 v[190:191], off
	v_lshl_add_u64 v[190:191], s[0:1], 0, v[130:131]
	s_mov_b32 m0, s33
	s_nop 0
	global_load_lds_dwordx4 v[190:191], off
	v_lshl_add_u64 v[190:191], s[0:1], 0, v[132:133]
	s_add_i32 m0, s33, 0x2000
	s_nop 0
	global_load_lds_dwordx4 v[190:191], off
	v_lshl_add_u64 v[190:191], s[30:31], 0, v[130:131]
	s_mov_b32 m0, s45
	s_nop 0
	global_load_lds_dwordx4 v[190:191], off
	v_lshl_add_u64 v[190:191], s[30:31], 0, v[132:133]
	s_mov_b32 m0, s46
	s_nop 0
	global_load_lds_dwordx4 v[190:191], off
	s_waitcnt vmcnt(8)
	s_waitcnt lgkmcnt(0)
	s_barrier
	s_setprio 1
	s_waitcnt lgkmcnt(0)
	v_mfma_f32_16x16x32_bf16 v[62:65], v[134:137], v[170:173], v[62:65]
	v_mfma_f32_16x16x32_bf16 v[58:61], v[146:149], v[170:173], v[58:61]
	v_mfma_f32_16x16x32_bf16 v[46:49], v[134:137], v[178:181], v[46:49]
	v_mfma_f32_16x16x32_bf16 v[42:45], v[146:149], v[178:181], v[42:45]
	v_mfma_f32_16x16x32_bf16 v[30:33], v[134:137], v[186:189], v[30:33]
	v_mfma_f32_16x16x32_bf16 v[26:29], v[146:149], v[186:189], v[26:29]
	v_mfma_f32_16x16x32_bf16 v[14:17], v[134:137], v[206:209], v[14:17]
	v_mfma_f32_16x16x32_bf16 v[10:13], v[146:149], v[206:209], v[10:13]
	v_mfma_f32_16x16x32_bf16 v[62:65], v[142:145], v[174:177], v[62:65]
	v_mfma_f32_16x16x32_bf16 v[58:61], v[150:153], v[174:177], v[58:61]
	v_mfma_f32_16x16x32_bf16 v[46:49], v[142:145], v[182:185], v[46:49]
	v_mfma_f32_16x16x32_bf16 v[42:45], v[150:153], v[182:185], v[42:45]
	v_mfma_f32_16x16x32_bf16 v[30:33], v[142:145], v[194:197], v[30:33]
	v_mfma_f32_16x16x32_bf16 v[26:29], v[150:153], v[194:197], v[26:29]
	v_mfma_f32_16x16x32_bf16 v[14:17], v[142:145], v[210:213], v[14:17]
	v_mfma_f32_16x16x32_bf16 v[10:13], v[150:153], v[210:213], v[10:13]
	s_setprio 0
	s_setprio 1
	v_mfma_f32_16x16x32_bf16 v[54:57], v[154:157], v[170:173], v[54:57]
	v_mfma_f32_16x16x32_bf16 v[50:53], v[162:165], v[170:173], v[50:53]
	v_mfma_f32_16x16x32_bf16 v[38:41], v[154:157], v[178:181], v[38:41]
	v_mfma_f32_16x16x32_bf16 v[34:37], v[162:165], v[178:181], v[34:37]
	v_mfma_f32_16x16x32_bf16 v[22:25], v[154:157], v[186:189], v[22:25]
	v_mfma_f32_16x16x32_bf16 v[18:21], v[162:165], v[186:189], v[18:21]
	v_mfma_f32_16x16x32_bf16 v[6:9], v[154:157], v[206:209], v[6:9]
	v_mfma_f32_16x16x32_bf16 v[2:5], v[162:165], v[206:209], v[2:5]
	v_mfma_f32_16x16x32_bf16 v[54:57], v[158:161], v[174:177], v[54:57]
	v_mfma_f32_16x16x32_bf16 v[50:53], v[166:169], v[174:177], v[50:53]
	v_mfma_f32_16x16x32_bf16 v[38:41], v[158:161], v[182:185], v[38:41]
	v_mfma_f32_16x16x32_bf16 v[34:37], v[166:169], v[182:185], v[34:37]
	v_mfma_f32_16x16x32_bf16 v[22:25], v[158:161], v[194:197], v[22:25]
	v_mfma_f32_16x16x32_bf16 v[18:21], v[166:169], v[194:197], v[18:21]
	v_mfma_f32_16x16x32_bf16 v[6:9], v[158:161], v[210:213], v[6:9]
	s_barrier
	v_mfma_f32_16x16x32_bf16 v[2:5], v[166:169], v[210:213], v[2:5]
	s_setprio 0
	s_add_i32 s56, s56, 2
	s_add_u32 s22, s22, 0x8000
	s_addc_u32 s23, s23, 0
	s_add_u32 s54, s54, 0x8000
	s_addc_u32 s55, s55, 0
	s_cmp_lt_u32 s56, 30
	s_cbranch_scc1 .LBB0_133
	s_andn2_b64 vcc, exec, s[18:19]
	s_cbranch_vccnz .LBB0_136
	s_barrier

; #define PG8_STAGE(bufoff, gbase, voff) do { _Pragma("unroll") for (int _i = 0; _i < 2; ++_i) \
;         __builtin_amdgcn_global_load_lds((const unsigned*)((const char*)(gbase) + (voff)[_i]), (LAS unsigned*)(lds + (bufoff) + ldsw + _i * 8192), 16, 0, 0); } while (0)
; #define PG8_LDA(dst, b, h) do { _Pragma("unroll") for (int m = 0; m < 4; ++m) _Pragma("unroll") for (int k = 0; k < 2; ++k) dst[m][k] = *(const LAS bf16x8*)(lds + PG8_SA(b, h) + aoff + m * 2048 + k * 1024); } while (0)
; #define PG8_LDB(dst, b, h) do { _Pragma("unroll") for (int n = 0; n < 2; ++n) _Pragma("unroll") for (int k = 0; k < 2; ++k) dst[n][k] = *(const LAS bf16x8*)(lds + PG8_SB(b, h) + boff + n * 2048 + k * 1024); } while (0)
; #define PG8_MMA(ai, bj, At, Bt) do { __builtin_amdgcn_s_setprio(1); _Pragma("unroll") for (int m = 0; m < 4; ++m) _Pragma("unroll") for (int n = 0; n < 2; ++n) _Pragma("unroll") for (int k = 0; k < 2; ++k) \
;         acc[ai][bj][m][n] = __builtin_amdgcn_mfma_f32_16x16x32_bf16(Bt[n][k], At[m][k], acc[ai][bj][m][n], 0, 0, 0); __builtin_amdgcn_s_setprio(0); } while (0)
; #define PG8_WAIT_V(n) asm volatile("s_waitcnt vmcnt(" #n ")" ::: "memory")
; #define PG8_WAIT_L(n) asm volatile("s_waitcnt lgkmcnt(" #n ")" ::: "memory")
; #define PG8_BAR __builtin_amdgcn_s_barrier()
; #define PG8_SCHED __builtin_amdgcn_sched_barrier(0)
; template <class Epi, bool ALIGN_EPI = true, bool SP2 = true>
; __device__ __forceinline__ void gemm_phase(LAS unsigned char* lds, const Gemm g, const StaticOrder& S, const Epi& E, unsigned long long& tacc, const int tmode) {
;     ...
;             const bool last = (t == nt - 2);
;             const char* a1 = cA + (size_t)(t + 1) * kstepA;
;             const char* a2 = last ? nA : cA + (size_t)(t + 2) * kstepA; const char* b2 = last ? nB : cB + (size_t)(t + 2) * kstepB;
;             const char* a3 = a2 + kstepA; const char* b3 = b2 + kstepB;
;             if constexpr (SP2) {
;             PG8_LDB(B0, 0, 0); PG8_LDB(B1, 0, 1); PG8_SCHED; PG8_LDA(At, 0, 0); PG8_STAGE(PG8_SA(1, 1), a1 + hstepA, voffA);
;             PG8_WAIT_V(8); PG8_WAIT_L(0); PG8_BAR; PG8_MMA(0, 0, At, B0); PG8_MMA(0, 1, At, B1); PG8_BAR; PG8_SCHED;
;             PG8_LDA(At, 0, 1); PG8_STAGE(PG8_SB(0, 0), b2, voffB); PG8_STAGE(PG8_SB(0, 1), b2 + hstepB, voffB); PG8_STAGE(PG8_SA(0, 0), a2, voffA);
.LBB0_581:
	s_add_u32 s0, s22, 0xfff84000
	s_addc_u32 s1, s23, -1
	s_cmp_eq_u32 s56, 28
	s_cselect_b32 s34, s50, s0
	s_cselect_b32 s35, s25, s1
	s_cselect_b32 s38, s51, s54
	s_cselect_b32 s39, s21, s55
	s_add_u32 s30, s34, 0x4000
	s_addc_u32 s31, s35, 0
	s_add_i32 s0, 0, 0x10000
	v_add_u32_e32 v142, s0, v146
	s_add_i32 s33, 0, 0x14000
	ds_read_b128 v[132:135], v142
	ds_read_b128 v[136:139], v142 offset:1024
	ds_read_b128 v[148:151], v142 offset:2048
	ds_read_b128 v[152:155], v142 offset:3072
	v_add_u32_e32 v142, s33, v146
	ds_read_b128 v[156:159], v142
	ds_read_b128 v[160:163], v142 offset:1024
	ds_read_b128 v[164:167], v142 offset:2048
	ds_read_b128 v[168:171], v142 offset:3072
	v_lshl_add_u64 v[144:145], s[22:23], 0, v[130:131]
	s_add_i32 m0, s10, 0xc000
	ds_read_b128 v[172:175], v147
	ds_read_b128 v[176:179], v147 offset:1024
	ds_read_b128 v[180:183], v147 offset:2048
	ds_read_b128 v[184:187], v147 offset:3072
	ds_read_b128 v[188:191], v147 offset:4096
	ds_read_b128 v[194:197], v147 offset:5120
	ds_read_b128 v[206:209], v147 offset:6144
	ds_read_b128 v[210:213], v147 offset:7168
	global_load_lds_dwordx4 v[144:145], off
	v_lshl_add_u64 v[144:145], s[22:23], 0, v[140:141]
	s_add_i32 m0, s10, 0xe000
	s_nop 0
	global_load_lds_dwordx4 v[144:145], off
	s_waitcnt vmcnt(8)
	s_waitcnt lgkmcnt(0)
	s_barrier
	s_setprio 1
	s_waitcnt lgkmcnt(0)
	v_mfma_f32_16x16x32_bf16 v[126:129], v[132:135], v[172:175], v[126:129]
	v_mfma_f32_16x16x32_bf16 v[122:125], v[148:151], v[172:175], v[122:125]
	v_mfma_f32_16x16x32_bf16 v[118:121], v[132:135], v[180:183], v[118:121]
	v_mfma_f32_16x16x32_bf16 v[114:117], v[148:151], v[180:183], v[114:117]
	v_mfma_f32_16x16x32_bf16 v[110:113], v[132:135], v[188:191], v[110:113]
	v_mfma_f32_16x16x32_bf16 v[106:109], v[148:151], v[188:191], v[106:109]
	v_mfma_f32_16x16x32_bf16 v[102:105], v[132:135], v[206:209], v[102:105]
	v_mfma_f32_16x16x32_bf16 v[98:101], v[148:151], v[206:209], v[98:101]
	v_mfma_f32_16x16x32_bf16 v[126:129], v[136:139], v[176:179], v[126:129]
	v_mfma_f32_16x16x32_bf16 v[122:125], v[152:155], v[176:179], v[122:125]
	v_mfma_f32_16x16x32_bf16 v[118:121], v[136:139], v[184:187], v[118:121]
	v_mfma_f32_16x16x32_bf16 v[114:117], v[152:155], v[184:187], v[114:117]
	v_mfma_f32_16x16x32_bf16 v[110:113], v[136:139], v[194:197], v[110:113]
	v_mfma_f32_16x16x32_bf16 v[106:109], v[152:155], v[194:197], v[106:109]
	v_mfma_f32_16x16x32_bf16 v[102:105], v[136:139], v[210:213], v[102:105]
	v_mfma_f32_16x16x32_bf16 v[98:101], v[152:155], v[210:213], v[98:101]
	s_setprio 0
	s_setprio 1
	v_mfma_f32_16x16x32_bf16 v[62:65], v[156:159], v[172:175], v[62:65]
	v_mfma_f32_16x16x32_bf16 v[58:61], v[164:167], v[172:175], v[58:61]
	v_mfma_f32_16x16x32_bf16 v[54:57], v[156:159], v[180:183], v[54:57]
	v_mfma_f32_16x16x32_bf16 v[50:53], v[164:167], v[180:183], v[50:53]
	v_mfma_f32_16x16x32_bf16 v[46:49], v[156:159], v[188:191], v[46:49]
	v_mfma_f32_16x16x32_bf16 v[42:45], v[164:167], v[188:191], v[42:45]
	v_mfma_f32_16x16x32_bf16 v[38:41], v[156:159], v[206:209], v[38:41]
	v_mfma_f32_16x16x32_bf16 v[34:37], v[164:167], v[206:209], v[34:37]
	v_mfma_f32_16x16x32_bf16 v[62:65], v[160:163], v[176:179], v[62:65]
	v_mfma_f32_16x16x32_bf16 v[58:61], v[168:171], v[176:179], v[58:61]
	v_mfma_f32_16x16x32_bf16 v[54:57], v[160:163], v[184:187], v[54:57]
	v_mfma_f32_16x16x32_bf16 v[50:53], v[168:171], v[184:187], v[50:53]
	v_mfma_f32_16x16x32_bf16 v[46:49], v[160:163], v[194:197], v[46:49]
	v_mfma_f32_16x16x32_bf16 v[42:45], v[168:171], v[194:197], v[42:45]
	v_mfma_f32_16x16x32_bf16 v[38:41], v[160:163], v[210:213], v[38:41]
	s_barrier
	v_mfma_f32_16x16x32_bf16 v[34:37], v[168:171], v[210:213], v[34:37]
	s_setprio 0
	s_add_i32 s0, s0, s2
	v_lshl_add_u64 v[144:145], s[38:39], 0, v[130:131]
	s_mov_b32 m0, s0
	ds_read_b128 v[172:175], v147 offset:16384
	ds_read_b128 v[176:179], v147 offset:17408
	ds_read_b128 v[180:183], v147 offset:18432
	ds_read_b128 v[184:187], v147 offset:19456
	ds_read_b128 v[188:191], v147 offset:20480
	ds_read_b128 v[194:197], v147 offset:21504
	ds_read_b128 v[206:209], v147 offset:22528
	ds_read_b128 v[210:213], v147 offset:23552
	global_load_lds_dwordx4 v[144:145], off
	s_add_i32 m0, s0, 0x2000
	s_add_u32 s0, s38, 0x80000
	v_lshl_add_u64 v[144:145], s[38:39], 0, v[140:141]
	s_addc_u32 s1, s39, 0
	s_add_i32 s33, s33, s2
	global_load_lds_dwordx4 v[144:145], off
	v_lshl_add_u64 v[144:145], s[0:1], 0, v[130:131]
	s_mov_b32 m0, s33
	s_nop 0
	global_load_lds_dwordx4 v[144:145], off
	v_lshl_add_u64 v[144:145], s[0:1], 0, v[140:141]
	s_add_i32 m0, s33, 0x2000
	s_nop 0
	global_load_lds_dwordx4 v[144:145], off
	v_lshl_add_u64 v[144:145], s[34:35], 0, v[130:131]
	s_mov_b32 m0, s10
	s_nop 0
	global_load_lds_dwordx4 v[144:145], off
	v_lshl_add_u64 v[144:145], s[34:35], 0, v[140:141]
	s_mov_b32 m0, s40
	s_nop 0
	global_load_lds_dwordx4 v[144:145], off
	s_waitcnt vmcnt(8)
	s_waitcnt lgkmcnt(0)
	s_barrier
; #define PG8_STAGE(bufoff, gbase, voff) do { _Pragma("unroll") for (int _i = 0; _i < 2; ++_i) \
;         __builtin_amdgcn_global_load_lds((const unsigned*)((const char*)(gbase) + (voff)[_i]), (LAS unsigned*)(lds + (bufoff) + ldsw + _i * 8192), 16, 0, 0); } while (0)
; #define PG8_LDA(dst, b, h) do { _Pragma("unroll") for (int m = 0; m < 4; ++m) _Pragma("unroll") for (int k = 0; k < 2; ++k) dst[m][k] = *(const LAS bf16x8*)(lds + PG8_SA(b, h) + aoff + m * 2048 + k * 1024); } while (0)
; #define PG8_LDB(dst, b, h) do { _Pragma("unroll") for (int n = 0; n < 2; ++n) _Pragma("unroll") for (int k = 0; k < 2; ++k) dst[n][k] = *(const LAS bf16x8*)(lds + PG8_SB(b, h) + boff + n * 2048 + k * 1024); } while (0)
; #define PG8_MMA(ai, bj, At, Bt) do { __builtin_amdgcn_s_setprio(1); _Pragma("unroll") for (int m = 0; m < 4; ++m) _Pragma("unroll") for (int n = 0; n < 2; ++n) _Pragma("unroll") for (int k = 0; k < 2; ++k) \
;         acc[ai][bj][m][n] = __builtin_amdgcn_mfma_f32_16x16x32_bf16(Bt[n][k], At[m][k], acc[ai][bj][m][n], 0, 0, 0); __builtin_amdgcn_s_setprio(0); } while (0)
; #define PG8_WAIT_V(n) asm volatile("s_waitcnt vmcnt(" #n ")" ::: "memory")
; #define PG8_WAIT_L(n) asm volatile("s_waitcnt lgkmcnt(" #n ")" ::: "memory")
; #define PG8_BAR __builtin_amdgcn_s_barrier()
; #define PG8_SCHED __builtin_amdgcn_sched_barrier(0)
; template <class Epi, bool ALIGN_EPI = true, bool SP2 = true>
; __device__ __forceinline__ void gemm_phase(LAS unsigned char* lds, const Gemm g, const StaticOrder& S, const Epi& E, unsigned long long& tacc, const int tmode) {
;     ...
;             PG8_WAIT_V(8); PG8_WAIT_L(0); PG8_BAR; PG8_MMA(1, 0, At, B0); PG8_MMA(1, 1, At, B1); PG8_BAR; PG8_SCHED;
;             PG8_LDB(B0, 1, 0); PG8_LDB(B1, 1, 1); PG8_SCHED; PG8_LDA(At, 1, 0); PG8_STAGE(PG8_SA(0, 1), a2 + hstepA, voffA);
;             PG8_WAIT_V(8); PG8_WAIT_L(0); PG8_BAR; PG8_MMA(0, 0, At, B0); PG8_MMA(0, 1, At, B1); PG8_BAR; PG8_SCHED;
	s_setprio 1
	s_waitcnt lgkmcnt(0)
	v_mfma_f32_16x16x32_bf16 v[94:97], v[132:135], v[172:175], v[94:97]
	v_mfma_f32_16x16x32_bf16 v[90:93], v[148:151], v[172:175], v[90:93]
	v_mfma_f32_16x16x32_bf16 v[86:89], v[132:135], v[180:183], v[86:89]
	v_mfma_f32_16x16x32_bf16 v[82:85], v[148:151], v[180:183], v[82:85]
	v_mfma_f32_16x16x32_bf16 v[78:81], v[132:135], v[188:191], v[78:81]
	v_mfma_f32_16x16x32_bf16 v[74:77], v[148:151], v[188:191], v[74:77]
	v_mfma_f32_16x16x32_bf16 v[70:73], v[132:135], v[206:209], v[70:73]
	v_mfma_f32_16x16x32_bf16 v[66:69], v[148:151], v[206:209], v[66:69]
	v_mfma_f32_16x16x32_bf16 v[94:97], v[136:139], v[176:179], v[94:97]
	v_mfma_f32_16x16x32_bf16 v[90:93], v[152:155], v[176:179], v[90:93]
	v_mfma_f32_16x16x32_bf16 v[86:89], v[136:139], v[184:187], v[86:89]
	v_mfma_f32_16x16x32_bf16 v[82:85], v[152:155], v[184:187], v[82:85]
	v_mfma_f32_16x16x32_bf16 v[78:81], v[136:139], v[194:197], v[78:81]
	v_mfma_f32_16x16x32_bf16 v[74:77], v[152:155], v[194:197], v[74:77]
	v_mfma_f32_16x16x32_bf16 v[70:73], v[136:139], v[210:213], v[70:73]
	v_mfma_f32_16x16x32_bf16 v[66:69], v[152:155], v[210:213], v[66:69]
	s_setprio 0
	s_setprio 1
	v_mfma_f32_16x16x32_bf16 v[30:33], v[156:159], v[172:175], v[30:33]
	v_mfma_f32_16x16x32_bf16 v[26:29], v[164:167], v[172:175], v[26:29]
	v_mfma_f32_16x16x32_bf16 v[22:25], v[156:159], v[180:183], v[22:25]
	v_mfma_f32_16x16x32_bf16 v[18:21], v[164:167], v[180:183], v[18:21]
	v_mfma_f32_16x16x32_bf16 v[14:17], v[156:159], v[188:191], v[14:17]
	v_mfma_f32_16x16x32_bf16 v[10:13], v[164:167], v[188:191], v[10:13]
	v_mfma_f32_16x16x32_bf16 v[6:9], v[156:159], v[206:209], v[6:9]
	v_mfma_f32_16x16x32_bf16 v[2:5], v[164:167], v[206:209], v[2:5]
	v_mfma_f32_16x16x32_bf16 v[30:33], v[160:163], v[176:179], v[30:33]
	v_mfma_f32_16x16x32_bf16 v[26:29], v[168:171], v[176:179], v[26:29]
	v_mfma_f32_16x16x32_bf16 v[22:25], v[160:163], v[184:187], v[22:25]
	v_mfma_f32_16x16x32_bf16 v[18:21], v[168:171], v[184:187], v[18:21]
	v_mfma_f32_16x16x32_bf16 v[14:17], v[160:163], v[194:197], v[14:17]
	v_mfma_f32_16x16x32_bf16 v[10:13], v[168:171], v[194:197], v[10:13]
	v_mfma_f32_16x16x32_bf16 v[6:9], v[160:163], v[210:213], v[6:9]
	s_barrier
	v_mfma_f32_16x16x32_bf16 v[2:5], v[168:171], v[210:213], v[2:5]
	s_setprio 0
	s_add_i32 s33, 0, 0x18000
	v_add_u32_e32 v142, s33, v146
	s_add_i32 s57, 0, 0x1c000
	ds_read_b128 v[132:135], v142
	ds_read_b128 v[136:139], v142 offset:1024
	ds_read_b128 v[148:151], v142 offset:2048
	ds_read_b128 v[152:155], v142 offset:3072
	v_add_u32_e32 v142, s57, v146
	ds_read_b128 v[156:159], v142
	ds_read_b128 v[160:163], v142 offset:1024
	ds_read_b128 v[164:167], v142 offset:2048
	ds_read_b128 v[168:171], v142 offset:3072
	s_add_u32 s0, s34, 0x80000
	s_addc_u32 s1, s35, 0
	s_mov_b32 m0, s41
	v_lshl_add_u64 v[144:145], s[0:1], 0, v[130:131]
	ds_read_b128 v[172:175], v147 offset:32768
	ds_read_b128 v[176:179], v147 offset:33792
	ds_read_b128 v[180:183], v147 offset:34816
	ds_read_b128 v[184:187], v147 offset:35840
	ds_read_b128 v[188:191], v147 offset:36864
	ds_read_b128 v[194:197], v147 offset:37888
	ds_read_b128 v[206:209], v147 offset:38912
	ds_read_b128 v[210:213], v147 offset:39936
	global_load_lds_dwordx4 v[144:145], off
	v_lshl_add_u64 v[144:145], s[0:1], 0, v[140:141]
	s_mov_b32 m0, s42
	s_nop 0
	global_load_lds_dwordx4 v[144:145], off
	s_waitcnt vmcnt(8)
	s_waitcnt lgkmcnt(0)
	s_barrier
	s_setprio 1
	s_waitcnt lgkmcnt(0)
	v_mfma_f32_16x16x32_bf16 v[126:129], v[132:135], v[172:175], v[126:129]
	v_mfma_f32_16x16x32_bf16 v[122:125], v[148:151], v[172:175], v[122:125]
	v_mfma_f32_16x16x32_bf16 v[118:121], v[132:135], v[180:183], v[118:121]
	v_mfma_f32_16x16x32_bf16 v[114:117], v[148:151], v[180:183], v[114:117]
	v_mfma_f32_16x16x32_bf16 v[110:113], v[132:135], v[188:191], v[110:113]
	v_mfma_f32_16x16x32_bf16 v[106:109], v[148:151], v[188:191], v[106:109]
	v_mfma_f32_16x16x32_bf16 v[102:105], v[132:135], v[206:209], v[102:105]
	v_mfma_f32_16x16x32_bf16 v[98:101], v[148:151], v[206:209], v[98:101]
	v_mfma_f32_16x16x32_bf16 v[126:129], v[136:139], v[176:179], v[126:129]
	v_mfma_f32_16x16x32_bf16 v[122:125], v[152:155], v[176:179], v[122:125]
	v_mfma_f32_16x16x32_bf16 v[118:121], v[136:139], v[184:187], v[118:121]
	v_mfma_f32_16x16x32_bf16 v[114:117], v[152:155], v[184:187], v[114:117]
	v_mfma_f32_16x16x32_bf16 v[110:113], v[136:139], v[194:197], v[110:113]
	v_mfma_f32_16x16x32_bf16 v[106:109], v[152:155], v[194:197], v[106:109]
	v_mfma_f32_16x16x32_bf16 v[102:105], v[136:139], v[210:213], v[102:105]
	v_mfma_f32_16x16x32_bf16 v[98:101], v[152:155], v[210:213], v[98:101]
	s_setprio 0
	s_setprio 1
	v_mfma_f32_16x16x32_bf16 v[62:65], v[156:159], v[172:175], v[62:65]
	v_mfma_f32_16x16x32_bf16 v[58:61], v[164:167], v[172:175], v[58:61]
	v_mfma_f32_16x16x32_bf16 v[54:57], v[156:159], v[180:183], v[54:57]
	v_mfma_f32_16x16x32_bf16 v[50:53], v[164:167], v[180:183], v[50:53]
	v_mfma_f32_16x16x32_bf16 v[46:49], v[156:159], v[188:191], v[46:49]
	v_mfma_f32_16x16x32_bf16 v[42:45], v[164:167], v[188:191], v[42:45]
	v_mfma_f32_16x16x32_bf16 v[38:41], v[156:159], v[206:209], v[38:41]
	v_mfma_f32_16x16x32_bf16 v[34:37], v[164:167], v[206:209], v[34:37]
	v_mfma_f32_16x16x32_bf16 v[62:65], v[160:163], v[176:179], v[62:65]
	v_mfma_f32_16x16x32_bf16 v[58:61], v[168:171], v[176:179], v[58:61]
	v_mfma_f32_16x16x32_bf16 v[54:57], v[160:163], v[184:187], v[54:57]
	v_mfma_f32_16x16x32_bf16 v[50:53], v[168:171], v[184:187], v[50:53]
	v_mfma_f32_16x16x32_bf16 v[46:49], v[160:163], v[194:197], v[46:49]
	v_mfma_f32_16x16x32_bf16 v[42:45], v[168:171], v[194:197], v[42:45]
	v_mfma_f32_16x16x32_bf16 v[38:41], v[160:163], v[210:213], v[38:41]
	s_barrier
; #define PG8_STAGE(bufoff, gbase, voff) do { _Pragma("unroll") for (int _i = 0; _i < 2; ++_i) \
;         __builtin_amdgcn_global_load_lds((const unsigned*)((const char*)(gbase) + (voff)[_i]), (LAS unsigned*)(lds + (bufoff) + ldsw + _i * 8192), 16, 0, 0); } while (0)
; #define PG8_LDA(dst, b, h) do { _Pragma("unroll") for (int m = 0; m < 4; ++m) _Pragma("unroll") for (int k = 0; k < 2; ++k) dst[m][k] = *(const LAS bf16x8*)(lds + PG8_SA(b, h) + aoff + m * 2048 + k * 1024); } while (0)
; #define PG8_MMA(ai, bj, At, Bt) do { __builtin_amdgcn_s_setprio(1); _Pragma("unroll") for (int m = 0; m < 4; ++m) _Pragma("unroll") for (int n = 0; n < 2; ++n) _Pragma("unroll") for (int k = 0; k < 2; ++k) \
;         acc[ai][bj][m][n] = __builtin_amdgcn_mfma_f32_16x16x32_bf16(Bt[n][k], At[m][k], acc[ai][bj][m][n], 0, 0, 0); __builtin_amdgcn_s_setprio(0); } while (0)
; #define PG8_WAIT_V(n) asm volatile("s_waitcnt vmcnt(" #n ")" ::: "memory")
; #define PG8_WAIT_L(n) asm volatile("s_waitcnt lgkmcnt(" #n ")" ::: "memory")
; #define PG8_BAR __builtin_amdgcn_s_barrier()
; #define PG8_SCHED __builtin_amdgcn_sched_barrier(0)
; template <class Epi, bool ALIGN_EPI = true, bool SP2 = true>
; __device__ __forceinline__ void gemm_phase(LAS unsigned char* lds, const Gemm g, const StaticOrder& S, const Epi& E, unsigned long long& tacc, const int tmode) {
;     ...
;             PG8_WAIT_V(8); PG8_WAIT_L(0); PG8_BAR; PG8_MMA(0, 0, At, B0); PG8_MMA(0, 1, At, B1); PG8_BAR; PG8_SCHED;
;             PG8_LDA(At, 1, 1); PG8_STAGE(PG8_SB(1, 0), b3, voffB); PG8_STAGE(PG8_SB(1, 1), b3 + hstepB, voffB); PG8_STAGE(PG8_SA(1, 0), a3, voffA);
;             PG8_WAIT_V(8); PG8_WAIT_L(0); PG8_BAR; PG8_MMA(1, 0, At, B0); PG8_MMA(1, 1, At, B1); PG8_BAR; PG8_SCHED;
	v_mfma_f32_16x16x32_bf16 v[34:37], v[168:171], v[210:213], v[34:37]
	s_setprio 0
	s_add_u32 s0, s38, 0x4000
	s_addc_u32 s1, s39, 0
	s_add_i32 s33, s33, s2
	v_lshl_add_u64 v[144:145], s[0:1], 0, v[130:131]
	s_mov_b32 m0, s33
	ds_read_b128 v[172:175], v147 offset:49152
	ds_read_b128 v[176:179], v147 offset:50176
	ds_read_b128 v[180:183], v147 offset:51200
	ds_read_b128 v[184:187], v147 offset:52224
	ds_read_b128 v[188:191], v147 offset:53248
	ds_read_b128 v[194:197], v147 offset:54272
	ds_read_b128 v[206:209], v147 offset:55296
	ds_read_b128 v[210:213], v147 offset:56320
	global_load_lds_dwordx4 v[144:145], off
	s_add_i32 m0, s33, 0x2000
	v_lshl_add_u64 v[144:145], s[0:1], 0, v[140:141]
	s_add_u32 s0, s38, 0x84000
	s_addc_u32 s1, s39, 0
	s_add_i32 s33, s57, s2
	global_load_lds_dwordx4 v[144:145], off
	v_lshl_add_u64 v[144:145], s[0:1], 0, v[130:131]
	s_mov_b32 m0, s33
	s_nop 0
	global_load_lds_dwordx4 v[144:145], off
	v_lshl_add_u64 v[144:145], s[0:1], 0, v[140:141]
	s_add_i32 m0, s33, 0x2000
	s_nop 0
	global_load_lds_dwordx4 v[144:145], off
	v_lshl_add_u64 v[144:145], s[30:31], 0, v[130:131]
	s_mov_b32 m0, s45
	s_nop 0
	global_load_lds_dwordx4 v[144:145], off
	v_lshl_add_u64 v[144:145], s[30:31], 0, v[140:141]
	s_mov_b32 m0, s46
	s_nop 0
	global_load_lds_dwordx4 v[144:145], off
	s_waitcnt vmcnt(8)
	s_waitcnt lgkmcnt(0)
	s_barrier
	s_setprio 1
	s_waitcnt lgkmcnt(0)
	v_mfma_f32_16x16x32_bf16 v[94:97], v[132:135], v[172:175], v[94:97]
	v_mfma_f32_16x16x32_bf16 v[90:93], v[148:151], v[172:175], v[90:93]
	v_mfma_f32_16x16x32_bf16 v[86:89], v[132:135], v[180:183], v[86:89]
	v_mfma_f32_16x16x32_bf16 v[82:85], v[148:151], v[180:183], v[82:85]
	v_mfma_f32_16x16x32_bf16 v[78:81], v[132:135], v[188:191], v[78:81]
	v_mfma_f32_16x16x32_bf16 v[74:77], v[148:151], v[188:191], v[74:77]
	v_mfma_f32_16x16x32_bf16 v[70:73], v[132:135], v[206:209], v[70:73]
	v_mfma_f32_16x16x32_bf16 v[66:69], v[148:151], v[206:209], v[66:69]
	v_mfma_f32_16x16x32_bf16 v[94:97], v[136:139], v[176:179], v[94:97]
	v_mfma_f32_16x16x32_bf16 v[90:93], v[152:155], v[176:179], v[90:93]
	v_mfma_f32_16x16x32_bf16 v[86:89], v[136:139], v[184:187], v[86:89]
	v_mfma_f32_16x16x32_bf16 v[82:85], v[152:155], v[184:187], v[82:85]
	v_mfma_f32_16x16x32_bf16 v[78:81], v[136:139], v[194:197], v[78:81]
	v_mfma_f32_16x16x32_bf16 v[74:77], v[152:155], v[194:197], v[74:77]
	v_mfma_f32_16x16x32_bf16 v[70:73], v[136:139], v[210:213], v[70:73]
	v_mfma_f32_16x16x32_bf16 v[66:69], v[152:155], v[210:213], v[66:69]
	s_setprio 0
	s_setprio 1
	v_mfma_f32_16x16x32_bf16 v[30:33], v[156:159], v[172:175], v[30:33]
	v_mfma_f32_16x16x32_bf16 v[26:29], v[164:167], v[172:175], v[26:29]
	v_mfma_f32_16x16x32_bf16 v[22:25], v[156:159], v[180:183], v[22:25]
	v_mfma_f32_16x16x32_bf16 v[18:21], v[164:167], v[180:183], v[18:21]
	v_mfma_f32_16x16x32_bf16 v[14:17], v[156:159], v[188:191], v[14:17]
	v_mfma_f32_16x16x32_bf16 v[10:13], v[164:167], v[188:191], v[10:13]
	v_mfma_f32_16x16x32_bf16 v[6:9], v[156:159], v[206:209], v[6:9]
	v_mfma_f32_16x16x32_bf16 v[2:5], v[164:167], v[206:209], v[2:5]
	v_mfma_f32_16x16x32_bf16 v[30:33], v[160:163], v[176:179], v[30:33]
	v_mfma_f32_16x16x32_bf16 v[26:29], v[168:171], v[176:179], v[26:29]
	v_mfma_f32_16x16x32_bf16 v[22:25], v[160:163], v[184:187], v[22:25]
	v_mfma_f32_16x16x32_bf16 v[18:21], v[168:171], v[184:187], v[18:21]
	v_mfma_f32_16x16x32_bf16 v[14:17], v[160:163], v[194:197], v[14:17]
	v_mfma_f32_16x16x32_bf16 v[10:13], v[168:171], v[194:197], v[10:13]
	v_mfma_f32_16x16x32_bf16 v[6:9], v[160:163], v[210:213], v[6:9]
	s_barrier
	v_mfma_f32_16x16x32_bf16 v[2:5], v[168:171], v[210:213], v[2:5]
	s_setprio 0
	s_add_i32 s56, s56, 2
	s_add_u32 s22, s22, 0x8000
	s_addc_u32 s23, s23, 0
	s_add_u32 s54, s54, 0x8000
	s_addc_u32 s55, s55, 0
	s_cmp_lt_u32 s56, 30
	s_cbranch_scc1 .LBB0_581
	s_andn2_b64 vcc, exec, s[18:19]
	s_cbranch_vccnz .LBB0_584
	s_barrier

; #define PG8_STAGE(bufoff, gbase, voff) do { _Pragma("unroll") for (int _i = 0; _i < 2; ++_i) \
;         __builtin_amdgcn_global_load_lds((const unsigned*)((const char*)(gbase) + (voff)[_i]), (LAS unsigned*)(lds + (bufoff) + ldsw + _i * 8192), 16, 0, 0); } while (0)
; #define PG8_LDA(dst, b, h) do { _Pragma("unroll") for (int m = 0; m < 4; ++m) _Pragma("unroll") for (int k = 0; k < 2; ++k) dst[m][k] = *(const LAS bf16x8*)(lds + PG8_SA(b, h) + aoff + m * 2048 + k * 1024); } while (0)
; #define PG8_LDB(dst, b, h) do { _Pragma("unroll") for (int n = 0; n < 2; ++n) _Pragma("unroll") for (int k = 0; k < 2; ++k) dst[n][k] = *(const LAS bf16x8*)(lds + PG8_SB(b, h) + boff + n * 2048 + k * 1024); } while (0)
; #define PG8_MMA(ai, bj, At, Bt) do { __builtin_amdgcn_s_setprio(1); _Pragma("unroll") for (int m = 0; m < 4; ++m) _Pragma("unroll") for (int n = 0; n < 2; ++n) _Pragma("unroll") for (int k = 0; k < 2; ++k) \
;         acc[ai][bj][m][n] = __builtin_amdgcn_mfma_f32_16x16x32_bf16(Bt[n][k], At[m][k], acc[ai][bj][m][n], 0, 0, 0); __builtin_amdgcn_s_setprio(0); } while (0)
; #define PG8_WAIT_V(n) asm volatile("s_waitcnt vmcnt(" #n ")" ::: "memory")
; #define PG8_WAIT_L(n) asm volatile("s_waitcnt lgkmcnt(" #n ")" ::: "memory")
; #define PG8_BAR __builtin_amdgcn_s_barrier()
; #define PG8_SCHED __builtin_amdgcn_sched_barrier(0)
; template <class Epi, bool ALIGN_EPI = true, bool SP2 = true>
; __device__ __forceinline__ void gemm_phase(LAS unsigned char* lds, const Gemm g, const StaticOrder& S, const Epi& E, unsigned long long& tacc, const int tmode) {
;     ...
;             const bool last = (t == nt - 2);
;             const char* a1 = cA + (size_t)(t + 1) * kstepA;
;             const char* a2 = last ? nA : cA + (size_t)(t + 2) * kstepA; const char* b2 = last ? nB : cB + (size_t)(t + 2) * kstepB;
;             const char* a3 = a2 + kstepA; const char* b3 = b2 + kstepB;
;             if constexpr (SP2) {
;             PG8_LDB(B0, 0, 0); PG8_LDB(B1, 0, 1); PG8_SCHED; PG8_LDA(At, 0, 0); PG8_STAGE(PG8_SA(1, 1), a1 + hstepA, voffA);
;             PG8_WAIT_V(8); PG8_WAIT_L(0); PG8_BAR; PG8_MMA(0, 0, At, B0); PG8_MMA(0, 1, At, B1); PG8_BAR; PG8_SCHED;
;             PG8_LDA(At, 0, 1); PG8_STAGE(PG8_SB(0, 0), b2, voffB); PG8_STAGE(PG8_SB(0, 1), b2 + hstepB, voffB); PG8_STAGE(PG8_SA(0, 0), a2, voffA);
.LBB0_739:
	s_add_u32 s0, s22, 0xfff84000
	s_addc_u32 s1, s23, -1
	s_cmp_eq_u32 s65, 28
	s_cselect_b32 s34, s56, s0
	s_cselect_b32 s35, s25, s1
	s_cselect_b32 s40, s57, s60
	s_cselect_b32 s41, s21, s61
	s_add_u32 s30, s34, 0x4000
	s_addc_u32 s31, s35, 0
	s_add_i32 s0, 0, 0x10000
	v_add_u32_e32 v138, s0, v141
	s_add_i32 s33, 0, 0x14000
	ds_read_b128 v[134:137], v138
	ds_read_b128 v[144:147], v138 offset:1024
	ds_read_b128 v[148:151], v138 offset:2048
	ds_read_b128 v[152:155], v138 offset:3072
	v_add_u32_e32 v138, s33, v141
	ds_read_b128 v[156:159], v138
	ds_read_b128 v[160:163], v138 offset:1024
	ds_read_b128 v[164:167], v138 offset:2048
	ds_read_b128 v[168:171], v138 offset:3072
	v_lshl_add_u64 v[138:139], s[22:23], 0, v[130:131]
	s_add_i32 m0, s43, 0xc000
	ds_read_b128 v[172:175], v142
	ds_read_b128 v[176:179], v142 offset:1024
	ds_read_b128 v[180:183], v142 offset:2048
	ds_read_b128 v[184:187], v142 offset:3072
	ds_read_b128 v[188:191], v142 offset:4096
	ds_read_b128 v[206:209], v142 offset:5120
	ds_read_b128 v[210:213], v142 offset:6144
	ds_read_b128 v[214:217], v142 offset:7168
	global_load_lds_dwordx4 v[138:139], off
	v_lshl_add_u64 v[138:139], s[22:23], 0, v[132:133]
	s_add_i32 m0, s43, 0xe000
	s_nop 0
	global_load_lds_dwordx4 v[138:139], off
	s_waitcnt vmcnt(8)
	s_waitcnt lgkmcnt(0)
	s_barrier
	s_setprio 1
	s_waitcnt lgkmcnt(0)
	v_mfma_f32_16x16x32_bf16 v[126:129], v[134:137], v[172:175], v[126:129]
	v_mfma_f32_16x16x32_bf16 v[122:125], v[148:151], v[172:175], v[122:125]
	v_mfma_f32_16x16x32_bf16 v[110:113], v[134:137], v[180:183], v[110:113]
	v_mfma_f32_16x16x32_bf16 v[106:109], v[148:151], v[180:183], v[106:109]
	v_mfma_f32_16x16x32_bf16 v[94:97], v[134:137], v[188:191], v[94:97]
	v_mfma_f32_16x16x32_bf16 v[90:93], v[148:151], v[188:191], v[90:93]
	v_mfma_f32_16x16x32_bf16 v[78:81], v[134:137], v[210:213], v[78:81]
	v_mfma_f32_16x16x32_bf16 v[74:77], v[148:151], v[210:213], v[74:77]
	v_mfma_f32_16x16x32_bf16 v[126:129], v[144:147], v[176:179], v[126:129]
	v_mfma_f32_16x16x32_bf16 v[122:125], v[152:155], v[176:179], v[122:125]
	v_mfma_f32_16x16x32_bf16 v[110:113], v[144:147], v[184:187], v[110:113]
	v_mfma_f32_16x16x32_bf16 v[106:109], v[152:155], v[184:187], v[106:109]
	v_mfma_f32_16x16x32_bf16 v[94:97], v[144:147], v[206:209], v[94:97]
	v_mfma_f32_16x16x32_bf16 v[90:93], v[152:155], v[206:209], v[90:93]
	v_mfma_f32_16x16x32_bf16 v[78:81], v[144:147], v[214:217], v[78:81]
	v_mfma_f32_16x16x32_bf16 v[74:77], v[152:155], v[214:217], v[74:77]
	s_setprio 0
	s_setprio 1
	v_mfma_f32_16x16x32_bf16 v[118:121], v[156:159], v[172:175], v[118:121]
	v_mfma_f32_16x16x32_bf16 v[114:117], v[164:167], v[172:175], v[114:117]
	v_mfma_f32_16x16x32_bf16 v[102:105], v[156:159], v[180:183], v[102:105]
	v_mfma_f32_16x16x32_bf16 v[98:101], v[164:167], v[180:183], v[98:101]
	v_mfma_f32_16x16x32_bf16 v[86:89], v[156:159], v[188:191], v[86:89]
	v_mfma_f32_16x16x32_bf16 v[82:85], v[164:167], v[188:191], v[82:85]
	v_mfma_f32_16x16x32_bf16 v[70:73], v[156:159], v[210:213], v[70:73]
	v_mfma_f32_16x16x32_bf16 v[66:69], v[164:167], v[210:213], v[66:69]
	v_mfma_f32_16x16x32_bf16 v[118:121], v[160:163], v[176:179], v[118:121]
	v_mfma_f32_16x16x32_bf16 v[114:117], v[168:171], v[176:179], v[114:117]
	v_mfma_f32_16x16x32_bf16 v[102:105], v[160:163], v[184:187], v[102:105]
	v_mfma_f32_16x16x32_bf16 v[98:101], v[168:171], v[184:187], v[98:101]
	v_mfma_f32_16x16x32_bf16 v[86:89], v[160:163], v[206:209], v[86:89]
	v_mfma_f32_16x16x32_bf16 v[82:85], v[168:171], v[206:209], v[82:85]
	v_mfma_f32_16x16x32_bf16 v[70:73], v[160:163], v[214:217], v[70:73]
	s_barrier
	v_mfma_f32_16x16x32_bf16 v[66:69], v[168:171], v[214:217], v[66:69]
	s_setprio 0
	s_add_i32 s0, s0, s42
	v_lshl_add_u64 v[138:139], s[40:41], 0, v[130:131]
	s_mov_b32 m0, s0
	ds_read_b128 v[172:175], v142 offset:16384
	ds_read_b128 v[176:179], v142 offset:17408
	ds_read_b128 v[180:183], v142 offset:18432
	ds_read_b128 v[184:187], v142 offset:19456
	ds_read_b128 v[188:191], v142 offset:20480
	ds_read_b128 v[206:209], v142 offset:21504
	ds_read_b128 v[210:213], v142 offset:22528
	ds_read_b128 v[214:217], v142 offset:23552
	global_load_lds_dwordx4 v[138:139], off
	s_add_i32 m0, s0, 0x2000
	s_add_u32 s0, s40, 0x80000
	v_lshl_add_u64 v[138:139], s[40:41], 0, v[132:133]
	s_addc_u32 s1, s41, 0
	s_add_i32 s33, s33, s42
	global_load_lds_dwordx4 v[138:139], off
	v_lshl_add_u64 v[138:139], s[0:1], 0, v[130:131]
	s_mov_b32 m0, s33
	s_nop 0
	global_load_lds_dwordx4 v[138:139], off
	v_lshl_add_u64 v[138:139], s[0:1], 0, v[132:133]
	s_add_i32 m0, s33, 0x2000
	s_nop 0
	global_load_lds_dwordx4 v[138:139], off
	v_lshl_add_u64 v[138:139], s[34:35], 0, v[130:131]
	s_mov_b32 m0, s43
	s_nop 0
	global_load_lds_dwordx4 v[138:139], off
	v_lshl_add_u64 v[138:139], s[34:35], 0, v[132:133]
	s_mov_b32 m0, s44
	s_nop 0
	global_load_lds_dwordx4 v[138:139], off
	s_waitcnt vmcnt(8)
	s_waitcnt lgkmcnt(0)
	s_barrier
; #define PG8_STAGE(bufoff, gbase, voff) do { _Pragma("unroll") for (int _i = 0; _i < 2; ++_i) \
;         __builtin_amdgcn_global_load_lds((const unsigned*)((const char*)(gbase) + (voff)[_i]), (LAS unsigned*)(lds + (bufoff) + ldsw + _i * 8192), 16, 0, 0); } while (0)
; #define PG8_LDA(dst, b, h) do { _Pragma("unroll") for (int m = 0; m < 4; ++m) _Pragma("unroll") for (int k = 0; k < 2; ++k) dst[m][k] = *(const LAS bf16x8*)(lds + PG8_SA(b, h) + aoff + m * 2048 + k * 1024); } while (0)
; #define PG8_LDB(dst, b, h) do { _Pragma("unroll") for (int n = 0; n < 2; ++n) _Pragma("unroll") for (int k = 0; k < 2; ++k) dst[n][k] = *(const LAS bf16x8*)(lds + PG8_SB(b, h) + boff + n * 2048 + k * 1024); } while (0)
; #define PG8_MMA(ai, bj, At, Bt) do { __builtin_amdgcn_s_setprio(1); _Pragma("unroll") for (int m = 0; m < 4; ++m) _Pragma("unroll") for (int n = 0; n < 2; ++n) _Pragma("unroll") for (int k = 0; k < 2; ++k) \
;         acc[ai][bj][m][n] = __builtin_amdgcn_mfma_f32_16x16x32_bf16(Bt[n][k], At[m][k], acc[ai][bj][m][n], 0, 0, 0); __builtin_amdgcn_s_setprio(0); } while (0)
; #define PG8_WAIT_V(n) asm volatile("s_waitcnt vmcnt(" #n ")" ::: "memory")
; #define PG8_WAIT_L(n) asm volatile("s_waitcnt lgkmcnt(" #n ")" ::: "memory")
; #define PG8_BAR __builtin_amdgcn_s_barrier()
; #define PG8_SCHED __builtin_amdgcn_sched_barrier(0)
; template <class Epi, bool ALIGN_EPI = true, bool SP2 = true>
; __device__ __forceinline__ void gemm_phase(LAS unsigned char* lds, const Gemm g, const StaticOrder& S, const Epi& E, unsigned long long& tacc, const int tmode) {
;     ...
;             PG8_WAIT_V(8); PG8_WAIT_L(0); PG8_BAR; PG8_MMA(1, 0, At, B0); PG8_MMA(1, 1, At, B1); PG8_BAR; PG8_SCHED;
;             PG8_LDB(B0, 1, 0); PG8_LDB(B1, 1, 1); PG8_SCHED; PG8_LDA(At, 1, 0); PG8_STAGE(PG8_SA(0, 1), a2 + hstepA, voffA);
;             PG8_WAIT_V(8); PG8_WAIT_L(0); PG8_BAR; PG8_MMA(0, 0, At, B0); PG8_MMA(0, 1, At, B1); PG8_BAR; PG8_SCHED;
	s_setprio 1
	s_waitcnt lgkmcnt(0)
	v_mfma_f32_16x16x32_bf16 v[62:65], v[134:137], v[172:175], v[62:65]
	v_mfma_f32_16x16x32_bf16 v[58:61], v[148:151], v[172:175], v[58:61]
	v_mfma_f32_16x16x32_bf16 v[46:49], v[134:137], v[180:183], v[46:49]
	v_mfma_f32_16x16x32_bf16 v[42:45], v[148:151], v[180:183], v[42:45]
	v_mfma_f32_16x16x32_bf16 v[30:33], v[134:137], v[188:191], v[30:33]
	v_mfma_f32_16x16x32_bf16 v[26:29], v[148:151], v[188:191], v[26:29]
	v_mfma_f32_16x16x32_bf16 v[14:17], v[134:137], v[210:213], v[14:17]
	v_mfma_f32_16x16x32_bf16 v[10:13], v[148:151], v[210:213], v[10:13]
	v_mfma_f32_16x16x32_bf16 v[62:65], v[144:147], v[176:179], v[62:65]
	v_mfma_f32_16x16x32_bf16 v[58:61], v[152:155], v[176:179], v[58:61]
	v_mfma_f32_16x16x32_bf16 v[46:49], v[144:147], v[184:187], v[46:49]
	v_mfma_f32_16x16x32_bf16 v[42:45], v[152:155], v[184:187], v[42:45]
	v_mfma_f32_16x16x32_bf16 v[30:33], v[144:147], v[206:209], v[30:33]
	v_mfma_f32_16x16x32_bf16 v[26:29], v[152:155], v[206:209], v[26:29]
	v_mfma_f32_16x16x32_bf16 v[14:17], v[144:147], v[214:217], v[14:17]
	v_mfma_f32_16x16x32_bf16 v[10:13], v[152:155], v[214:217], v[10:13]
	s_setprio 0
	s_setprio 1
	v_mfma_f32_16x16x32_bf16 v[54:57], v[156:159], v[172:175], v[54:57]
	v_mfma_f32_16x16x32_bf16 v[50:53], v[164:167], v[172:175], v[50:53]
	v_mfma_f32_16x16x32_bf16 v[38:41], v[156:159], v[180:183], v[38:41]
	v_mfma_f32_16x16x32_bf16 v[34:37], v[164:167], v[180:183], v[34:37]
	v_mfma_f32_16x16x32_bf16 v[22:25], v[156:159], v[188:191], v[22:25]
	v_mfma_f32_16x16x32_bf16 v[18:21], v[164:167], v[188:191], v[18:21]
	v_mfma_f32_16x16x32_bf16 v[6:9], v[156:159], v[210:213], v[6:9]
	v_mfma_f32_16x16x32_bf16 v[2:5], v[164:167], v[210:213], v[2:5]
	v_mfma_f32_16x16x32_bf16 v[54:57], v[160:163], v[176:179], v[54:57]
	v_mfma_f32_16x16x32_bf16 v[50:53], v[168:171], v[176:179], v[50:53]
	v_mfma_f32_16x16x32_bf16 v[38:41], v[160:163], v[184:187], v[38:41]
	v_mfma_f32_16x16x32_bf16 v[34:37], v[168:171], v[184:187], v[34:37]
	v_mfma_f32_16x16x32_bf16 v[22:25], v[160:163], v[206:209], v[22:25]
	v_mfma_f32_16x16x32_bf16 v[18:21], v[168:171], v[206:209], v[18:21]
	v_mfma_f32_16x16x32_bf16 v[6:9], v[160:163], v[214:217], v[6:9]
	s_barrier
	v_mfma_f32_16x16x32_bf16 v[2:5], v[168:171], v[214:217], v[2:5]
	s_setprio 0
	s_add_i32 s33, 0, 0x18000
	v_add_u32_e32 v138, s33, v141
	s_add_i32 s64, 0, 0x1c000
	ds_read_b128 v[134:137], v138
	ds_read_b128 v[144:147], v138 offset:1024
	ds_read_b128 v[148:151], v138 offset:2048
	ds_read_b128 v[152:155], v138 offset:3072
	v_add_u32_e32 v138, s64, v141
	ds_read_b128 v[156:159], v138
	ds_read_b128 v[160:163], v138 offset:1024
	ds_read_b128 v[164:167], v138 offset:2048
	ds_read_b128 v[168:171], v138 offset:3072
	s_add_u32 s0, s34, 0x80000
	s_addc_u32 s1, s35, 0
	s_mov_b32 m0, s45
	v_lshl_add_u64 v[138:139], s[0:1], 0, v[130:131]
	ds_read_b128 v[172:175], v142 offset:32768
	ds_read_b128 v[176:179], v142 offset:33792
	ds_read_b128 v[180:183], v142 offset:34816
	ds_read_b128 v[184:187], v142 offset:35840
	ds_read_b128 v[188:191], v142 offset:36864
	ds_read_b128 v[206:209], v142 offset:37888
	ds_read_b128 v[210:213], v142 offset:38912
	ds_read_b128 v[214:217], v142 offset:39936
	global_load_lds_dwordx4 v[138:139], off
	v_lshl_add_u64 v[138:139], s[0:1], 0, v[132:133]
	s_mov_b32 m0, s46
	s_nop 0
	global_load_lds_dwordx4 v[138:139], off
	s_waitcnt vmcnt(8)
	s_waitcnt lgkmcnt(0)
	s_barrier
	s_setprio 1
	s_waitcnt lgkmcnt(0)
	v_mfma_f32_16x16x32_bf16 v[126:129], v[134:137], v[172:175], v[126:129]
	v_mfma_f32_16x16x32_bf16 v[122:125], v[148:151], v[172:175], v[122:125]
	v_mfma_f32_16x16x32_bf16 v[110:113], v[134:137], v[180:183], v[110:113]
	v_mfma_f32_16x16x32_bf16 v[106:109], v[148:151], v[180:183], v[106:109]
	v_mfma_f32_16x16x32_bf16 v[94:97], v[134:137], v[188:191], v[94:97]
	v_mfma_f32_16x16x32_bf16 v[90:93], v[148:151], v[188:191], v[90:93]
	v_mfma_f32_16x16x32_bf16 v[78:81], v[134:137], v[210:213], v[78:81]
	v_mfma_f32_16x16x32_bf16 v[74:77], v[148:151], v[210:213], v[74:77]
	v_mfma_f32_16x16x32_bf16 v[126:129], v[144:147], v[176:179], v[126:129]
	v_mfma_f32_16x16x32_bf16 v[122:125], v[152:155], v[176:179], v[122:125]
	v_mfma_f32_16x16x32_bf16 v[110:113], v[144:147], v[184:187], v[110:113]
	v_mfma_f32_16x16x32_bf16 v[106:109], v[152:155], v[184:187], v[106:109]
	v_mfma_f32_16x16x32_bf16 v[94:97], v[144:147], v[206:209], v[94:97]
	v_mfma_f32_16x16x32_bf16 v[90:93], v[152:155], v[206:209], v[90:93]
	v_mfma_f32_16x16x32_bf16 v[78:81], v[144:147], v[214:217], v[78:81]
	v_mfma_f32_16x16x32_bf16 v[74:77], v[152:155], v[214:217], v[74:77]
	s_setprio 0
	s_setprio 1
	v_mfma_f32_16x16x32_bf16 v[118:121], v[156:159], v[172:175], v[118:121]
	v_mfma_f32_16x16x32_bf16 v[114:117], v[164:167], v[172:175], v[114:117]
	v_mfma_f32_16x16x32_bf16 v[102:105], v[156:159], v[180:183], v[102:105]
	v_mfma_f32_16x16x32_bf16 v[98:101], v[164:167], v[180:183], v[98:101]
	v_mfma_f32_16x16x32_bf16 v[86:89], v[156:159], v[188:191], v[86:89]
	v_mfma_f32_16x16x32_bf16 v[82:85], v[164:167], v[188:191], v[82:85]
	v_mfma_f32_16x16x32_bf16 v[70:73], v[156:159], v[210:213], v[70:73]
	v_mfma_f32_16x16x32_bf16 v[66:69], v[164:167], v[210:213], v[66:69]
	v_mfma_f32_16x16x32_bf16 v[118:121], v[160:163], v[176:179], v[118:121]
	v_mfma_f32_16x16x32_bf16 v[114:117], v[168:171], v[176:179], v[114:117]
	v_mfma_f32_16x16x32_bf16 v[102:105], v[160:163], v[184:187], v[102:105]
	v_mfma_f32_16x16x32_bf16 v[98:101], v[168:171], v[184:187], v[98:101]
	v_mfma_f32_16x16x32_bf16 v[86:89], v[160:163], v[206:209], v[86:89]
	v_mfma_f32_16x16x32_bf16 v[82:85], v[168:171], v[206:209], v[82:85]
	v_mfma_f32_16x16x32_bf16 v[70:73], v[160:163], v[214:217], v[70:73]
	s_barrier
; #define PG8_STAGE(bufoff, gbase, voff) do { _Pragma("unroll") for (int _i = 0; _i < 2; ++_i) \
;         __builtin_amdgcn_global_load_lds((const unsigned*)((const char*)(gbase) + (voff)[_i]), (LAS unsigned*)(lds + (bufoff) + ldsw + _i * 8192), 16, 0, 0); } while (0)
; #define PG8_LDA(dst, b, h) do { _Pragma("unroll") for (int m = 0; m < 4; ++m) _Pragma("unroll") for (int k = 0; k < 2; ++k) dst[m][k] = *(const LAS bf16x8*)(lds + PG8_SA(b, h) + aoff + m * 2048 + k * 1024); } while (0)
; #define PG8_MMA(ai, bj, At, Bt) do { __builtin_amdgcn_s_setprio(1); _Pragma("unroll") for (int m = 0; m < 4; ++m) _Pragma("unroll") for (int n = 0; n < 2; ++n) _Pragma("unroll") for (int k = 0; k < 2; ++k) \
;         acc[ai][bj][m][n] = __builtin_amdgcn_mfma_f32_16x16x32_bf16(Bt[n][k], At[m][k], acc[ai][bj][m][n], 0, 0, 0); __builtin_amdgcn_s_setprio(0); } while (0)
; #define PG8_WAIT_V(n) asm volatile("s_waitcnt vmcnt(" #n ")" ::: "memory")
; #define PG8_WAIT_L(n) asm volatile("s_waitcnt lgkmcnt(" #n ")" ::: "memory")
; #define PG8_BAR __builtin_amdgcn_s_barrier()
; #define PG8_SCHED __builtin_amdgcn_sched_barrier(0)
; template <class Epi, bool ALIGN_EPI = true, bool SP2 = true>
; __device__ __forceinline__ void gemm_phase(LAS unsigned char* lds, const Gemm g, const StaticOrder& S, const Epi& E, unsigned long long& tacc, const int tmode) {
;     ...
;             PG8_WAIT_V(8); PG8_WAIT_L(0); PG8_BAR; PG8_MMA(0, 0, At, B0); PG8_MMA(0, 1, At, B1); PG8_BAR; PG8_SCHED;
;             PG8_LDA(At, 1, 1); PG8_STAGE(PG8_SB(1, 0), b3, voffB); PG8_STAGE(PG8_SB(1, 1), b3 + hstepB, voffB); PG8_STAGE(PG8_SA(1, 0), a3, voffA);
;             PG8_WAIT_V(8); PG8_WAIT_L(0); PG8_BAR; PG8_MMA(1, 0, At, B0); PG8_MMA(1, 1, At, B1); PG8_BAR; PG8_SCHED;
	v_mfma_f32_16x16x32_bf16 v[66:69], v[168:171], v[214:217], v[66:69]
	s_setprio 0
	s_add_u32 s0, s40, 0x4000
	s_addc_u32 s1, s41, 0
	s_add_i32 s33, s33, s42
	v_lshl_add_u64 v[138:139], s[0:1], 0, v[130:131]
	s_mov_b32 m0, s33
	ds_read_b128 v[172:175], v142 offset:49152
	ds_read_b128 v[176:179], v142 offset:50176
	ds_read_b128 v[180:183], v142 offset:51200
	ds_read_b128 v[184:187], v142 offset:52224
	ds_read_b128 v[188:191], v142 offset:53248
	ds_read_b128 v[206:209], v142 offset:54272
	ds_read_b128 v[210:213], v142 offset:55296
	ds_read_b128 v[214:217], v142 offset:56320
	global_load_lds_dwordx4 v[138:139], off
	s_add_i32 m0, s33, 0x2000
	v_lshl_add_u64 v[138:139], s[0:1], 0, v[132:133]
	s_add_u32 s0, s40, 0x84000
	s_addc_u32 s1, s41, 0
	s_add_i32 s33, s64, s42
	global_load_lds_dwordx4 v[138:139], off
	v_lshl_add_u64 v[138:139], s[0:1], 0, v[130:131]
	s_mov_b32 m0, s33
	s_nop 0
	global_load_lds_dwordx4 v[138:139], off
	v_lshl_add_u64 v[138:139], s[0:1], 0, v[132:133]
	s_add_i32 m0, s33, 0x2000
	s_nop 0
	global_load_lds_dwordx4 v[138:139], off
	v_lshl_add_u64 v[138:139], s[30:31], 0, v[130:131]
	s_mov_b32 m0, s49
	s_nop 0
	global_load_lds_dwordx4 v[138:139], off
	v_lshl_add_u64 v[138:139], s[30:31], 0, v[132:133]
	s_mov_b32 m0, s50
	s_nop 0
	global_load_lds_dwordx4 v[138:139], off
	s_waitcnt vmcnt(8)
	s_waitcnt lgkmcnt(0)
	s_barrier
	s_setprio 1
	s_waitcnt lgkmcnt(0)
	v_mfma_f32_16x16x32_bf16 v[62:65], v[134:137], v[172:175], v[62:65]
	v_mfma_f32_16x16x32_bf16 v[58:61], v[148:151], v[172:175], v[58:61]
	v_mfma_f32_16x16x32_bf16 v[46:49], v[134:137], v[180:183], v[46:49]
	v_mfma_f32_16x16x32_bf16 v[42:45], v[148:151], v[180:183], v[42:45]
	v_mfma_f32_16x16x32_bf16 v[30:33], v[134:137], v[188:191], v[30:33]
	v_mfma_f32_16x16x32_bf16 v[26:29], v[148:151], v[188:191], v[26:29]
	v_mfma_f32_16x16x32_bf16 v[14:17], v[134:137], v[210:213], v[14:17]
	v_mfma_f32_16x16x32_bf16 v[10:13], v[148:151], v[210:213], v[10:13]
	v_mfma_f32_16x16x32_bf16 v[62:65], v[144:147], v[176:179], v[62:65]
	v_mfma_f32_16x16x32_bf16 v[58:61], v[152:155], v[176:179], v[58:61]
	v_mfma_f32_16x16x32_bf16 v[46:49], v[144:147], v[184:187], v[46:49]
	v_mfma_f32_16x16x32_bf16 v[42:45], v[152:155], v[184:187], v[42:45]
	v_mfma_f32_16x16x32_bf16 v[30:33], v[144:147], v[206:209], v[30:33]
	v_mfma_f32_16x16x32_bf16 v[26:29], v[152:155], v[206:209], v[26:29]
	v_mfma_f32_16x16x32_bf16 v[14:17], v[144:147], v[214:217], v[14:17]
	v_mfma_f32_16x16x32_bf16 v[10:13], v[152:155], v[214:217], v[10:13]
	s_setprio 0
	s_setprio 1
	v_mfma_f32_16x16x32_bf16 v[54:57], v[156:159], v[172:175], v[54:57]
	v_mfma_f32_16x16x32_bf16 v[50:53], v[164:167], v[172:175], v[50:53]
	v_mfma_f32_16x16x32_bf16 v[38:41], v[156:159], v[180:183], v[38:41]
	v_mfma_f32_16x16x32_bf16 v[34:37], v[164:167], v[180:183], v[34:37]
	v_mfma_f32_16x16x32_bf16 v[22:25], v[156:159], v[188:191], v[22:25]
	v_mfma_f32_16x16x32_bf16 v[18:21], v[164:167], v[188:191], v[18:21]
	v_mfma_f32_16x16x32_bf16 v[6:9], v[156:159], v[210:213], v[6:9]
	v_mfma_f32_16x16x32_bf16 v[2:5], v[164:167], v[210:213], v[2:5]
	v_mfma_f32_16x16x32_bf16 v[54:57], v[160:163], v[176:179], v[54:57]
	v_mfma_f32_16x16x32_bf16 v[50:53], v[168:171], v[176:179], v[50:53]
	v_mfma_f32_16x16x32_bf16 v[38:41], v[160:163], v[184:187], v[38:41]
	v_mfma_f32_16x16x32_bf16 v[34:37], v[168:171], v[184:187], v[34:37]
	v_mfma_f32_16x16x32_bf16 v[22:25], v[160:163], v[206:209], v[22:25]
	v_mfma_f32_16x16x32_bf16 v[18:21], v[168:171], v[206:209], v[18:21]
	v_mfma_f32_16x16x32_bf16 v[6:9], v[160:163], v[214:217], v[6:9]
	s_barrier
	v_mfma_f32_16x16x32_bf16 v[2:5], v[168:171], v[214:217], v[2:5]
	s_setprio 0
	s_add_i32 s65, s65, 2
	s_add_u32 s22, s22, 0x8000
	s_addc_u32 s23, s23, 0
	s_add_u32 s60, s60, 0x8000
	s_addc_u32 s61, s61, 0
	s_cmp_lt_u32 s65, 30
	s_cbranch_scc1 .LBB0_739
	s_andn2_b64 vcc, exec, s[18:19]
	s_cbranch_vccnz .LBB0_742
	s_barrier

; #define PG8_STAGE(bufoff, gbase, voff) do { _Pragma("unroll") for (int _i = 0; _i < 2; ++_i) \
;         __builtin_amdgcn_global_load_lds((const unsigned*)((const char*)(gbase) + (voff)[_i]), (LAS unsigned*)(lds + (bufoff) + ldsw + _i * 8192), 16, 0, 0); } while (0)
; #define PG8_LDA(dst, b, h) do { _Pragma("unroll") for (int m = 0; m < 4; ++m) _Pragma("unroll") for (int k = 0; k < 2; ++k) dst[m][k] = *(const LAS bf16x8*)(lds + PG8_SA(b, h) + aoff + m * 2048 + k * 1024); } while (0)
; #define PG8_LDB(dst, b, h) do { _Pragma("unroll") for (int n = 0; n < 2; ++n) _Pragma("unroll") for (int k = 0; k < 2; ++k) dst[n][k] = *(const LAS bf16x8*)(lds + PG8_SB(b, h) + boff + n * 2048 + k * 1024); } while (0)
; #define PG8_MMA(ai, bj, At, Bt) do { __builtin_amdgcn_s_setprio(1); _Pragma("unroll") for (int m = 0; m < 4; ++m) _Pragma("unroll") for (int n = 0; n < 2; ++n) _Pragma("unroll") for (int k = 0; k < 2; ++k) \
;         acc[ai][bj][m][n] = __builtin_amdgcn_mfma_f32_16x16x32_bf16(Bt[n][k], At[m][k], acc[ai][bj][m][n], 0, 0, 0); __builtin_amdgcn_s_setprio(0); } while (0)
; #define PG8_WAIT_V(n) asm volatile("s_waitcnt vmcnt(" #n ")" ::: "memory")
; #define PG8_WAIT_L(n) asm volatile("s_waitcnt lgkmcnt(" #n ")" ::: "memory")
; #define PG8_BAR __builtin_amdgcn_s_barrier()
; #define PG8_SCHED __builtin_amdgcn_sched_barrier(0)
; template <class Epi, bool ALIGN_EPI = true, bool SP2 = true>
; __device__ __forceinline__ void gemm_phase(LAS unsigned char* lds, const Gemm g, const StaticOrder& S, const Epi& E, unsigned long long& tacc, const int tmode) {
;     ...
;             const bool last = (t == nt - 2);
;             const char* a1 = cA + (size_t)(t + 1) * kstepA;
;             const char* a2 = last ? nA : cA + (size_t)(t + 2) * kstepA; const char* b2 = last ? nB : cB + (size_t)(t + 2) * kstepB;
;             const char* a3 = a2 + kstepA; const char* b3 = b2 + kstepB;
;             if constexpr (SP2) {
;             PG8_LDB(B0, 0, 0); PG8_LDB(B1, 0, 1); PG8_SCHED; PG8_LDA(At, 0, 0); PG8_STAGE(PG8_SA(1, 1), a1 + hstepA, voffA);
;             PG8_WAIT_V(8); PG8_WAIT_L(0); PG8_BAR; PG8_MMA(0, 0, At, B0); PG8_MMA(0, 1, At, B1); PG8_BAR; PG8_SCHED;
;             PG8_LDA(At, 0, 1); PG8_STAGE(PG8_SB(0, 0), b2, voffB); PG8_STAGE(PG8_SB(0, 1), b2 + hstepB, voffB); PG8_STAGE(PG8_SA(0, 0), a2, voffA);
.LBB0_1045:
	s_add_i32 s1, s0, 2
	s_add_u32 s33, s20, s42
	s_addc_u32 s34, s21, s43
	s_add_i32 s64, 0, 0x10000
	s_cmp_eq_u32 s17, s0
	s_cselect_b32 s45, s23, s34
	s_cselect_b32 s44, s22, s33
	v_add_u32_e32 v149, s64, v147
	s_cselect_b32 s35, s31, vcc_lo
	s_cselect_b32 s34, s30, s37
	s_add_i32 s0, 0, 0x14000
	ds_read_b128 v[150:153], v149
	ds_read_b128 v[154:157], v149 offset:1024
	ds_read_b128 v[158:161], v149 offset:2048
	ds_read_b128 v[162:165], v149 offset:3072
	v_add_u32_e32 v149, s0, v147
	ds_read_b128 v[166:169], v149
	ds_read_b128 v[170:173], v149 offset:1024
	ds_read_b128 v[174:177], v149 offset:2048
	ds_read_b128 v[178:181], v149 offset:3072
	v_lshl_add_u64 v[190:191], s[20:21], 0, v[144:145]
	s_add_i32 m0, s57, 0xc000
	ds_read_b128 v[182:185], v148
	ds_read_b128 v[186:189], v148 offset:1024
	ds_read_b128 v[194:197], v148 offset:2048
	ds_read_b128 v[206:209], v148 offset:3072
	ds_read_b128 v[210:213], v148 offset:4096
	ds_read_b128 v[214:217], v148 offset:5120
	ds_read_b128 v[218:221], v148 offset:6144
	ds_read_b128 v[222:225], v148 offset:7168
	global_load_lds_dwordx4 v[190:191], off
	v_lshl_add_u64 v[190:191], s[20:21], 0, v[142:143]
	s_add_i32 m0, s57, 0xe000
	s_nop 0
	global_load_lds_dwordx4 v[190:191], off
	s_waitcnt vmcnt(8)
	s_waitcnt lgkmcnt(0)
	s_barrier
	s_setprio 1
	s_waitcnt lgkmcnt(0)
	v_mfma_f32_16x16x32_bf16 v[126:129], v[150:153], v[182:185], v[126:129]
	v_mfma_f32_16x16x32_bf16 v[122:125], v[158:161], v[182:185], v[122:125]
	v_mfma_f32_16x16x32_bf16 v[118:121], v[150:153], v[194:197], v[118:121]
	v_mfma_f32_16x16x32_bf16 v[110:113], v[158:161], v[194:197], v[110:113]
	v_mfma_f32_16x16x32_bf16 v[102:105], v[150:153], v[210:213], v[102:105]
	v_mfma_f32_16x16x32_bf16 v[94:97], v[158:161], v[210:213], v[94:97]
	v_mfma_f32_16x16x32_bf16 v[86:89], v[150:153], v[218:221], v[86:89]
	v_mfma_f32_16x16x32_bf16 v[78:81], v[158:161], v[218:221], v[78:81]
	v_mfma_f32_16x16x32_bf16 v[126:129], v[154:157], v[186:189], v[126:129]
	v_mfma_f32_16x16x32_bf16 v[122:125], v[162:165], v[186:189], v[122:125]
	v_mfma_f32_16x16x32_bf16 v[118:121], v[154:157], v[206:209], v[118:121]
	v_mfma_f32_16x16x32_bf16 v[110:113], v[162:165], v[206:209], v[110:113]
	v_mfma_f32_16x16x32_bf16 v[102:105], v[154:157], v[214:217], v[102:105]
	v_mfma_f32_16x16x32_bf16 v[94:97], v[162:165], v[214:217], v[94:97]
	v_mfma_f32_16x16x32_bf16 v[86:89], v[154:157], v[222:225], v[86:89]
	v_mfma_f32_16x16x32_bf16 v[78:81], v[162:165], v[222:225], v[78:81]
	s_setprio 0
	s_setprio 1
	v_mfma_f32_16x16x32_bf16 v[114:117], v[166:169], v[182:185], v[114:117]
	v_mfma_f32_16x16x32_bf16 v[106:109], v[174:177], v[182:185], v[106:109]
	v_mfma_f32_16x16x32_bf16 v[98:101], v[166:169], v[194:197], v[98:101]
	v_mfma_f32_16x16x32_bf16 v[90:93], v[174:177], v[194:197], v[90:93]
	v_mfma_f32_16x16x32_bf16 v[82:85], v[166:169], v[210:213], v[82:85]
	v_mfma_f32_16x16x32_bf16 v[74:77], v[174:177], v[210:213], v[74:77]
	v_mfma_f32_16x16x32_bf16 v[70:73], v[166:169], v[218:221], v[70:73]
	v_mfma_f32_16x16x32_bf16 v[66:69], v[174:177], v[218:221], v[66:69]
	v_mfma_f32_16x16x32_bf16 v[114:117], v[170:173], v[186:189], v[114:117]
	v_mfma_f32_16x16x32_bf16 v[106:109], v[178:181], v[186:189], v[106:109]
	v_mfma_f32_16x16x32_bf16 v[98:101], v[170:173], v[206:209], v[98:101]
	v_mfma_f32_16x16x32_bf16 v[90:93], v[178:181], v[206:209], v[90:93]
	v_mfma_f32_16x16x32_bf16 v[82:85], v[170:173], v[214:217], v[82:85]
	v_mfma_f32_16x16x32_bf16 v[74:77], v[178:181], v[214:217], v[74:77]
	v_mfma_f32_16x16x32_bf16 v[70:73], v[170:173], v[222:225], v[70:73]
	s_barrier
	v_mfma_f32_16x16x32_bf16 v[66:69], v[178:181], v[222:225], v[66:69]
	s_setprio 0
	s_add_i32 s33, s64, s55
	v_lshl_add_u64 v[190:191], s[34:35], 0, v[132:133]
	s_mov_b32 m0, s33
	ds_read_b128 v[182:185], v148 offset:16384
	ds_read_b128 v[186:189], v148 offset:17408
	ds_read_b128 v[194:197], v148 offset:18432
	ds_read_b128 v[206:209], v148 offset:19456
	ds_read_b128 v[210:213], v148 offset:20480
	ds_read_b128 v[214:217], v148 offset:21504
	ds_read_b128 v[218:221], v148 offset:22528
	ds_read_b128 v[222:225], v148 offset:23552
	global_load_lds_dwordx4 v[190:191], off
	s_add_i32 m0, s33, 0x2000
	s_add_u32 s66, s34, s54
	v_lshl_add_u64 v[190:191], s[34:35], 0, v[134:135]
	s_addc_u32 s67, s35, 0
	s_add_i32 s0, s0, s55
	global_load_lds_dwordx4 v[190:191], off
	v_lshl_add_u64 v[190:191], s[66:67], 0, v[132:133]
	s_mov_b32 m0, s0
	v_lshl_add_u64 v[236:237], s[44:45], 0, v[136:137]
	global_load_lds_dwordx4 v[190:191], off
	v_lshl_add_u64 v[190:191], s[66:67], 0, v[134:135]
	s_add_i32 m0, s0, 0x2000
	s_nop 0
	global_load_lds_dwordx4 v[190:191], off
	v_lshl_add_u64 v[190:191], s[44:45], 0, v[130:131]
	s_mov_b32 m0, s57
	s_nop 0
	global_load_lds_dwordx4 v[190:191], off
	s_mov_b32 m0, s60
	s_nop 0
	global_load_lds_dwordx4 v[236:237], off
	s_waitcnt vmcnt(8)
	s_waitcnt lgkmcnt(0)
	s_barrier
; #define PG8_STAGE(bufoff, gbase, voff) do { _Pragma("unroll") for (int _i = 0; _i < 2; ++_i) \
;         __builtin_amdgcn_global_load_lds((const unsigned*)((const char*)(gbase) + (voff)[_i]), (LAS unsigned*)(lds + (bufoff) + ldsw + _i * 8192), 16, 0, 0); } while (0)
; #define PG8_LDA(dst, b, h) do { _Pragma("unroll") for (int m = 0; m < 4; ++m) _Pragma("unroll") for (int k = 0; k < 2; ++k) dst[m][k] = *(const LAS bf16x8*)(lds + PG8_SA(b, h) + aoff + m * 2048 + k * 1024); } while (0)
; #define PG8_LDB(dst, b, h) do { _Pragma("unroll") for (int n = 0; n < 2; ++n) _Pragma("unroll") for (int k = 0; k < 2; ++k) dst[n][k] = *(const LAS bf16x8*)(lds + PG8_SB(b, h) + boff + n * 2048 + k * 1024); } while (0)
; #define PG8_MMA(ai, bj, At, Bt) do { __builtin_amdgcn_s_setprio(1); _Pragma("unroll") for (int m = 0; m < 4; ++m) _Pragma("unroll") for (int n = 0; n < 2; ++n) _Pragma("unroll") for (int k = 0; k < 2; ++k) \
;         acc[ai][bj][m][n] = __builtin_amdgcn_mfma_f32_16x16x32_bf16(Bt[n][k], At[m][k], acc[ai][bj][m][n], 0, 0, 0); __builtin_amdgcn_s_setprio(0); } while (0)
; #define PG8_WAIT_V(n) asm volatile("s_waitcnt vmcnt(" #n ")" ::: "memory")
; #define PG8_WAIT_L(n) asm volatile("s_waitcnt lgkmcnt(" #n ")" ::: "memory")
; #define PG8_BAR __builtin_amdgcn_s_barrier()
; #define PG8_SCHED __builtin_amdgcn_sched_barrier(0)
; template <class Epi, bool ALIGN_EPI = true, bool SP2 = true>
; __device__ __forceinline__ void gemm_phase(LAS unsigned char* lds, const Gemm g, const StaticOrder& S, const Epi& E, unsigned long long& tacc, const int tmode) {
;     ...
;             PG8_WAIT_V(8); PG8_WAIT_L(0); PG8_BAR; PG8_MMA(1, 0, At, B0); PG8_MMA(1, 1, At, B1); PG8_BAR; PG8_SCHED;
;             PG8_LDB(B0, 1, 0); PG8_LDB(B1, 1, 1); PG8_SCHED; PG8_LDA(At, 1, 0); PG8_STAGE(PG8_SA(0, 1), a2 + hstepA, voffA);
;             PG8_WAIT_V(8); PG8_WAIT_L(0); PG8_BAR; PG8_MMA(0, 0, At, B0); PG8_MMA(0, 1, At, B1); PG8_BAR; PG8_SCHED;
	s_setprio 1
	s_waitcnt lgkmcnt(0)
	v_mfma_f32_16x16x32_bf16 v[62:65], v[150:153], v[182:185], v[62:65]
	v_mfma_f32_16x16x32_bf16 v[58:61], v[158:161], v[182:185], v[58:61]
	v_mfma_f32_16x16x32_bf16 v[54:57], v[150:153], v[194:197], v[54:57]
	v_mfma_f32_16x16x32_bf16 v[46:49], v[158:161], v[194:197], v[46:49]
	v_mfma_f32_16x16x32_bf16 v[38:41], v[150:153], v[210:213], v[38:41]
	v_mfma_f32_16x16x32_bf16 v[30:33], v[158:161], v[210:213], v[30:33]
	v_mfma_f32_16x16x32_bf16 v[22:25], v[150:153], v[218:221], v[22:25]
	v_mfma_f32_16x16x32_bf16 v[14:17], v[158:161], v[218:221], v[14:17]
	v_mfma_f32_16x16x32_bf16 v[62:65], v[154:157], v[186:189], v[62:65]
	v_mfma_f32_16x16x32_bf16 v[58:61], v[162:165], v[186:189], v[58:61]
	v_mfma_f32_16x16x32_bf16 v[54:57], v[154:157], v[206:209], v[54:57]
	v_mfma_f32_16x16x32_bf16 v[46:49], v[162:165], v[206:209], v[46:49]
	v_mfma_f32_16x16x32_bf16 v[38:41], v[154:157], v[214:217], v[38:41]
	v_mfma_f32_16x16x32_bf16 v[30:33], v[162:165], v[214:217], v[30:33]
	v_mfma_f32_16x16x32_bf16 v[22:25], v[154:157], v[222:225], v[22:25]
	v_mfma_f32_16x16x32_bf16 v[14:17], v[162:165], v[222:225], v[14:17]
	s_setprio 0
	s_setprio 1
	v_mfma_f32_16x16x32_bf16 v[50:53], v[166:169], v[182:185], v[50:53]
	v_mfma_f32_16x16x32_bf16 v[42:45], v[174:177], v[182:185], v[42:45]
	v_mfma_f32_16x16x32_bf16 v[34:37], v[166:169], v[194:197], v[34:37]
	v_mfma_f32_16x16x32_bf16 v[26:29], v[174:177], v[194:197], v[26:29]
	v_mfma_f32_16x16x32_bf16 v[18:21], v[166:169], v[210:213], v[18:21]
	v_mfma_f32_16x16x32_bf16 v[10:13], v[174:177], v[210:213], v[10:13]
	v_mfma_f32_16x16x32_bf16 v[6:9], v[166:169], v[218:221], v[6:9]
	v_mfma_f32_16x16x32_bf16 v[2:5], v[174:177], v[218:221], v[2:5]
	v_mfma_f32_16x16x32_bf16 v[50:53], v[170:173], v[186:189], v[50:53]
	v_mfma_f32_16x16x32_bf16 v[42:45], v[178:181], v[186:189], v[42:45]
	v_mfma_f32_16x16x32_bf16 v[34:37], v[170:173], v[206:209], v[34:37]
	v_mfma_f32_16x16x32_bf16 v[26:29], v[178:181], v[206:209], v[26:29]
	v_mfma_f32_16x16x32_bf16 v[18:21], v[170:173], v[214:217], v[18:21]
	v_mfma_f32_16x16x32_bf16 v[10:13], v[178:181], v[214:217], v[10:13]
	v_mfma_f32_16x16x32_bf16 v[6:9], v[170:173], v[222:225], v[6:9]
	s_barrier
	v_mfma_f32_16x16x32_bf16 v[2:5], v[178:181], v[222:225], v[2:5]
	s_setprio 0
	s_add_i32 s0, 0, 0x18000
	v_add_u32_e32 v149, s0, v147
	s_add_i32 s33, 0, 0x1c000
	ds_read_b128 v[150:153], v149
	ds_read_b128 v[154:157], v149 offset:1024
	ds_read_b128 v[158:161], v149 offset:2048
	ds_read_b128 v[162:165], v149 offset:3072
	v_add_u32_e32 v149, s33, v147
	ds_read_b128 v[166:169], v149
	ds_read_b128 v[170:173], v149 offset:1024
	ds_read_b128 v[174:177], v149 offset:2048
	ds_read_b128 v[178:181], v149 offset:3072
	s_add_u32 s44, s44, s51
	s_addc_u32 s45, s45, 0
	s_mov_b32 m0, s61
	v_lshl_add_u64 v[238:239], s[44:45], 0, v[130:131]
	ds_read_b128 v[182:185], v148 offset:32768
	ds_read_b128 v[186:189], v148 offset:33792
	ds_read_b128 v[194:197], v148 offset:34816
	ds_read_b128 v[206:209], v148 offset:35840
	ds_read_b128 v[210:213], v148 offset:36864
	ds_read_b128 v[214:217], v148 offset:37888
	ds_read_b128 v[218:221], v148 offset:38912
	ds_read_b128 v[222:225], v148 offset:39936
	global_load_lds_dwordx4 v[238:239], off
	v_lshl_add_u64 v[238:239], s[44:45], 0, v[136:137]
	s_mov_b32 m0, s65
	s_nop 0
	global_load_lds_dwordx4 v[238:239], off
	s_waitcnt vmcnt(8)
	s_waitcnt lgkmcnt(0)
	s_barrier
	s_setprio 1
	s_waitcnt lgkmcnt(0)
	v_mfma_f32_16x16x32_bf16 v[126:129], v[150:153], v[182:185], v[126:129]
	v_mfma_f32_16x16x32_bf16 v[122:125], v[158:161], v[182:185], v[122:125]
	v_mfma_f32_16x16x32_bf16 v[118:121], v[150:153], v[194:197], v[118:121]
	v_mfma_f32_16x16x32_bf16 v[110:113], v[158:161], v[194:197], v[110:113]
	v_mfma_f32_16x16x32_bf16 v[102:105], v[150:153], v[210:213], v[102:105]
	v_mfma_f32_16x16x32_bf16 v[94:97], v[158:161], v[210:213], v[94:97]
	v_mfma_f32_16x16x32_bf16 v[86:89], v[150:153], v[218:221], v[86:89]
	v_mfma_f32_16x16x32_bf16 v[78:81], v[158:161], v[218:221], v[78:81]
	v_mfma_f32_16x16x32_bf16 v[126:129], v[154:157], v[186:189], v[126:129]
	v_mfma_f32_16x16x32_bf16 v[122:125], v[162:165], v[186:189], v[122:125]
	v_mfma_f32_16x16x32_bf16 v[118:121], v[154:157], v[206:209], v[118:121]
	v_mfma_f32_16x16x32_bf16 v[110:113], v[162:165], v[206:209], v[110:113]
	v_mfma_f32_16x16x32_bf16 v[102:105], v[154:157], v[214:217], v[102:105]
	v_mfma_f32_16x16x32_bf16 v[94:97], v[162:165], v[214:217], v[94:97]
	v_mfma_f32_16x16x32_bf16 v[86:89], v[154:157], v[222:225], v[86:89]
	v_mfma_f32_16x16x32_bf16 v[78:81], v[162:165], v[222:225], v[78:81]
	s_setprio 0
	s_setprio 1
	v_mfma_f32_16x16x32_bf16 v[114:117], v[166:169], v[182:185], v[114:117]
	v_mfma_f32_16x16x32_bf16 v[106:109], v[174:177], v[182:185], v[106:109]
	v_mfma_f32_16x16x32_bf16 v[98:101], v[166:169], v[194:197], v[98:101]
	v_mfma_f32_16x16x32_bf16 v[90:93], v[174:177], v[194:197], v[90:93]
	v_mfma_f32_16x16x32_bf16 v[82:85], v[166:169], v[210:213], v[82:85]
	v_mfma_f32_16x16x32_bf16 v[74:77], v[174:177], v[210:213], v[74:77]
	v_mfma_f32_16x16x32_bf16 v[70:73], v[166:169], v[218:221], v[70:73]
	v_mfma_f32_16x16x32_bf16 v[66:69], v[174:177], v[218:221], v[66:69]
	v_mfma_f32_16x16x32_bf16 v[114:117], v[170:173], v[186:189], v[114:117]
	v_mfma_f32_16x16x32_bf16 v[106:109], v[178:181], v[186:189], v[106:109]
	v_mfma_f32_16x16x32_bf16 v[98:101], v[170:173], v[206:209], v[98:101]
	v_mfma_f32_16x16x32_bf16 v[90:93], v[178:181], v[206:209], v[90:93]
	v_mfma_f32_16x16x32_bf16 v[82:85], v[170:173], v[214:217], v[82:85]
	v_mfma_f32_16x16x32_bf16 v[74:77], v[178:181], v[214:217], v[74:77]
	v_mfma_f32_16x16x32_bf16 v[70:73], v[170:173], v[222:225], v[70:73]
	s_barrier
; #define PG8_STAGE(bufoff, gbase, voff) do { _Pragma("unroll") for (int _i = 0; _i < 2; ++_i) \
;         __builtin_amdgcn_global_load_lds((const unsigned*)((const char*)(gbase) + (voff)[_i]), (LAS unsigned*)(lds + (bufoff) + ldsw + _i * 8192), 16, 0, 0); } while (0)
; #define PG8_LDA(dst, b, h) do { _Pragma("unroll") for (int m = 0; m < 4; ++m) _Pragma("unroll") for (int k = 0; k < 2; ++k) dst[m][k] = *(const LAS bf16x8*)(lds + PG8_SA(b, h) + aoff + m * 2048 + k * 1024); } while (0)
; #define PG8_MMA(ai, bj, At, Bt) do { __builtin_amdgcn_s_setprio(1); _Pragma("unroll") for (int m = 0; m < 4; ++m) _Pragma("unroll") for (int n = 0; n < 2; ++n) _Pragma("unroll") for (int k = 0; k < 2; ++k) \
;         acc[ai][bj][m][n] = __builtin_amdgcn_mfma_f32_16x16x32_bf16(Bt[n][k], At[m][k], acc[ai][bj][m][n], 0, 0, 0); __builtin_amdgcn_s_setprio(0); } while (0)
; #define PG8_WAIT_V(n) asm volatile("s_waitcnt vmcnt(" #n ")" ::: "memory")
; #define PG8_WAIT_L(n) asm volatile("s_waitcnt lgkmcnt(" #n ")" ::: "memory")
; #define PG8_BAR __builtin_amdgcn_s_barrier()
; #define PG8_SCHED __builtin_amdgcn_sched_barrier(0)
; template <class Epi, bool ALIGN_EPI = true, bool SP2 = true>
; __device__ __forceinline__ void gemm_phase(LAS unsigned char* lds, const Gemm g, const StaticOrder& S, const Epi& E, unsigned long long& tacc, const int tmode) {
;     ...
;             PG8_WAIT_V(8); PG8_WAIT_L(0); PG8_BAR; PG8_MMA(0, 0, At, B0); PG8_MMA(0, 1, At, B1); PG8_BAR; PG8_SCHED;
;             PG8_LDA(At, 1, 1); PG8_STAGE(PG8_SB(1, 0), b3, voffB); PG8_STAGE(PG8_SB(1, 1), b3 + hstepB, voffB); PG8_STAGE(PG8_SA(1, 0), a3, voffA);
;             PG8_WAIT_V(8); PG8_WAIT_L(0); PG8_BAR; PG8_MMA(1, 0, At, B0); PG8_MMA(1, 1, At, B1); PG8_BAR; PG8_SCHED;
	v_mfma_f32_16x16x32_bf16 v[66:69], v[178:181], v[222:225], v[66:69]
	s_setprio 0
	s_add_u32 s34, s34, 0x4000
	s_addc_u32 s35, s35, 0
	s_add_i32 s0, s0, s55
	v_lshl_add_u64 v[238:239], s[34:35], 0, v[132:133]
	s_mov_b32 m0, s0
	ds_read_b128 v[182:185], v148 offset:49152
	ds_read_b128 v[186:189], v148 offset:50176
	ds_read_b128 v[194:197], v148 offset:51200
	ds_read_b128 v[206:209], v148 offset:52224
	ds_read_b128 v[210:213], v148 offset:53248
	ds_read_b128 v[214:217], v148 offset:54272
	ds_read_b128 v[218:221], v148 offset:55296
	ds_read_b128 v[222:225], v148 offset:56320
	global_load_lds_dwordx4 v[238:239], off
	s_add_i32 m0, s0, 0x2000
	v_lshl_add_u64 v[238:239], s[34:35], 0, v[134:135]
	s_add_u32 s34, s34, s54
	s_addc_u32 s35, s35, 0
	s_add_i32 s0, s33, s55
	global_load_lds_dwordx4 v[238:239], off
	v_lshl_add_u64 v[238:239], s[34:35], 0, v[132:133]
	s_mov_b32 m0, s0
	v_lshl_add_u64 v[190:191], v[190:191], 0, s[4:5]
	global_load_lds_dwordx4 v[238:239], off
	v_lshl_add_u64 v[238:239], s[34:35], 0, v[134:135]
	s_add_i32 m0, s0, 0x2000
	s_nop 0
	global_load_lds_dwordx4 v[238:239], off
	s_mov_b32 m0, s72
	s_nop 0
	global_load_lds_dwordx4 v[190:191], off
	v_lshl_add_u64 v[190:191], v[236:237], 0, s[4:5]
	s_mov_b32 m0, s73
	s_nop 0
	global_load_lds_dwordx4 v[190:191], off
	s_waitcnt vmcnt(8)
	s_waitcnt lgkmcnt(0)
	s_barrier
	s_setprio 1
	s_waitcnt lgkmcnt(0)
	v_mfma_f32_16x16x32_bf16 v[62:65], v[150:153], v[182:185], v[62:65]
	v_mfma_f32_16x16x32_bf16 v[58:61], v[158:161], v[182:185], v[58:61]
	v_mfma_f32_16x16x32_bf16 v[54:57], v[150:153], v[194:197], v[54:57]
	v_mfma_f32_16x16x32_bf16 v[46:49], v[158:161], v[194:197], v[46:49]
	v_mfma_f32_16x16x32_bf16 v[38:41], v[150:153], v[210:213], v[38:41]
	v_mfma_f32_16x16x32_bf16 v[30:33], v[158:161], v[210:213], v[30:33]
	v_mfma_f32_16x16x32_bf16 v[22:25], v[150:153], v[218:221], v[22:25]
	v_mfma_f32_16x16x32_bf16 v[14:17], v[158:161], v[218:221], v[14:17]
	v_mfma_f32_16x16x32_bf16 v[62:65], v[154:157], v[186:189], v[62:65]
	v_mfma_f32_16x16x32_bf16 v[58:61], v[162:165], v[186:189], v[58:61]
	v_mfma_f32_16x16x32_bf16 v[54:57], v[154:157], v[206:209], v[54:57]
	v_mfma_f32_16x16x32_bf16 v[46:49], v[162:165], v[206:209], v[46:49]
	v_mfma_f32_16x16x32_bf16 v[38:41], v[154:157], v[214:217], v[38:41]
	v_mfma_f32_16x16x32_bf16 v[30:33], v[162:165], v[214:217], v[30:33]
	v_mfma_f32_16x16x32_bf16 v[22:25], v[154:157], v[222:225], v[22:25]
	v_mfma_f32_16x16x32_bf16 v[14:17], v[162:165], v[222:225], v[14:17]
	s_setprio 0
	s_setprio 1
	v_mfma_f32_16x16x32_bf16 v[50:53], v[166:169], v[182:185], v[50:53]
	v_mfma_f32_16x16x32_bf16 v[42:45], v[174:177], v[182:185], v[42:45]
	v_mfma_f32_16x16x32_bf16 v[34:37], v[166:169], v[194:197], v[34:37]
	v_mfma_f32_16x16x32_bf16 v[26:29], v[174:177], v[194:197], v[26:29]
	v_mfma_f32_16x16x32_bf16 v[18:21], v[166:169], v[210:213], v[18:21]
	v_mfma_f32_16x16x32_bf16 v[10:13], v[174:177], v[210:213], v[10:13]
	v_mfma_f32_16x16x32_bf16 v[6:9], v[166:169], v[218:221], v[6:9]
	v_mfma_f32_16x16x32_bf16 v[2:5], v[174:177], v[218:221], v[2:5]
	v_mfma_f32_16x16x32_bf16 v[50:53], v[170:173], v[186:189], v[50:53]
	v_mfma_f32_16x16x32_bf16 v[42:45], v[178:181], v[186:189], v[42:45]
	v_mfma_f32_16x16x32_bf16 v[34:37], v[170:173], v[206:209], v[34:37]
	v_mfma_f32_16x16x32_bf16 v[26:29], v[178:181], v[206:209], v[26:29]
	v_mfma_f32_16x16x32_bf16 v[18:21], v[170:173], v[214:217], v[18:21]
	v_mfma_f32_16x16x32_bf16 v[10:13], v[178:181], v[214:217], v[10:13]
	v_mfma_f32_16x16x32_bf16 v[6:9], v[170:173], v[222:225], v[6:9]
	s_barrier
	v_mfma_f32_16x16x32_bf16 v[2:5], v[178:181], v[222:225], v[2:5]
	s_setprio 0
	s_add_u32 s37, s37, 0x8000
	s_addc_u32 vcc_lo, vcc_lo, 0
	s_add_u32 s42, s42, 0x100
	s_addc_u32 s43, s43, 0
	v_lshl_add_u64 v[144:145], v[144:145], 0, s[58:59]
	v_lshl_add_u64 v[142:143], v[142:143], 0, s[58:59]
	s_cmp_lt_u32 s1, s50
	s_mov_b32 s0, s1
	s_cbranch_scc1 .LBB0_1045
	s_andn2_b64 vcc, exec, s[28:29]
	s_cbranch_vccnz .LBB0_1048
	s_barrier

; #define PG8_STAGE(bufoff, gbase, voff) do { _Pragma("unroll") for (int _i = 0; _i < 2; ++_i) \
;         __builtin_amdgcn_global_load_lds((const unsigned*)((const char*)(gbase) + (voff)[_i]), (LAS unsigned*)(lds + (bufoff) + ldsw + _i * 8192), 16, 0, 0); } while (0)
; #define PG8_LDA(dst, b, h) do { _Pragma("unroll") for (int m = 0; m < 4; ++m) _Pragma("unroll") for (int k = 0; k < 2; ++k) dst[m][k] = *(const LAS bf16x8*)(lds + PG8_SA(b, h) + aoff + m * 2048 + k * 1024); } while (0)
; #define PG8_LDB(dst, b, h) do { _Pragma("unroll") for (int n = 0; n < 2; ++n) _Pragma("unroll") for (int k = 0; k < 2; ++k) dst[n][k] = *(const LAS bf16x8*)(lds + PG8_SB(b, h) + boff + n * 2048 + k * 1024); } while (0)
; #define PG8_MMA(ai, bj, At, Bt) do { __builtin_amdgcn_s_setprio(1); _Pragma("unroll") for (int m = 0; m < 4; ++m) _Pragma("unroll") for (int n = 0; n < 2; ++n) _Pragma("unroll") for (int k = 0; k < 2; ++k) \
;         acc[ai][bj][m][n] = __builtin_amdgcn_mfma_f32_16x16x32_bf16(Bt[n][k], At[m][k], acc[ai][bj][m][n], 0, 0, 0); __builtin_amdgcn_s_setprio(0); } while (0)
; #define PG8_WAIT_V(n) asm volatile("s_waitcnt vmcnt(" #n ")" ::: "memory")
; #define PG8_WAIT_L(n) asm volatile("s_waitcnt lgkmcnt(" #n ")" ::: "memory")
; #define PG8_BAR __builtin_amdgcn_s_barrier()
; #define PG8_SCHED __builtin_amdgcn_sched_barrier(0)
; template <class Epi, bool ALIGN_EPI = true, bool SP2 = true>
; __device__ __forceinline__ void gemm_phase(LAS unsigned char* lds, const Gemm g, const StaticOrder& S, const Epi& E, unsigned long long& tacc, const int tmode) {
;     ...
;             const bool last = (t == nt - 2);
;             const char* a1 = cA + (size_t)(t + 1) * kstepA;
;             const char* a2 = last ? nA : cA + (size_t)(t + 2) * kstepA; const char* b2 = last ? nB : cB + (size_t)(t + 2) * kstepB;
;             const char* a3 = a2 + kstepA; const char* b3 = b2 + kstepB;
;             if constexpr (SP2) {
;             PG8_LDB(B0, 0, 0); PG8_LDB(B1, 0, 1); PG8_SCHED; PG8_LDA(At, 0, 0); PG8_STAGE(PG8_SA(1, 1), a1 + hstepA, voffA);
;             PG8_WAIT_V(8); PG8_WAIT_L(0); PG8_BAR; PG8_MMA(0, 0, At, B0); PG8_MMA(0, 1, At, B1); PG8_BAR; PG8_SCHED;
;             PG8_LDA(At, 0, 1); PG8_STAGE(PG8_SB(0, 0), b2, voffB); PG8_STAGE(PG8_SB(0, 1), b2 + hstepB, voffB); PG8_STAGE(PG8_SA(0, 0), a2, voffA);
.LBB0_1154:
	s_add_u32 s0, s22, 0xfff84000
	s_addc_u32 s1, s23, -1
	s_cmp_eq_u32 s61, 28
	s_cselect_b32 s34, s55, s0
	s_cselect_b32 s35, s25, s1
	s_cselect_b32 s40, s56, s57
	s_cselect_b32 s41, s21, s60
	s_add_u32 s30, s34, 0x4000
	s_addc_u32 s31, s35, 0
	s_add_i32 s0, 0, 0x10000
	v_add_u32_e32 v130, s0, v137
	s_add_i32 s33, 0, 0x14000
	ds_read_b128 v[140:143], v130
	ds_read_b128 v[144:147], v130 offset:1024
	ds_read_b128 v[148:151], v130 offset:2048
	ds_read_b128 v[152:155], v130 offset:3072
	v_add_u32_e32 v130, s33, v137
	ds_read_b128 v[156:159], v130
	ds_read_b128 v[160:163], v130 offset:1024
	ds_read_b128 v[164:167], v130 offset:2048
	ds_read_b128 v[168:171], v130 offset:3072
	v_lshl_add_u64 v[214:215], s[22:23], 0, v[132:133]
	s_add_i32 m0, s44, 0xc000
	ds_read_b128 v[172:175], v138
	ds_read_b128 v[176:179], v138 offset:1024
	ds_read_b128 v[180:183], v138 offset:2048
	ds_read_b128 v[184:187], v138 offset:3072
	ds_read_b128 v[188:191], v138 offset:4096
	ds_read_b128 v[194:197], v138 offset:5120
	ds_read_b128 v[206:209], v138 offset:6144
	ds_read_b128 v[210:213], v138 offset:7168
	global_load_lds_dwordx4 v[214:215], off
	v_lshl_add_u64 v[214:215], s[22:23], 0, v[134:135]
	s_add_i32 m0, s44, 0xe000
	s_nop 0
	global_load_lds_dwordx4 v[214:215], off
	s_waitcnt vmcnt(8)
	s_waitcnt lgkmcnt(0)
	s_barrier
	s_setprio 1
	s_waitcnt lgkmcnt(0)
	v_mfma_f32_16x16x32_bf16 v[126:129], v[140:143], v[172:175], v[126:129]
	v_mfma_f32_16x16x32_bf16 v[122:125], v[148:151], v[172:175], v[122:125]
	v_mfma_f32_16x16x32_bf16 v[110:113], v[140:143], v[180:183], v[110:113]
	v_mfma_f32_16x16x32_bf16 v[106:109], v[148:151], v[180:183], v[106:109]
	v_mfma_f32_16x16x32_bf16 v[94:97], v[140:143], v[188:191], v[94:97]
	v_mfma_f32_16x16x32_bf16 v[90:93], v[148:151], v[188:191], v[90:93]
	v_mfma_f32_16x16x32_bf16 v[78:81], v[140:143], v[206:209], v[78:81]
	v_mfma_f32_16x16x32_bf16 v[74:77], v[148:151], v[206:209], v[74:77]
	v_mfma_f32_16x16x32_bf16 v[126:129], v[144:147], v[176:179], v[126:129]
	v_mfma_f32_16x16x32_bf16 v[122:125], v[152:155], v[176:179], v[122:125]
	v_mfma_f32_16x16x32_bf16 v[110:113], v[144:147], v[184:187], v[110:113]
	v_mfma_f32_16x16x32_bf16 v[106:109], v[152:155], v[184:187], v[106:109]
	v_mfma_f32_16x16x32_bf16 v[94:97], v[144:147], v[194:197], v[94:97]
	v_mfma_f32_16x16x32_bf16 v[90:93], v[152:155], v[194:197], v[90:93]
	v_mfma_f32_16x16x32_bf16 v[78:81], v[144:147], v[210:213], v[78:81]
	v_mfma_f32_16x16x32_bf16 v[74:77], v[152:155], v[210:213], v[74:77]
	s_setprio 0
	s_setprio 1
	v_mfma_f32_16x16x32_bf16 v[118:121], v[156:159], v[172:175], v[118:121]
	v_mfma_f32_16x16x32_bf16 v[114:117], v[164:167], v[172:175], v[114:117]
	v_mfma_f32_16x16x32_bf16 v[102:105], v[156:159], v[180:183], v[102:105]
	v_mfma_f32_16x16x32_bf16 v[98:101], v[164:167], v[180:183], v[98:101]
	v_mfma_f32_16x16x32_bf16 v[86:89], v[156:159], v[188:191], v[86:89]
	v_mfma_f32_16x16x32_bf16 v[82:85], v[164:167], v[188:191], v[82:85]
	v_mfma_f32_16x16x32_bf16 v[70:73], v[156:159], v[206:209], v[70:73]
	v_mfma_f32_16x16x32_bf16 v[66:69], v[164:167], v[206:209], v[66:69]
	v_mfma_f32_16x16x32_bf16 v[118:121], v[160:163], v[176:179], v[118:121]
	v_mfma_f32_16x16x32_bf16 v[114:117], v[168:171], v[176:179], v[114:117]
	v_mfma_f32_16x16x32_bf16 v[102:105], v[160:163], v[184:187], v[102:105]
	v_mfma_f32_16x16x32_bf16 v[98:101], v[168:171], v[184:187], v[98:101]
	v_mfma_f32_16x16x32_bf16 v[86:89], v[160:163], v[194:197], v[86:89]
	v_mfma_f32_16x16x32_bf16 v[82:85], v[168:171], v[194:197], v[82:85]
	v_mfma_f32_16x16x32_bf16 v[70:73], v[160:163], v[210:213], v[70:73]
	s_barrier
	v_mfma_f32_16x16x32_bf16 v[66:69], v[168:171], v[210:213], v[66:69]
	s_setprio 0
	s_add_i32 s0, s0, s43
	v_lshl_add_u64 v[214:215], s[40:41], 0, v[132:133]
	s_mov_b32 m0, s0
	ds_read_b128 v[172:175], v138 offset:16384
	ds_read_b128 v[176:179], v138 offset:17408
	ds_read_b128 v[180:183], v138 offset:18432
	ds_read_b128 v[184:187], v138 offset:19456
	ds_read_b128 v[188:191], v138 offset:20480
	ds_read_b128 v[194:197], v138 offset:21504
	ds_read_b128 v[206:209], v138 offset:22528
	ds_read_b128 v[210:213], v138 offset:23552
	global_load_lds_dwordx4 v[214:215], off
	s_add_i32 m0, s0, 0x2000
	s_add_u32 s0, s40, 0x80000
	v_lshl_add_u64 v[214:215], s[40:41], 0, v[134:135]
	s_addc_u32 s1, s41, 0
	s_add_i32 s33, s33, s43
	global_load_lds_dwordx4 v[214:215], off
	v_lshl_add_u64 v[214:215], s[0:1], 0, v[132:133]
	s_mov_b32 m0, s33
	s_nop 0
	global_load_lds_dwordx4 v[214:215], off
	v_lshl_add_u64 v[214:215], s[0:1], 0, v[134:135]
	s_add_i32 m0, s33, 0x2000
	s_nop 0
	global_load_lds_dwordx4 v[214:215], off
	v_lshl_add_u64 v[214:215], s[34:35], 0, v[132:133]
	s_mov_b32 m0, s44
	s_nop 0
	global_load_lds_dwordx4 v[214:215], off
	v_lshl_add_u64 v[214:215], s[34:35], 0, v[134:135]
	s_mov_b32 m0, s45
	s_nop 0
	global_load_lds_dwordx4 v[214:215], off
	s_waitcnt vmcnt(8)
	s_waitcnt lgkmcnt(0)
	s_barrier
; #define PG8_STAGE(bufoff, gbase, voff) do { _Pragma("unroll") for (int _i = 0; _i < 2; ++_i) \
;         __builtin_amdgcn_global_load_lds((const unsigned*)((const char*)(gbase) + (voff)[_i]), (LAS unsigned*)(lds + (bufoff) + ldsw + _i * 8192), 16, 0, 0); } while (0)
; #define PG8_LDA(dst, b, h) do { _Pragma("unroll") for (int m = 0; m < 4; ++m) _Pragma("unroll") for (int k = 0; k < 2; ++k) dst[m][k] = *(const LAS bf16x8*)(lds + PG8_SA(b, h) + aoff + m * 2048 + k * 1024); } while (0)
; #define PG8_LDB(dst, b, h) do { _Pragma("unroll") for (int n = 0; n < 2; ++n) _Pragma("unroll") for (int k = 0; k < 2; ++k) dst[n][k] = *(const LAS bf16x8*)(lds + PG8_SB(b, h) + boff + n * 2048 + k * 1024); } while (0)
; #define PG8_MMA(ai, bj, At, Bt) do { __builtin_amdgcn_s_setprio(1); _Pragma("unroll") for (int m = 0; m < 4; ++m) _Pragma("unroll") for (int n = 0; n < 2; ++n) _Pragma("unroll") for (int k = 0; k < 2; ++k) \
;         acc[ai][bj][m][n] = __builtin_amdgcn_mfma_f32_16x16x32_bf16(Bt[n][k], At[m][k], acc[ai][bj][m][n], 0, 0, 0); __builtin_amdgcn_s_setprio(0); } while (0)
; #define PG8_WAIT_V(n) asm volatile("s_waitcnt vmcnt(" #n ")" ::: "memory")
; #define PG8_WAIT_L(n) asm volatile("s_waitcnt lgkmcnt(" #n ")" ::: "memory")
; #define PG8_BAR __builtin_amdgcn_s_barrier()
; #define PG8_SCHED __builtin_amdgcn_sched_barrier(0)
; template <class Epi, bool ALIGN_EPI = true, bool SP2 = true>
; __device__ __forceinline__ void gemm_phase(LAS unsigned char* lds, const Gemm g, const StaticOrder& S, const Epi& E, unsigned long long& tacc, const int tmode) {
;     ...
;             PG8_WAIT_V(8); PG8_WAIT_L(0); PG8_BAR; PG8_MMA(1, 0, At, B0); PG8_MMA(1, 1, At, B1); PG8_BAR; PG8_SCHED;
;             PG8_LDB(B0, 1, 0); PG8_LDB(B1, 1, 1); PG8_SCHED; PG8_LDA(At, 1, 0); PG8_STAGE(PG8_SA(0, 1), a2 + hstepA, voffA);
;             PG8_WAIT_V(8); PG8_WAIT_L(0); PG8_BAR; PG8_MMA(0, 0, At, B0); PG8_MMA(0, 1, At, B1); PG8_BAR; PG8_SCHED;
	s_setprio 1
	s_waitcnt lgkmcnt(0)
	v_mfma_f32_16x16x32_bf16 v[62:65], v[140:143], v[172:175], v[62:65]
	v_mfma_f32_16x16x32_bf16 v[58:61], v[148:151], v[172:175], v[58:61]
	v_mfma_f32_16x16x32_bf16 v[46:49], v[140:143], v[180:183], v[46:49]
	v_mfma_f32_16x16x32_bf16 v[42:45], v[148:151], v[180:183], v[42:45]
	v_mfma_f32_16x16x32_bf16 v[30:33], v[140:143], v[188:191], v[30:33]
	v_mfma_f32_16x16x32_bf16 v[26:29], v[148:151], v[188:191], v[26:29]
	v_mfma_f32_16x16x32_bf16 v[14:17], v[140:143], v[206:209], v[14:17]
	v_mfma_f32_16x16x32_bf16 v[10:13], v[148:151], v[206:209], v[10:13]
	v_mfma_f32_16x16x32_bf16 v[62:65], v[144:147], v[176:179], v[62:65]
	v_mfma_f32_16x16x32_bf16 v[58:61], v[152:155], v[176:179], v[58:61]
	v_mfma_f32_16x16x32_bf16 v[46:49], v[144:147], v[184:187], v[46:49]
	v_mfma_f32_16x16x32_bf16 v[42:45], v[152:155], v[184:187], v[42:45]
	v_mfma_f32_16x16x32_bf16 v[30:33], v[144:147], v[194:197], v[30:33]
	v_mfma_f32_16x16x32_bf16 v[26:29], v[152:155], v[194:197], v[26:29]
	v_mfma_f32_16x16x32_bf16 v[14:17], v[144:147], v[210:213], v[14:17]
	v_mfma_f32_16x16x32_bf16 v[10:13], v[152:155], v[210:213], v[10:13]
	s_setprio 0
	s_setprio 1
	v_mfma_f32_16x16x32_bf16 v[54:57], v[156:159], v[172:175], v[54:57]
	v_mfma_f32_16x16x32_bf16 v[50:53], v[164:167], v[172:175], v[50:53]
	v_mfma_f32_16x16x32_bf16 v[38:41], v[156:159], v[180:183], v[38:41]
	v_mfma_f32_16x16x32_bf16 v[34:37], v[164:167], v[180:183], v[34:37]
	v_mfma_f32_16x16x32_bf16 v[22:25], v[156:159], v[188:191], v[22:25]
	v_mfma_f32_16x16x32_bf16 v[18:21], v[164:167], v[188:191], v[18:21]
	v_mfma_f32_16x16x32_bf16 v[6:9], v[156:159], v[206:209], v[6:9]
	v_mfma_f32_16x16x32_bf16 v[2:5], v[164:167], v[206:209], v[2:5]
	v_mfma_f32_16x16x32_bf16 v[54:57], v[160:163], v[176:179], v[54:57]
	v_mfma_f32_16x16x32_bf16 v[50:53], v[168:171], v[176:179], v[50:53]
	v_mfma_f32_16x16x32_bf16 v[38:41], v[160:163], v[184:187], v[38:41]
	v_mfma_f32_16x16x32_bf16 v[34:37], v[168:171], v[184:187], v[34:37]
	v_mfma_f32_16x16x32_bf16 v[22:25], v[160:163], v[194:197], v[22:25]
	v_mfma_f32_16x16x32_bf16 v[18:21], v[168:171], v[194:197], v[18:21]
	v_mfma_f32_16x16x32_bf16 v[6:9], v[160:163], v[210:213], v[6:9]
	s_barrier
	v_mfma_f32_16x16x32_bf16 v[2:5], v[168:171], v[210:213], v[2:5]
	s_setprio 0
	s_add_i32 s33, 0, 0x18000
	v_add_u32_e32 v130, s33, v137
	s_add_i32 s64, 0, 0x1c000
	ds_read_b128 v[140:143], v130
	ds_read_b128 v[144:147], v130 offset:1024
	ds_read_b128 v[148:151], v130 offset:2048
	ds_read_b128 v[152:155], v130 offset:3072
	v_add_u32_e32 v130, s64, v137
	ds_read_b128 v[156:159], v130
	ds_read_b128 v[160:163], v130 offset:1024
	ds_read_b128 v[164:167], v130 offset:2048
	ds_read_b128 v[168:171], v130 offset:3072
	s_add_u32 s0, s34, 0x80000
	s_addc_u32 s1, s35, 0
	s_mov_b32 m0, s46
	v_lshl_add_u64 v[214:215], s[0:1], 0, v[132:133]
	ds_read_b128 v[172:175], v138 offset:32768
	ds_read_b128 v[176:179], v138 offset:33792
	ds_read_b128 v[180:183], v138 offset:34816
	ds_read_b128 v[184:187], v138 offset:35840
	ds_read_b128 v[188:191], v138 offset:36864
	ds_read_b128 v[194:197], v138 offset:37888
	ds_read_b128 v[206:209], v138 offset:38912
	ds_read_b128 v[210:213], v138 offset:39936
	global_load_lds_dwordx4 v[214:215], off
	v_lshl_add_u64 v[214:215], s[0:1], 0, v[134:135]
	s_mov_b32 m0, s47
	s_nop 0
	global_load_lds_dwordx4 v[214:215], off
	s_waitcnt vmcnt(8)
	s_waitcnt lgkmcnt(0)
	s_barrier
	s_setprio 1
	s_waitcnt lgkmcnt(0)
	v_mfma_f32_16x16x32_bf16 v[126:129], v[140:143], v[172:175], v[126:129]
	v_mfma_f32_16x16x32_bf16 v[122:125], v[148:151], v[172:175], v[122:125]
	v_mfma_f32_16x16x32_bf16 v[110:113], v[140:143], v[180:183], v[110:113]
	v_mfma_f32_16x16x32_bf16 v[106:109], v[148:151], v[180:183], v[106:109]
	v_mfma_f32_16x16x32_bf16 v[94:97], v[140:143], v[188:191], v[94:97]
	v_mfma_f32_16x16x32_bf16 v[90:93], v[148:151], v[188:191], v[90:93]
	v_mfma_f32_16x16x32_bf16 v[78:81], v[140:143], v[206:209], v[78:81]
	v_mfma_f32_16x16x32_bf16 v[74:77], v[148:151], v[206:209], v[74:77]
	v_mfma_f32_16x16x32_bf16 v[126:129], v[144:147], v[176:179], v[126:129]
	v_mfma_f32_16x16x32_bf16 v[122:125], v[152:155], v[176:179], v[122:125]
	v_mfma_f32_16x16x32_bf16 v[110:113], v[144:147], v[184:187], v[110:113]
	v_mfma_f32_16x16x32_bf16 v[106:109], v[152:155], v[184:187], v[106:109]
	v_mfma_f32_16x16x32_bf16 v[94:97], v[144:147], v[194:197], v[94:97]
	v_mfma_f32_16x16x32_bf16 v[90:93], v[152:155], v[194:197], v[90:93]
	v_mfma_f32_16x16x32_bf16 v[78:81], v[144:147], v[210:213], v[78:81]
	v_mfma_f32_16x16x32_bf16 v[74:77], v[152:155], v[210:213], v[74:77]
	s_setprio 0
	s_setprio 1
	v_mfma_f32_16x16x32_bf16 v[118:121], v[156:159], v[172:175], v[118:121]
	v_mfma_f32_16x16x32_bf16 v[114:117], v[164:167], v[172:175], v[114:117]
	v_mfma_f32_16x16x32_bf16 v[102:105], v[156:159], v[180:183], v[102:105]
	v_mfma_f32_16x16x32_bf16 v[98:101], v[164:167], v[180:183], v[98:101]
	v_mfma_f32_16x16x32_bf16 v[86:89], v[156:159], v[188:191], v[86:89]
	v_mfma_f32_16x16x32_bf16 v[82:85], v[164:167], v[188:191], v[82:85]
	v_mfma_f32_16x16x32_bf16 v[70:73], v[156:159], v[206:209], v[70:73]
	v_mfma_f32_16x16x32_bf16 v[66:69], v[164:167], v[206:209], v[66:69]
	v_mfma_f32_16x16x32_bf16 v[118:121], v[160:163], v[176:179], v[118:121]
	v_mfma_f32_16x16x32_bf16 v[114:117], v[168:171], v[176:179], v[114:117]
	v_mfma_f32_16x16x32_bf16 v[102:105], v[160:163], v[184:187], v[102:105]
	v_mfma_f32_16x16x32_bf16 v[98:101], v[168:171], v[184:187], v[98:101]
	v_mfma_f32_16x16x32_bf16 v[86:89], v[160:163], v[194:197], v[86:89]
	v_mfma_f32_16x16x32_bf16 v[82:85], v[168:171], v[194:197], v[82:85]
	v_mfma_f32_16x16x32_bf16 v[70:73], v[160:163], v[210:213], v[70:73]
	s_barrier
; #define PG8_STAGE(bufoff, gbase, voff) do { _Pragma("unroll") for (int _i = 0; _i < 2; ++_i) \
;         __builtin_amdgcn_global_load_lds((const unsigned*)((const char*)(gbase) + (voff)[_i]), (LAS unsigned*)(lds + (bufoff) + ldsw + _i * 8192), 16, 0, 0); } while (0)
; #define PG8_LDA(dst, b, h) do { _Pragma("unroll") for (int m = 0; m < 4; ++m) _Pragma("unroll") for (int k = 0; k < 2; ++k) dst[m][k] = *(const LAS bf16x8*)(lds + PG8_SA(b, h) + aoff + m * 2048 + k * 1024); } while (0)
; #define PG8_MMA(ai, bj, At, Bt) do { __builtin_amdgcn_s_setprio(1); _Pragma("unroll") for (int m = 0; m < 4; ++m) _Pragma("unroll") for (int n = 0; n < 2; ++n) _Pragma("unroll") for (int k = 0; k < 2; ++k) \
;         acc[ai][bj][m][n] = __builtin_amdgcn_mfma_f32_16x16x32_bf16(Bt[n][k], At[m][k], acc[ai][bj][m][n], 0, 0, 0); __builtin_amdgcn_s_setprio(0); } while (0)
; #define PG8_WAIT_V(n) asm volatile("s_waitcnt vmcnt(" #n ")" ::: "memory")
; #define PG8_WAIT_L(n) asm volatile("s_waitcnt lgkmcnt(" #n ")" ::: "memory")
; #define PG8_BAR __builtin_amdgcn_s_barrier()
; #define PG8_SCHED __builtin_amdgcn_sched_barrier(0)
; template <class Epi, bool ALIGN_EPI = true, bool SP2 = true>
; __device__ __forceinline__ void gemm_phase(LAS unsigned char* lds, const Gemm g, const StaticOrder& S, const Epi& E, unsigned long long& tacc, const int tmode) {
;     ...
;             PG8_WAIT_V(8); PG8_WAIT_L(0); PG8_BAR; PG8_MMA(0, 0, At, B0); PG8_MMA(0, 1, At, B1); PG8_BAR; PG8_SCHED;
;             PG8_LDA(At, 1, 1); PG8_STAGE(PG8_SB(1, 0), b3, voffB); PG8_STAGE(PG8_SB(1, 1), b3 + hstepB, voffB); PG8_STAGE(PG8_SA(1, 0), a3, voffA);
;             PG8_WAIT_V(8); PG8_WAIT_L(0); PG8_BAR; PG8_MMA(1, 0, At, B0); PG8_MMA(1, 1, At, B1); PG8_BAR; PG8_SCHED;
	v_mfma_f32_16x16x32_bf16 v[66:69], v[168:171], v[210:213], v[66:69]
	s_setprio 0
	s_add_u32 s0, s40, 0x4000
	s_addc_u32 s1, s41, 0
	s_add_i32 s33, s33, s43
	v_lshl_add_u64 v[214:215], s[0:1], 0, v[132:133]
	s_mov_b32 m0, s33
	ds_read_b128 v[172:175], v138 offset:49152
	ds_read_b128 v[176:179], v138 offset:50176
	ds_read_b128 v[180:183], v138 offset:51200
	ds_read_b128 v[184:187], v138 offset:52224
	ds_read_b128 v[188:191], v138 offset:53248
	ds_read_b128 v[194:197], v138 offset:54272
	ds_read_b128 v[206:209], v138 offset:55296
	ds_read_b128 v[210:213], v138 offset:56320
	global_load_lds_dwordx4 v[214:215], off
	s_add_i32 m0, s33, 0x2000
	v_lshl_add_u64 v[214:215], s[0:1], 0, v[134:135]
	s_add_u32 s0, s40, 0x84000
	s_addc_u32 s1, s41, 0
	s_add_i32 s33, s64, s43
	global_load_lds_dwordx4 v[214:215], off
	v_lshl_add_u64 v[214:215], s[0:1], 0, v[132:133]
	s_mov_b32 m0, s33
	s_nop 0
	global_load_lds_dwordx4 v[214:215], off
	v_lshl_add_u64 v[214:215], s[0:1], 0, v[134:135]
	s_add_i32 m0, s33, 0x2000
	s_nop 0
	global_load_lds_dwordx4 v[214:215], off
	v_lshl_add_u64 v[214:215], s[30:31], 0, v[132:133]
	s_mov_b32 m0, s50
	s_nop 0
	global_load_lds_dwordx4 v[214:215], off
	v_lshl_add_u64 v[214:215], s[30:31], 0, v[134:135]
	s_mov_b32 m0, s51
	s_nop 0
	global_load_lds_dwordx4 v[214:215], off
	s_waitcnt vmcnt(8)
	s_waitcnt lgkmcnt(0)
	s_barrier
	s_setprio 1
	s_waitcnt lgkmcnt(0)
	v_mfma_f32_16x16x32_bf16 v[62:65], v[140:143], v[172:175], v[62:65]
	v_mfma_f32_16x16x32_bf16 v[58:61], v[148:151], v[172:175], v[58:61]
	v_mfma_f32_16x16x32_bf16 v[46:49], v[140:143], v[180:183], v[46:49]
	v_mfma_f32_16x16x32_bf16 v[42:45], v[148:151], v[180:183], v[42:45]
	v_mfma_f32_16x16x32_bf16 v[30:33], v[140:143], v[188:191], v[30:33]
	v_mfma_f32_16x16x32_bf16 v[26:29], v[148:151], v[188:191], v[26:29]
	v_mfma_f32_16x16x32_bf16 v[14:17], v[140:143], v[206:209], v[14:17]
	v_mfma_f32_16x16x32_bf16 v[10:13], v[148:151], v[206:209], v[10:13]
	v_mfma_f32_16x16x32_bf16 v[62:65], v[144:147], v[176:179], v[62:65]
	v_mfma_f32_16x16x32_bf16 v[58:61], v[152:155], v[176:179], v[58:61]
	v_mfma_f32_16x16x32_bf16 v[46:49], v[144:147], v[184:187], v[46:49]
	v_mfma_f32_16x16x32_bf16 v[42:45], v[152:155], v[184:187], v[42:45]
	v_mfma_f32_16x16x32_bf16 v[30:33], v[144:147], v[194:197], v[30:33]
	v_mfma_f32_16x16x32_bf16 v[26:29], v[152:155], v[194:197], v[26:29]
	v_mfma_f32_16x16x32_bf16 v[14:17], v[144:147], v[210:213], v[14:17]
	v_mfma_f32_16x16x32_bf16 v[10:13], v[152:155], v[210:213], v[10:13]
	s_setprio 0
	s_setprio 1
	v_mfma_f32_16x16x32_bf16 v[54:57], v[156:159], v[172:175], v[54:57]
	v_mfma_f32_16x16x32_bf16 v[50:53], v[164:167], v[172:175], v[50:53]
	v_mfma_f32_16x16x32_bf16 v[38:41], v[156:159], v[180:183], v[38:41]
	v_mfma_f32_16x16x32_bf16 v[34:37], v[164:167], v[180:183], v[34:37]
	v_mfma_f32_16x16x32_bf16 v[22:25], v[156:159], v[188:191], v[22:25]
	v_mfma_f32_16x16x32_bf16 v[18:21], v[164:167], v[188:191], v[18:21]
	v_mfma_f32_16x16x32_bf16 v[6:9], v[156:159], v[206:209], v[6:9]
	v_mfma_f32_16x16x32_bf16 v[2:5], v[164:167], v[206:209], v[2:5]
	v_mfma_f32_16x16x32_bf16 v[54:57], v[160:163], v[176:179], v[54:57]
	v_mfma_f32_16x16x32_bf16 v[50:53], v[168:171], v[176:179], v[50:53]
	v_mfma_f32_16x16x32_bf16 v[38:41], v[160:163], v[184:187], v[38:41]
	v_mfma_f32_16x16x32_bf16 v[34:37], v[168:171], v[184:187], v[34:37]
	v_mfma_f32_16x16x32_bf16 v[22:25], v[160:163], v[194:197], v[22:25]
	v_mfma_f32_16x16x32_bf16 v[18:21], v[168:171], v[194:197], v[18:21]
	v_mfma_f32_16x16x32_bf16 v[6:9], v[160:163], v[210:213], v[6:9]
	s_barrier
	v_mfma_f32_16x16x32_bf16 v[2:5], v[168:171], v[210:213], v[2:5]
	s_setprio 0
	s_add_i32 s61, s61, 2
	s_add_u32 s22, s22, 0x8000
	s_addc_u32 s23, s23, 0
	s_add_u32 s57, s57, 0x8000
	s_addc_u32 s60, s60, 0
	s_cmp_lt_u32 s61, 30
	s_cbranch_scc1 .LBB0_1154
	s_andn2_b64 vcc, exec, s[18:19]
	s_cbranch_vccnz .LBB0_1157
	s_barrier

; #define PG8_STAGE(bufoff, gbase, voff) do { _Pragma("unroll") for (int _i = 0; _i < 2; ++_i) \
;         __builtin_amdgcn_global_load_lds((const unsigned*)((const char*)(gbase) + (voff)[_i]), (LAS unsigned*)(lds + (bufoff) + ldsw + _i * 8192), 16, 0, 0); } while (0)
; #define PG8_LDA(dst, b, h) do { _Pragma("unroll") for (int m = 0; m < 4; ++m) _Pragma("unroll") for (int k = 0; k < 2; ++k) dst[m][k] = *(const LAS bf16x8*)(lds + PG8_SA(b, h) + aoff + m * 2048 + k * 1024); } while (0)
; #define PG8_LDB(dst, b, h) do { _Pragma("unroll") for (int n = 0; n < 2; ++n) _Pragma("unroll") for (int k = 0; k < 2; ++k) dst[n][k] = *(const LAS bf16x8*)(lds + PG8_SB(b, h) + boff + n * 2048 + k * 1024); } while (0)
; #define PG8_MMA(ai, bj, At, Bt) do { __builtin_amdgcn_s_setprio(1); _Pragma("unroll") for (int m = 0; m < 4; ++m) _Pragma("unroll") for (int n = 0; n < 2; ++n) _Pragma("unroll") for (int k = 0; k < 2; ++k) \
;         acc[ai][bj][m][n] = __builtin_amdgcn_mfma_f32_16x16x32_bf16(Bt[n][k], At[m][k], acc[ai][bj][m][n], 0, 0, 0); __builtin_amdgcn_s_setprio(0); } while (0)
; #define PG8_WAIT_V(n) asm volatile("s_waitcnt vmcnt(" #n ")" ::: "memory")
; #define PG8_WAIT_L(n) asm volatile("s_waitcnt lgkmcnt(" #n ")" ::: "memory")
; #define PG8_BAR __builtin_amdgcn_s_barrier()
; #define PG8_SCHED __builtin_amdgcn_sched_barrier(0)
; template <class Epi, bool ALIGN_EPI = true, bool SP2 = true>
; __device__ __forceinline__ void gemm_phase(LAS unsigned char* lds, const Gemm g, const StaticOrder& S, const Epi& E, unsigned long long& tacc, const int tmode) {
;     ...
;             const bool last = (t == nt - 2);
;             const char* a1 = cA + (size_t)(t + 1) * kstepA;
;             const char* a2 = last ? nA : cA + (size_t)(t + 2) * kstepA; const char* b2 = last ? nB : cB + (size_t)(t + 2) * kstepB;
;             const char* a3 = a2 + kstepA; const char* b3 = b2 + kstepB;
;             if constexpr (SP2) {
;             PG8_LDB(B0, 0, 0); PG8_LDB(B1, 0, 1); PG8_SCHED; PG8_LDA(At, 0, 0); PG8_STAGE(PG8_SA(1, 1), a1 + hstepA, voffA);
;             PG8_WAIT_V(8); PG8_WAIT_L(0); PG8_BAR; PG8_MMA(0, 0, At, B0); PG8_MMA(0, 1, At, B1); PG8_BAR; PG8_SCHED;
;             PG8_LDA(At, 0, 1); PG8_STAGE(PG8_SB(0, 0), b2, voffB); PG8_STAGE(PG8_SB(0, 1), b2 + hstepB, voffB); PG8_STAGE(PG8_SA(0, 0), a2, voffA);
.LBB0_1224:
	s_add_u32 s0, s22, s46
	s_addc_u32 s1, s23, s47
	s_add_u32 s0, s0, 0x8000
	s_addc_u32 s1, s1, 0
	s_add_u32 s33, s36, s46
	s_addc_u32 s48, s37, s47
	s_cmp_eq_u32 s46, 0x1f8000
	s_cselect_b32 s34, vcc_lo, s0
	s_cselect_b32 s35, s27, s1
	s_cselect_b32 s50, vcc_hi, s33
	s_cselect_b32 s51, s25, s48
	s_add_u32 s48, s34, 0x4000
	s_addc_u32 s49, s35, 0
	s_add_i32 s0, 0, 0x10000
	v_add_u32_e32 v141, s0, v139
	s_add_i32 s33, 0, 0x14000
	ds_read_b128 v[142:145], v141
	ds_read_b128 v[146:149], v141 offset:1024
	ds_read_b128 v[150:153], v141 offset:2048
	ds_read_b128 v[154:157], v141 offset:3072
	v_add_u32_e32 v141, s33, v139
	ds_read_b128 v[158:161], v141
	ds_read_b128 v[162:165], v141 offset:1024
	ds_read_b128 v[166:169], v141 offset:2048
	ds_read_b128 v[170:173], v141 offset:3072
	v_lshl_add_u64 v[190:191], v[134:135], 0, s[46:47]
	s_add_i32 m0, s65, 0xc000
	ds_read_b128 v[174:177], v140
	ds_read_b128 v[178:181], v140 offset:1024
	ds_read_b128 v[182:185], v140 offset:2048
	ds_read_b128 v[186:189], v140 offset:3072
	ds_read_b128 v[194:197], v140 offset:4096
	ds_read_b128 v[206:209], v140 offset:5120
	ds_read_b128 v[210:213], v140 offset:6144
	ds_read_b128 v[214:217], v140 offset:7168
	global_load_lds_dwordx4 v[190:191], off
	v_lshl_add_u64 v[190:191], v[136:137], 0, s[46:47]
	s_add_i32 m0, s65, 0xe000
	s_nop 0
	global_load_lds_dwordx4 v[190:191], off
	s_waitcnt vmcnt(8)
	s_waitcnt lgkmcnt(0)
	s_barrier
	s_setprio 1
	s_waitcnt lgkmcnt(0)
	v_mfma_f32_16x16x32_bf16 v[126:129], v[142:145], v[174:177], v[126:129]
	v_mfma_f32_16x16x32_bf16 v[122:125], v[150:153], v[174:177], v[122:125]
	v_mfma_f32_16x16x32_bf16 v[118:121], v[142:145], v[182:185], v[118:121]
	v_mfma_f32_16x16x32_bf16 v[110:113], v[150:153], v[182:185], v[110:113]
	v_mfma_f32_16x16x32_bf16 v[102:105], v[142:145], v[194:197], v[102:105]
	v_mfma_f32_16x16x32_bf16 v[94:97], v[150:153], v[194:197], v[94:97]
	v_mfma_f32_16x16x32_bf16 v[86:89], v[142:145], v[210:213], v[86:89]
	v_mfma_f32_16x16x32_bf16 v[78:81], v[150:153], v[210:213], v[78:81]
	v_mfma_f32_16x16x32_bf16 v[126:129], v[146:149], v[178:181], v[126:129]
	v_mfma_f32_16x16x32_bf16 v[122:125], v[154:157], v[178:181], v[122:125]
	v_mfma_f32_16x16x32_bf16 v[118:121], v[146:149], v[186:189], v[118:121]
	v_mfma_f32_16x16x32_bf16 v[110:113], v[154:157], v[186:189], v[110:113]
	v_mfma_f32_16x16x32_bf16 v[102:105], v[146:149], v[206:209], v[102:105]
	v_mfma_f32_16x16x32_bf16 v[94:97], v[154:157], v[206:209], v[94:97]
	v_mfma_f32_16x16x32_bf16 v[86:89], v[146:149], v[214:217], v[86:89]
	v_mfma_f32_16x16x32_bf16 v[78:81], v[154:157], v[214:217], v[78:81]
	s_setprio 0
	s_setprio 1
	v_mfma_f32_16x16x32_bf16 v[114:117], v[158:161], v[174:177], v[114:117]
	v_mfma_f32_16x16x32_bf16 v[106:109], v[166:169], v[174:177], v[106:109]
	v_mfma_f32_16x16x32_bf16 v[98:101], v[158:161], v[182:185], v[98:101]
	v_mfma_f32_16x16x32_bf16 v[90:93], v[166:169], v[182:185], v[90:93]
	v_mfma_f32_16x16x32_bf16 v[82:85], v[158:161], v[194:197], v[82:85]
	v_mfma_f32_16x16x32_bf16 v[74:77], v[166:169], v[194:197], v[74:77]
	v_mfma_f32_16x16x32_bf16 v[70:73], v[158:161], v[210:213], v[70:73]
	v_mfma_f32_16x16x32_bf16 v[66:69], v[166:169], v[210:213], v[66:69]
	v_mfma_f32_16x16x32_bf16 v[114:117], v[162:165], v[178:181], v[114:117]
	v_mfma_f32_16x16x32_bf16 v[106:109], v[170:173], v[178:181], v[106:109]
	v_mfma_f32_16x16x32_bf16 v[98:101], v[162:165], v[186:189], v[98:101]
	v_mfma_f32_16x16x32_bf16 v[90:93], v[170:173], v[186:189], v[90:93]
	v_mfma_f32_16x16x32_bf16 v[82:85], v[162:165], v[206:209], v[82:85]
	v_mfma_f32_16x16x32_bf16 v[74:77], v[170:173], v[206:209], v[74:77]
	v_mfma_f32_16x16x32_bf16 v[70:73], v[162:165], v[214:217], v[70:73]
	s_barrier
	v_mfma_f32_16x16x32_bf16 v[66:69], v[170:173], v[214:217], v[66:69]
	s_setprio 0
	s_add_i32 s0, s0, s61
	v_lshl_add_u64 v[190:191], s[50:51], 0, v[130:131]
	s_mov_b32 m0, s0
	ds_read_b128 v[174:177], v140 offset:16384
	ds_read_b128 v[178:181], v140 offset:17408
	ds_read_b128 v[182:185], v140 offset:18432
	ds_read_b128 v[186:189], v140 offset:19456
	ds_read_b128 v[194:197], v140 offset:20480
	ds_read_b128 v[206:209], v140 offset:21504
	ds_read_b128 v[210:213], v140 offset:22528
	ds_read_b128 v[214:217], v140 offset:23552
	global_load_lds_dwordx4 v[190:191], off
	s_add_i32 m0, s0, 0x2000
	s_add_u32 s0, s50, 0x200000
	v_lshl_add_u64 v[190:191], s[50:51], 0, v[132:133]
	s_addc_u32 s1, s51, 0
	s_add_i32 s33, s33, s61
	global_load_lds_dwordx4 v[190:191], off
	v_lshl_add_u64 v[190:191], s[0:1], 0, v[130:131]
	s_mov_b32 m0, s33
	s_nop 0
	global_load_lds_dwordx4 v[190:191], off
	v_lshl_add_u64 v[190:191], s[0:1], 0, v[132:133]
	s_add_i32 m0, s33, 0x2000
	s_nop 0
	global_load_lds_dwordx4 v[190:191], off
	v_lshl_add_u64 v[190:191], s[34:35], 0, v[130:131]
	s_mov_b32 m0, s65
	s_nop 0
	global_load_lds_dwordx4 v[190:191], off
	v_lshl_add_u64 v[190:191], s[34:35], 0, v[132:133]
	s_mov_b32 m0, s71
	s_nop 0
	global_load_lds_dwordx4 v[190:191], off
	s_waitcnt vmcnt(8)
	s_waitcnt lgkmcnt(0)
	s_barrier
; #define PG8_STAGE(bufoff, gbase, voff) do { _Pragma("unroll") for (int _i = 0; _i < 2; ++_i) \
;         __builtin_amdgcn_global_load_lds((const unsigned*)((const char*)(gbase) + (voff)[_i]), (LAS unsigned*)(lds + (bufoff) + ldsw + _i * 8192), 16, 0, 0); } while (0)
; #define PG8_LDA(dst, b, h) do { _Pragma("unroll") for (int m = 0; m < 4; ++m) _Pragma("unroll") for (int k = 0; k < 2; ++k) dst[m][k] = *(const LAS bf16x8*)(lds + PG8_SA(b, h) + aoff + m * 2048 + k * 1024); } while (0)
; #define PG8_LDB(dst, b, h) do { _Pragma("unroll") for (int n = 0; n < 2; ++n) _Pragma("unroll") for (int k = 0; k < 2; ++k) dst[n][k] = *(const LAS bf16x8*)(lds + PG8_SB(b, h) + boff + n * 2048 + k * 1024); } while (0)
; #define PG8_MMA(ai, bj, At, Bt) do { __builtin_amdgcn_s_setprio(1); _Pragma("unroll") for (int m = 0; m < 4; ++m) _Pragma("unroll") for (int n = 0; n < 2; ++n) _Pragma("unroll") for (int k = 0; k < 2; ++k) \
;         acc[ai][bj][m][n] = __builtin_amdgcn_mfma_f32_16x16x32_bf16(Bt[n][k], At[m][k], acc[ai][bj][m][n], 0, 0, 0); __builtin_amdgcn_s_setprio(0); } while (0)
; #define PG8_WAIT_V(n) asm volatile("s_waitcnt vmcnt(" #n ")" ::: "memory")
; #define PG8_WAIT_L(n) asm volatile("s_waitcnt lgkmcnt(" #n ")" ::: "memory")
; #define PG8_BAR __builtin_amdgcn_s_barrier()
; #define PG8_SCHED __builtin_amdgcn_sched_barrier(0)
; template <class Epi, bool ALIGN_EPI = true, bool SP2 = true>
; __device__ __forceinline__ void gemm_phase(LAS unsigned char* lds, const Gemm g, const StaticOrder& S, const Epi& E, unsigned long long& tacc, const int tmode) {
;     ...
;             PG8_WAIT_V(8); PG8_WAIT_L(0); PG8_BAR; PG8_MMA(1, 0, At, B0); PG8_MMA(1, 1, At, B1); PG8_BAR; PG8_SCHED;
;             PG8_LDB(B0, 1, 0); PG8_LDB(B1, 1, 1); PG8_SCHED; PG8_LDA(At, 1, 0); PG8_STAGE(PG8_SA(0, 1), a2 + hstepA, voffA);
;             PG8_WAIT_V(8); PG8_WAIT_L(0); PG8_BAR; PG8_MMA(0, 0, At, B0); PG8_MMA(0, 1, At, B1); PG8_BAR; PG8_SCHED;
	s_setprio 1
	s_waitcnt lgkmcnt(0)
	v_mfma_f32_16x16x32_bf16 v[62:65], v[142:145], v[174:177], v[62:65]
	v_mfma_f32_16x16x32_bf16 v[58:61], v[150:153], v[174:177], v[58:61]
	v_mfma_f32_16x16x32_bf16 v[54:57], v[142:145], v[182:185], v[54:57]
	v_mfma_f32_16x16x32_bf16 v[46:49], v[150:153], v[182:185], v[46:49]
	v_mfma_f32_16x16x32_bf16 v[38:41], v[142:145], v[194:197], v[38:41]
	v_mfma_f32_16x16x32_bf16 v[30:33], v[150:153], v[194:197], v[30:33]
	v_mfma_f32_16x16x32_bf16 v[22:25], v[142:145], v[210:213], v[22:25]
	v_mfma_f32_16x16x32_bf16 v[14:17], v[150:153], v[210:213], v[14:17]
	v_mfma_f32_16x16x32_bf16 v[62:65], v[146:149], v[178:181], v[62:65]
	v_mfma_f32_16x16x32_bf16 v[58:61], v[154:157], v[178:181], v[58:61]
	v_mfma_f32_16x16x32_bf16 v[54:57], v[146:149], v[186:189], v[54:57]
	v_mfma_f32_16x16x32_bf16 v[46:49], v[154:157], v[186:189], v[46:49]
	v_mfma_f32_16x16x32_bf16 v[38:41], v[146:149], v[206:209], v[38:41]
	v_mfma_f32_16x16x32_bf16 v[30:33], v[154:157], v[206:209], v[30:33]
	v_mfma_f32_16x16x32_bf16 v[22:25], v[146:149], v[214:217], v[22:25]
	v_mfma_f32_16x16x32_bf16 v[14:17], v[154:157], v[214:217], v[14:17]
	s_setprio 0
	s_setprio 1
	v_mfma_f32_16x16x32_bf16 v[50:53], v[158:161], v[174:177], v[50:53]
	v_mfma_f32_16x16x32_bf16 v[42:45], v[166:169], v[174:177], v[42:45]
	v_mfma_f32_16x16x32_bf16 v[34:37], v[158:161], v[182:185], v[34:37]
	v_mfma_f32_16x16x32_bf16 v[26:29], v[166:169], v[182:185], v[26:29]
	v_mfma_f32_16x16x32_bf16 v[18:21], v[158:161], v[194:197], v[18:21]
	v_mfma_f32_16x16x32_bf16 v[10:13], v[166:169], v[194:197], v[10:13]
	v_mfma_f32_16x16x32_bf16 v[6:9], v[158:161], v[210:213], v[6:9]
	v_mfma_f32_16x16x32_bf16 v[2:5], v[166:169], v[210:213], v[2:5]
	v_mfma_f32_16x16x32_bf16 v[50:53], v[162:165], v[178:181], v[50:53]
	v_mfma_f32_16x16x32_bf16 v[42:45], v[170:173], v[178:181], v[42:45]
	v_mfma_f32_16x16x32_bf16 v[34:37], v[162:165], v[186:189], v[34:37]
	v_mfma_f32_16x16x32_bf16 v[26:29], v[170:173], v[186:189], v[26:29]
	v_mfma_f32_16x16x32_bf16 v[18:21], v[162:165], v[206:209], v[18:21]
	v_mfma_f32_16x16x32_bf16 v[10:13], v[170:173], v[206:209], v[10:13]
	v_mfma_f32_16x16x32_bf16 v[6:9], v[162:165], v[214:217], v[6:9]
	s_barrier
	v_mfma_f32_16x16x32_bf16 v[2:5], v[170:173], v[214:217], v[2:5]
	s_setprio 0
	s_add_i32 s33, 0, 0x18000
	v_add_u32_e32 v141, s33, v139
	s_add_i32 s64, 0, 0x1c000
	ds_read_b128 v[142:145], v141
	ds_read_b128 v[146:149], v141 offset:1024
	ds_read_b128 v[150:153], v141 offset:2048
	ds_read_b128 v[154:157], v141 offset:3072
	v_add_u32_e32 v141, s64, v139
	ds_read_b128 v[158:161], v141
	ds_read_b128 v[162:165], v141 offset:1024
	ds_read_b128 v[166:169], v141 offset:2048
	ds_read_b128 v[170:173], v141 offset:3072
	s_add_u32 s0, s34, 0x200000
	s_addc_u32 s1, s35, 0
	s_mov_b32 m0, s72
	v_lshl_add_u64 v[190:191], s[0:1], 0, v[130:131]
	ds_read_b128 v[174:177], v140 offset:32768
	ds_read_b128 v[178:181], v140 offset:33792
	ds_read_b128 v[182:185], v140 offset:34816
	ds_read_b128 v[186:189], v140 offset:35840
	ds_read_b128 v[194:197], v140 offset:36864
	ds_read_b128 v[206:209], v140 offset:37888
	ds_read_b128 v[210:213], v140 offset:38912
	ds_read_b128 v[214:217], v140 offset:39936
	global_load_lds_dwordx4 v[190:191], off
	v_lshl_add_u64 v[190:191], s[0:1], 0, v[132:133]
	s_mov_b32 m0, s73
	s_nop 0
	global_load_lds_dwordx4 v[190:191], off
	s_waitcnt vmcnt(8)
	s_waitcnt lgkmcnt(0)
	s_barrier
	s_setprio 1
	s_waitcnt lgkmcnt(0)
	v_mfma_f32_16x16x32_bf16 v[126:129], v[142:145], v[174:177], v[126:129]
	v_mfma_f32_16x16x32_bf16 v[122:125], v[150:153], v[174:177], v[122:125]
	v_mfma_f32_16x16x32_bf16 v[118:121], v[142:145], v[182:185], v[118:121]
	v_mfma_f32_16x16x32_bf16 v[110:113], v[150:153], v[182:185], v[110:113]
	v_mfma_f32_16x16x32_bf16 v[102:105], v[142:145], v[194:197], v[102:105]
	v_mfma_f32_16x16x32_bf16 v[94:97], v[150:153], v[194:197], v[94:97]
	v_mfma_f32_16x16x32_bf16 v[86:89], v[142:145], v[210:213], v[86:89]
	v_mfma_f32_16x16x32_bf16 v[78:81], v[150:153], v[210:213], v[78:81]
	v_mfma_f32_16x16x32_bf16 v[126:129], v[146:149], v[178:181], v[126:129]
	v_mfma_f32_16x16x32_bf16 v[122:125], v[154:157], v[178:181], v[122:125]
	v_mfma_f32_16x16x32_bf16 v[118:121], v[146:149], v[186:189], v[118:121]
	v_mfma_f32_16x16x32_bf16 v[110:113], v[154:157], v[186:189], v[110:113]
	v_mfma_f32_16x16x32_bf16 v[102:105], v[146:149], v[206:209], v[102:105]
	v_mfma_f32_16x16x32_bf16 v[94:97], v[154:157], v[206:209], v[94:97]
	v_mfma_f32_16x16x32_bf16 v[86:89], v[146:149], v[214:217], v[86:89]
	v_mfma_f32_16x16x32_bf16 v[78:81], v[154:157], v[214:217], v[78:81]
	s_setprio 0
	s_setprio 1
	v_mfma_f32_16x16x32_bf16 v[114:117], v[158:161], v[174:177], v[114:117]
	v_mfma_f32_16x16x32_bf16 v[106:109], v[166:169], v[174:177], v[106:109]
	v_mfma_f32_16x16x32_bf16 v[98:101], v[158:161], v[182:185], v[98:101]
	v_mfma_f32_16x16x32_bf16 v[90:93], v[166:169], v[182:185], v[90:93]
	v_mfma_f32_16x16x32_bf16 v[82:85], v[158:161], v[194:197], v[82:85]
	v_mfma_f32_16x16x32_bf16 v[74:77], v[166:169], v[194:197], v[74:77]
	v_mfma_f32_16x16x32_bf16 v[70:73], v[158:161], v[210:213], v[70:73]
	v_mfma_f32_16x16x32_bf16 v[66:69], v[166:169], v[210:213], v[66:69]
	v_mfma_f32_16x16x32_bf16 v[114:117], v[162:165], v[178:181], v[114:117]
	v_mfma_f32_16x16x32_bf16 v[106:109], v[170:173], v[178:181], v[106:109]
	v_mfma_f32_16x16x32_bf16 v[98:101], v[162:165], v[186:189], v[98:101]
	v_mfma_f32_16x16x32_bf16 v[90:93], v[170:173], v[186:189], v[90:93]
	v_mfma_f32_16x16x32_bf16 v[82:85], v[162:165], v[206:209], v[82:85]
	v_mfma_f32_16x16x32_bf16 v[74:77], v[170:173], v[206:209], v[74:77]
	v_mfma_f32_16x16x32_bf16 v[70:73], v[162:165], v[214:217], v[70:73]
	s_barrier
; #define PG8_STAGE(bufoff, gbase, voff) do { _Pragma("unroll") for (int _i = 0; _i < 2; ++_i) \
;         __builtin_amdgcn_global_load_lds((const unsigned*)((const char*)(gbase) + (voff)[_i]), (LAS unsigned*)(lds + (bufoff) + ldsw + _i * 8192), 16, 0, 0); } while (0)
; #define PG8_LDA(dst, b, h) do { _Pragma("unroll") for (int m = 0; m < 4; ++m) _Pragma("unroll") for (int k = 0; k < 2; ++k) dst[m][k] = *(const LAS bf16x8*)(lds + PG8_SA(b, h) + aoff + m * 2048 + k * 1024); } while (0)
; #define PG8_MMA(ai, bj, At, Bt) do { __builtin_amdgcn_s_setprio(1); _Pragma("unroll") for (int m = 0; m < 4; ++m) _Pragma("unroll") for (int n = 0; n < 2; ++n) _Pragma("unroll") for (int k = 0; k < 2; ++k) \
;         acc[ai][bj][m][n] = __builtin_amdgcn_mfma_f32_16x16x32_bf16(Bt[n][k], At[m][k], acc[ai][bj][m][n], 0, 0, 0); __builtin_amdgcn_s_setprio(0); } while (0)
; #define PG8_WAIT_V(n) asm volatile("s_waitcnt vmcnt(" #n ")" ::: "memory")
; #define PG8_WAIT_L(n) asm volatile("s_waitcnt lgkmcnt(" #n ")" ::: "memory")
; #define PG8_BAR __builtin_amdgcn_s_barrier()
; #define PG8_SCHED __builtin_amdgcn_sched_barrier(0)
; template <class Epi, bool ALIGN_EPI = true, bool SP2 = true>
; __device__ __forceinline__ void gemm_phase(LAS unsigned char* lds, const Gemm g, const StaticOrder& S, const Epi& E, unsigned long long& tacc, const int tmode) {
;     ...
;             PG8_WAIT_V(8); PG8_WAIT_L(0); PG8_BAR; PG8_MMA(0, 0, At, B0); PG8_MMA(0, 1, At, B1); PG8_BAR; PG8_SCHED;
;             PG8_LDA(At, 1, 1); PG8_STAGE(PG8_SB(1, 0), b3, voffB); PG8_STAGE(PG8_SB(1, 1), b3 + hstepB, voffB); PG8_STAGE(PG8_SA(1, 0), a3, voffA);
;             PG8_WAIT_V(8); PG8_WAIT_L(0); PG8_BAR; PG8_MMA(1, 0, At, B0); PG8_MMA(1, 1, At, B1); PG8_BAR; PG8_SCHED;
	v_mfma_f32_16x16x32_bf16 v[66:69], v[170:173], v[214:217], v[66:69]
	s_setprio 0
	s_add_u32 s0, s50, 0x4000
	s_addc_u32 s1, s51, 0
	s_add_i32 s33, s33, s61
	v_lshl_add_u64 v[190:191], s[0:1], 0, v[130:131]
	s_mov_b32 m0, s33
	ds_read_b128 v[174:177], v140 offset:49152
	ds_read_b128 v[178:181], v140 offset:50176
	ds_read_b128 v[182:185], v140 offset:51200
	ds_read_b128 v[186:189], v140 offset:52224
	ds_read_b128 v[194:197], v140 offset:53248
	ds_read_b128 v[206:209], v140 offset:54272
	ds_read_b128 v[210:213], v140 offset:55296
	ds_read_b128 v[214:217], v140 offset:56320
	global_load_lds_dwordx4 v[190:191], off
	s_add_i32 m0, s33, 0x2000
	v_lshl_add_u64 v[190:191], s[0:1], 0, v[132:133]
	s_add_u32 s0, s50, 0x204000
	s_addc_u32 s1, s51, 0
	s_add_i32 s33, s64, s61
	global_load_lds_dwordx4 v[190:191], off
	v_lshl_add_u64 v[190:191], s[0:1], 0, v[130:131]
	s_mov_b32 m0, s33
	s_nop 0
	global_load_lds_dwordx4 v[190:191], off
	v_lshl_add_u64 v[190:191], s[0:1], 0, v[132:133]
	s_add_i32 m0, s33, 0x2000
	s_nop 0
	global_load_lds_dwordx4 v[190:191], off
	v_lshl_add_u64 v[190:191], s[48:49], 0, v[130:131]
	s_mov_b32 m0, s84
	s_nop 0
	global_load_lds_dwordx4 v[190:191], off
	v_lshl_add_u64 v[190:191], s[48:49], 0, v[132:133]
	s_mov_b32 m0, s85
	s_nop 0
	global_load_lds_dwordx4 v[190:191], off
	s_waitcnt vmcnt(8)
	s_waitcnt lgkmcnt(0)
	s_barrier
	s_setprio 1
	s_waitcnt lgkmcnt(0)
	v_mfma_f32_16x16x32_bf16 v[62:65], v[142:145], v[174:177], v[62:65]
	v_mfma_f32_16x16x32_bf16 v[58:61], v[150:153], v[174:177], v[58:61]
	v_mfma_f32_16x16x32_bf16 v[54:57], v[142:145], v[182:185], v[54:57]
	v_mfma_f32_16x16x32_bf16 v[46:49], v[150:153], v[182:185], v[46:49]
	v_mfma_f32_16x16x32_bf16 v[38:41], v[142:145], v[194:197], v[38:41]
	v_mfma_f32_16x16x32_bf16 v[30:33], v[150:153], v[194:197], v[30:33]
	v_mfma_f32_16x16x32_bf16 v[22:25], v[142:145], v[210:213], v[22:25]
	v_mfma_f32_16x16x32_bf16 v[14:17], v[150:153], v[210:213], v[14:17]
	v_mfma_f32_16x16x32_bf16 v[62:65], v[146:149], v[178:181], v[62:65]
	v_mfma_f32_16x16x32_bf16 v[58:61], v[154:157], v[178:181], v[58:61]
	v_mfma_f32_16x16x32_bf16 v[54:57], v[146:149], v[186:189], v[54:57]
	v_mfma_f32_16x16x32_bf16 v[46:49], v[154:157], v[186:189], v[46:49]
	v_mfma_f32_16x16x32_bf16 v[38:41], v[146:149], v[206:209], v[38:41]
	v_mfma_f32_16x16x32_bf16 v[30:33], v[154:157], v[206:209], v[30:33]
	v_mfma_f32_16x16x32_bf16 v[22:25], v[146:149], v[214:217], v[22:25]
	v_mfma_f32_16x16x32_bf16 v[14:17], v[154:157], v[214:217], v[14:17]
	s_setprio 0
	s_setprio 1
	v_mfma_f32_16x16x32_bf16 v[50:53], v[158:161], v[174:177], v[50:53]
	v_mfma_f32_16x16x32_bf16 v[42:45], v[166:169], v[174:177], v[42:45]
	v_mfma_f32_16x16x32_bf16 v[34:37], v[158:161], v[182:185], v[34:37]
	v_mfma_f32_16x16x32_bf16 v[26:29], v[166:169], v[182:185], v[26:29]
	v_mfma_f32_16x16x32_bf16 v[18:21], v[158:161], v[194:197], v[18:21]
	v_mfma_f32_16x16x32_bf16 v[10:13], v[166:169], v[194:197], v[10:13]
	v_mfma_f32_16x16x32_bf16 v[6:9], v[158:161], v[210:213], v[6:9]
	v_mfma_f32_16x16x32_bf16 v[2:5], v[166:169], v[210:213], v[2:5]
	v_mfma_f32_16x16x32_bf16 v[50:53], v[162:165], v[178:181], v[50:53]
	v_mfma_f32_16x16x32_bf16 v[42:45], v[170:173], v[178:181], v[42:45]
	v_mfma_f32_16x16x32_bf16 v[34:37], v[162:165], v[186:189], v[34:37]
	v_mfma_f32_16x16x32_bf16 v[26:29], v[170:173], v[186:189], v[26:29]
	v_mfma_f32_16x16x32_bf16 v[18:21], v[162:165], v[206:209], v[18:21]
	v_mfma_f32_16x16x32_bf16 v[10:13], v[170:173], v[206:209], v[10:13]
	v_mfma_f32_16x16x32_bf16 v[6:9], v[162:165], v[214:217], v[6:9]
	s_barrier
	v_mfma_f32_16x16x32_bf16 v[2:5], v[170:173], v[214:217], v[2:5]
	s_setprio 0
	s_add_i32 s81, s81, 2
	s_add_u32 s46, s46, 0x8000
	s_addc_u32 s47, s47, 0
	s_cmpk_lt_u32 s81, 0x7e
	s_cbranch_scc1 .LBB0_1224
	s_andn2_b64 vcc, exec, s[20:21]
	s_cbranch_vccnz .LBB0_1227
	s_barrier

; #define PG8_STAGE(bufoff, gbase, voff) do { _Pragma("unroll") for (int _i = 0; _i < 2; ++_i) \
;         __builtin_amdgcn_global_load_lds((const unsigned*)((const char*)(gbase) + (voff)[_i]), (LAS unsigned*)(lds + (bufoff) + ldsw + _i * 8192), 16, 0, 0); } while (0)
; #define PG8_LDA(dst, b, h) do { _Pragma("unroll") for (int m = 0; m < 4; ++m) _Pragma("unroll") for (int k = 0; k < 2; ++k) dst[m][k] = *(const LAS bf16x8*)(lds + PG8_SA(b, h) + aoff + m * 2048 + k * 1024); } while (0)
; #define PG8_LDB(dst, b, h) do { _Pragma("unroll") for (int n = 0; n < 2; ++n) _Pragma("unroll") for (int k = 0; k < 2; ++k) dst[n][k] = *(const LAS bf16x8*)(lds + PG8_SB(b, h) + boff + n * 2048 + k * 1024); } while (0)
; #define PG8_MMA(ai, bj, At, Bt) do { __builtin_amdgcn_s_setprio(1); _Pragma("unroll") for (int m = 0; m < 4; ++m) _Pragma("unroll") for (int n = 0; n < 2; ++n) _Pragma("unroll") for (int k = 0; k < 2; ++k) \
;         acc[ai][bj][m][n] = __builtin_amdgcn_mfma_f32_16x16x32_bf16(Bt[n][k], At[m][k], acc[ai][bj][m][n], 0, 0, 0); __builtin_amdgcn_s_setprio(0); } while (0)
; #define PG8_WAIT_V(n) asm volatile("s_waitcnt vmcnt(" #n ")" ::: "memory")
; #define PG8_WAIT_L(n) asm volatile("s_waitcnt lgkmcnt(" #n ")" ::: "memory")
; #define PG8_BAR __builtin_amdgcn_s_barrier()
; #define PG8_SCHED __builtin_amdgcn_sched_barrier(0)
; template <class Epi, bool ALIGN_EPI = true, bool SP2 = true>
; __device__ __forceinline__ void gemm_phase(LAS unsigned char* lds, const Gemm g, const StaticOrder& S, const Epi& E, unsigned long long& tacc, const int tmode) {
;     ...
;             const bool last = (t == nt - 2);
;             const char* a1 = cA + (size_t)(t + 1) * kstepA;
;             const char* a2 = last ? nA : cA + (size_t)(t + 2) * kstepA; const char* b2 = last ? nB : cB + (size_t)(t + 2) * kstepB;
;             const char* a3 = a2 + kstepA; const char* b3 = b2 + kstepB;
;             if constexpr (SP2) {
;             PG8_LDB(B0, 0, 0); PG8_LDB(B1, 0, 1); PG8_SCHED; PG8_LDA(At, 0, 0); PG8_STAGE(PG8_SA(1, 1), a1 + hstepA, voffA);
;             PG8_WAIT_V(8); PG8_WAIT_L(0); PG8_BAR; PG8_MMA(0, 0, At, B0); PG8_MMA(0, 1, At, B1); PG8_BAR; PG8_SCHED;
;             PG8_LDA(At, 0, 1); PG8_STAGE(PG8_SB(0, 0), b2, voffB); PG8_STAGE(PG8_SB(0, 1), b2 + hstepB, voffB); PG8_STAGE(PG8_SA(0, 0), a2, voffA);
.LBB0_1285:
	s_add_u32 s0, s22, s40
	s_addc_u32 s1, s23, s41
	s_add_u32 s0, s0, 0x8000
	s_addc_u32 s1, s1, 0
	s_add_u32 s33, s86, s40
	s_addc_u32 s46, s87, s41
	s_cmp_eq_u32 s40, 0x1f8000
	s_cselect_b32 s34, vcc_lo, s0
	s_cselect_b32 s35, s27, s1
	s_cselect_b32 s48, vcc_hi, s33
	s_cselect_b32 s49, s25, s46
	s_add_u32 s46, s34, 0x4000
	s_addc_u32 s47, s35, 0
	s_add_i32 s0, 0, 0x10000
	v_add_u32_e32 v141, s0, v135
	s_add_i32 s33, 0, 0x14000
	ds_read_b128 v[142:145], v141
	ds_read_b128 v[146:149], v141 offset:1024
	ds_read_b128 v[150:153], v141 offset:2048
	ds_read_b128 v[154:157], v141 offset:3072
	v_add_u32_e32 v141, s33, v135
	ds_read_b128 v[158:161], v141
	ds_read_b128 v[162:165], v141 offset:1024
	ds_read_b128 v[166:169], v141 offset:2048
	ds_read_b128 v[170:173], v141 offset:3072
	v_lshl_add_u64 v[190:191], v[128:129], 0, s[40:41]
	s_add_i32 m0, s60, 0xc000
	ds_read_b128 v[174:177], v140
	ds_read_b128 v[178:181], v140 offset:1024
	ds_read_b128 v[182:185], v140 offset:2048
	ds_read_b128 v[186:189], v140 offset:3072
	ds_read_b128 v[194:197], v140 offset:4096
	ds_read_b128 v[206:209], v140 offset:5120
	ds_read_b128 v[210:213], v140 offset:6144
	ds_read_b128 v[214:217], v140 offset:7168
	global_load_lds_dwordx4 v[190:191], off
	v_lshl_add_u64 v[190:191], v[132:133], 0, s[40:41]
	s_add_i32 m0, s60, 0xe000
	s_nop 0
	global_load_lds_dwordx4 v[190:191], off
	s_waitcnt vmcnt(8)
	s_waitcnt lgkmcnt(0)
	s_barrier
	s_setprio 1
	s_waitcnt lgkmcnt(0)
	v_mfma_f32_16x16x32_bf16 v[118:121], v[142:145], v[174:177], v[118:121]
	v_mfma_f32_16x16x32_bf16 v[114:117], v[150:153], v[174:177], v[114:117]
	v_mfma_f32_16x16x32_bf16 v[136:139], v[142:145], v[182:185], v[136:139]
	v_mfma_f32_16x16x32_bf16 v[86:89], v[150:153], v[182:185], v[86:89]
	v_mfma_f32_16x16x32_bf16 v[110:113], v[142:145], v[194:197], v[110:113]
	v_mfma_f32_16x16x32_bf16 v[102:105], v[150:153], v[194:197], v[102:105]
	v_mfma_f32_16x16x32_bf16 v[122:125], v[142:145], v[210:213], v[122:125]
	v_mfma_f32_16x16x32_bf16 v[78:81], v[150:153], v[210:213], v[78:81]
	v_mfma_f32_16x16x32_bf16 v[118:121], v[146:149], v[178:181], v[118:121]
	v_mfma_f32_16x16x32_bf16 v[114:117], v[154:157], v[178:181], v[114:117]
	v_mfma_f32_16x16x32_bf16 v[136:139], v[146:149], v[186:189], v[136:139]
	v_mfma_f32_16x16x32_bf16 v[86:89], v[154:157], v[186:189], v[86:89]
	v_mfma_f32_16x16x32_bf16 v[110:113], v[146:149], v[206:209], v[110:113]
	v_mfma_f32_16x16x32_bf16 v[102:105], v[154:157], v[206:209], v[102:105]
	v_mfma_f32_16x16x32_bf16 v[122:125], v[146:149], v[214:217], v[122:125]
	v_mfma_f32_16x16x32_bf16 v[78:81], v[154:157], v[214:217], v[78:81]
	s_setprio 0
	s_setprio 1
	v_mfma_f32_16x16x32_bf16 v[98:101], v[158:161], v[174:177], v[98:101]
	v_mfma_f32_16x16x32_bf16 v[82:85], v[166:169], v[174:177], v[82:85]
	v_mfma_f32_16x16x32_bf16 v[90:93], v[158:161], v[182:185], v[90:93]
	v_mfma_f32_16x16x32_bf16 v[94:97], v[166:169], v[182:185], v[94:97]
	v_mfma_f32_16x16x32_bf16 v[106:109], v[158:161], v[194:197], v[106:109]
	v_mfma_f32_16x16x32_bf16 v[74:77], v[166:169], v[194:197], v[74:77]
	v_mfma_f32_16x16x32_bf16 v[70:73], v[158:161], v[210:213], v[70:73]
	v_mfma_f32_16x16x32_bf16 v[66:69], v[166:169], v[210:213], v[66:69]
	v_mfma_f32_16x16x32_bf16 v[98:101], v[162:165], v[178:181], v[98:101]
	v_mfma_f32_16x16x32_bf16 v[82:85], v[170:173], v[178:181], v[82:85]
	v_mfma_f32_16x16x32_bf16 v[90:93], v[162:165], v[186:189], v[90:93]
	v_mfma_f32_16x16x32_bf16 v[94:97], v[170:173], v[186:189], v[94:97]
	v_mfma_f32_16x16x32_bf16 v[106:109], v[162:165], v[206:209], v[106:109]
	v_mfma_f32_16x16x32_bf16 v[74:77], v[170:173], v[206:209], v[74:77]
	v_mfma_f32_16x16x32_bf16 v[70:73], v[162:165], v[214:217], v[70:73]
	s_barrier
	v_mfma_f32_16x16x32_bf16 v[66:69], v[170:173], v[214:217], v[66:69]
	s_setprio 0
	s_add_i32 s0, s0, s57
	v_lshl_add_u64 v[190:191], s[48:49], 0, v[130:131]
	s_mov_b32 m0, s0
	ds_read_b128 v[174:177], v140 offset:16384
	ds_read_b128 v[178:181], v140 offset:17408
	ds_read_b128 v[182:185], v140 offset:18432
	ds_read_b128 v[186:189], v140 offset:19456
	ds_read_b128 v[194:197], v140 offset:20480
	ds_read_b128 v[206:209], v140 offset:21504
	ds_read_b128 v[210:213], v140 offset:22528
	ds_read_b128 v[214:217], v140 offset:23552
	global_load_lds_dwordx4 v[190:191], off
	s_add_i32 m0, s0, 0x2000
	s_add_u32 s0, s48, 0x200000
	v_lshl_add_u64 v[190:191], s[48:49], 0, v[126:127]
	s_addc_u32 s1, s49, 0
	s_add_i32 s33, s33, s57
	global_load_lds_dwordx4 v[190:191], off
	v_lshl_add_u64 v[190:191], s[0:1], 0, v[130:131]
	s_mov_b32 m0, s33
	s_nop 0
	global_load_lds_dwordx4 v[190:191], off
	v_lshl_add_u64 v[190:191], s[0:1], 0, v[126:127]
	s_add_i32 m0, s33, 0x2000
	s_nop 0
	global_load_lds_dwordx4 v[190:191], off
	v_lshl_add_u64 v[190:191], s[34:35], 0, v[130:131]
	s_mov_b32 m0, s60
	s_nop 0
	global_load_lds_dwordx4 v[190:191], off
	v_lshl_add_u64 v[190:191], s[34:35], 0, v[126:127]
	s_mov_b32 m0, s61
	s_nop 0
	global_load_lds_dwordx4 v[190:191], off
	s_waitcnt vmcnt(8)
	s_waitcnt lgkmcnt(0)
	s_barrier
; #define PG8_STAGE(bufoff, gbase, voff) do { _Pragma("unroll") for (int _i = 0; _i < 2; ++_i) \
;         __builtin_amdgcn_global_load_lds((const unsigned*)((const char*)(gbase) + (voff)[_i]), (LAS unsigned*)(lds + (bufoff) + ldsw + _i * 8192), 16, 0, 0); } while (0)
; #define PG8_LDA(dst, b, h) do { _Pragma("unroll") for (int m = 0; m < 4; ++m) _Pragma("unroll") for (int k = 0; k < 2; ++k) dst[m][k] = *(const LAS bf16x8*)(lds + PG8_SA(b, h) + aoff + m * 2048 + k * 1024); } while (0)
; #define PG8_LDB(dst, b, h) do { _Pragma("unroll") for (int n = 0; n < 2; ++n) _Pragma("unroll") for (int k = 0; k < 2; ++k) dst[n][k] = *(const LAS bf16x8*)(lds + PG8_SB(b, h) + boff + n * 2048 + k * 1024); } while (0)
; #define PG8_MMA(ai, bj, At, Bt) do { __builtin_amdgcn_s_setprio(1); _Pragma("unroll") for (int m = 0; m < 4; ++m) _Pragma("unroll") for (int n = 0; n < 2; ++n) _Pragma("unroll") for (int k = 0; k < 2; ++k) \
;         acc[ai][bj][m][n] = __builtin_amdgcn_mfma_f32_16x16x32_bf16(Bt[n][k], At[m][k], acc[ai][bj][m][n], 0, 0, 0); __builtin_amdgcn_s_setprio(0); } while (0)
; #define PG8_WAIT_V(n) asm volatile("s_waitcnt vmcnt(" #n ")" ::: "memory")
; #define PG8_WAIT_L(n) asm volatile("s_waitcnt lgkmcnt(" #n ")" ::: "memory")
; #define PG8_BAR __builtin_amdgcn_s_barrier()
; #define PG8_SCHED __builtin_amdgcn_sched_barrier(0)
; template <class Epi, bool ALIGN_EPI = true, bool SP2 = true>
; __device__ __forceinline__ void gemm_phase(LAS unsigned char* lds, const Gemm g, const StaticOrder& S, const Epi& E, unsigned long long& tacc, const int tmode) {
;     ...
;             PG8_WAIT_V(8); PG8_WAIT_L(0); PG8_BAR; PG8_MMA(1, 0, At, B0); PG8_MMA(1, 1, At, B1); PG8_BAR; PG8_SCHED;
;             PG8_LDB(B0, 1, 0); PG8_LDB(B1, 1, 1); PG8_SCHED; PG8_LDA(At, 1, 0); PG8_STAGE(PG8_SA(0, 1), a2 + hstepA, voffA);
;             PG8_WAIT_V(8); PG8_WAIT_L(0); PG8_BAR; PG8_MMA(0, 0, At, B0); PG8_MMA(0, 1, At, B1); PG8_BAR; PG8_SCHED;
	s_setprio 1
	s_waitcnt lgkmcnt(0)
	v_mfma_f32_16x16x32_bf16 v[62:65], v[142:145], v[174:177], v[62:65]
	v_mfma_f32_16x16x32_bf16 v[58:61], v[150:153], v[174:177], v[58:61]
	v_mfma_f32_16x16x32_bf16 v[54:57], v[142:145], v[182:185], v[54:57]
	v_mfma_f32_16x16x32_bf16 v[46:49], v[150:153], v[182:185], v[46:49]
	v_mfma_f32_16x16x32_bf16 v[38:41], v[142:145], v[194:197], v[38:41]
	v_mfma_f32_16x16x32_bf16 v[30:33], v[150:153], v[194:197], v[30:33]
	v_mfma_f32_16x16x32_bf16 v[22:25], v[142:145], v[210:213], v[22:25]
	v_mfma_f32_16x16x32_bf16 v[14:17], v[150:153], v[210:213], v[14:17]
	v_mfma_f32_16x16x32_bf16 v[62:65], v[146:149], v[178:181], v[62:65]
	v_mfma_f32_16x16x32_bf16 v[58:61], v[154:157], v[178:181], v[58:61]
	v_mfma_f32_16x16x32_bf16 v[54:57], v[146:149], v[186:189], v[54:57]
	v_mfma_f32_16x16x32_bf16 v[46:49], v[154:157], v[186:189], v[46:49]
	v_mfma_f32_16x16x32_bf16 v[38:41], v[146:149], v[206:209], v[38:41]
	v_mfma_f32_16x16x32_bf16 v[30:33], v[154:157], v[206:209], v[30:33]
	v_mfma_f32_16x16x32_bf16 v[22:25], v[146:149], v[214:217], v[22:25]
	v_mfma_f32_16x16x32_bf16 v[14:17], v[154:157], v[214:217], v[14:17]
	s_setprio 0
	s_setprio 1
	v_mfma_f32_16x16x32_bf16 v[50:53], v[158:161], v[174:177], v[50:53]
	v_mfma_f32_16x16x32_bf16 v[42:45], v[166:169], v[174:177], v[42:45]
	v_mfma_f32_16x16x32_bf16 v[34:37], v[158:161], v[182:185], v[34:37]
	v_mfma_f32_16x16x32_bf16 v[26:29], v[166:169], v[182:185], v[26:29]
	v_mfma_f32_16x16x32_bf16 v[18:21], v[158:161], v[194:197], v[18:21]
	v_mfma_f32_16x16x32_bf16 v[10:13], v[166:169], v[194:197], v[10:13]
	v_mfma_f32_16x16x32_bf16 v[6:9], v[158:161], v[210:213], v[6:9]
	v_mfma_f32_16x16x32_bf16 v[2:5], v[166:169], v[210:213], v[2:5]
	v_mfma_f32_16x16x32_bf16 v[50:53], v[162:165], v[178:181], v[50:53]
	v_mfma_f32_16x16x32_bf16 v[42:45], v[170:173], v[178:181], v[42:45]
	v_mfma_f32_16x16x32_bf16 v[34:37], v[162:165], v[186:189], v[34:37]
	v_mfma_f32_16x16x32_bf16 v[26:29], v[170:173], v[186:189], v[26:29]
	v_mfma_f32_16x16x32_bf16 v[18:21], v[162:165], v[206:209], v[18:21]
	v_mfma_f32_16x16x32_bf16 v[10:13], v[170:173], v[206:209], v[10:13]
	v_mfma_f32_16x16x32_bf16 v[6:9], v[162:165], v[214:217], v[6:9]
	s_barrier
	v_mfma_f32_16x16x32_bf16 v[2:5], v[170:173], v[214:217], v[2:5]
	s_setprio 0
	s_add_i32 s33, 0, 0x18000
	v_add_u32_e32 v141, s33, v135
	s_add_i32 s64, 0, 0x1c000
	ds_read_b128 v[142:145], v141
	ds_read_b128 v[146:149], v141 offset:1024
	ds_read_b128 v[150:153], v141 offset:2048
	ds_read_b128 v[154:157], v141 offset:3072
	v_add_u32_e32 v141, s64, v135
	ds_read_b128 v[158:161], v141
	ds_read_b128 v[162:165], v141 offset:1024
	ds_read_b128 v[166:169], v141 offset:2048
	ds_read_b128 v[170:173], v141 offset:3072
	s_add_u32 s0, s34, 0x200000
	s_addc_u32 s1, s35, 0
	s_mov_b32 m0, s65
	v_lshl_add_u64 v[190:191], s[0:1], 0, v[130:131]
	ds_read_b128 v[174:177], v140 offset:32768
	ds_read_b128 v[178:181], v140 offset:33792
	ds_read_b128 v[182:185], v140 offset:34816
	ds_read_b128 v[186:189], v140 offset:35840
	ds_read_b128 v[194:197], v140 offset:36864
	ds_read_b128 v[206:209], v140 offset:37888
	ds_read_b128 v[210:213], v140 offset:38912
	ds_read_b128 v[214:217], v140 offset:39936
	global_load_lds_dwordx4 v[190:191], off
	v_lshl_add_u64 v[190:191], s[0:1], 0, v[126:127]
	s_mov_b32 m0, s71
	s_nop 0
	global_load_lds_dwordx4 v[190:191], off
	s_waitcnt vmcnt(8)
	s_waitcnt lgkmcnt(0)
	s_barrier
	s_setprio 1
	s_waitcnt lgkmcnt(0)
	v_mfma_f32_16x16x32_bf16 v[118:121], v[142:145], v[174:177], v[118:121]
	v_mfma_f32_16x16x32_bf16 v[114:117], v[150:153], v[174:177], v[114:117]
	v_mfma_f32_16x16x32_bf16 v[136:139], v[142:145], v[182:185], v[136:139]
	v_mfma_f32_16x16x32_bf16 v[86:89], v[150:153], v[182:185], v[86:89]
	v_mfma_f32_16x16x32_bf16 v[110:113], v[142:145], v[194:197], v[110:113]
	v_mfma_f32_16x16x32_bf16 v[102:105], v[150:153], v[194:197], v[102:105]
	v_mfma_f32_16x16x32_bf16 v[122:125], v[142:145], v[210:213], v[122:125]
	v_mfma_f32_16x16x32_bf16 v[78:81], v[150:153], v[210:213], v[78:81]
	v_mfma_f32_16x16x32_bf16 v[118:121], v[146:149], v[178:181], v[118:121]
	v_mfma_f32_16x16x32_bf16 v[114:117], v[154:157], v[178:181], v[114:117]
	v_mfma_f32_16x16x32_bf16 v[136:139], v[146:149], v[186:189], v[136:139]
	v_mfma_f32_16x16x32_bf16 v[86:89], v[154:157], v[186:189], v[86:89]
	v_mfma_f32_16x16x32_bf16 v[110:113], v[146:149], v[206:209], v[110:113]
	v_mfma_f32_16x16x32_bf16 v[102:105], v[154:157], v[206:209], v[102:105]
	v_mfma_f32_16x16x32_bf16 v[122:125], v[146:149], v[214:217], v[122:125]
	v_mfma_f32_16x16x32_bf16 v[78:81], v[154:157], v[214:217], v[78:81]
	s_setprio 0
	s_setprio 1
	v_mfma_f32_16x16x32_bf16 v[98:101], v[158:161], v[174:177], v[98:101]
	v_mfma_f32_16x16x32_bf16 v[82:85], v[166:169], v[174:177], v[82:85]
	v_mfma_f32_16x16x32_bf16 v[90:93], v[158:161], v[182:185], v[90:93]
	v_mfma_f32_16x16x32_bf16 v[94:97], v[166:169], v[182:185], v[94:97]
	v_mfma_f32_16x16x32_bf16 v[106:109], v[158:161], v[194:197], v[106:109]
	v_mfma_f32_16x16x32_bf16 v[74:77], v[166:169], v[194:197], v[74:77]
	v_mfma_f32_16x16x32_bf16 v[70:73], v[158:161], v[210:213], v[70:73]
	v_mfma_f32_16x16x32_bf16 v[66:69], v[166:169], v[210:213], v[66:69]
	v_mfma_f32_16x16x32_bf16 v[98:101], v[162:165], v[178:181], v[98:101]
	v_mfma_f32_16x16x32_bf16 v[82:85], v[170:173], v[178:181], v[82:85]
	v_mfma_f32_16x16x32_bf16 v[90:93], v[162:165], v[186:189], v[90:93]
	v_mfma_f32_16x16x32_bf16 v[94:97], v[170:173], v[186:189], v[94:97]
	v_mfma_f32_16x16x32_bf16 v[106:109], v[162:165], v[206:209], v[106:109]
	v_mfma_f32_16x16x32_bf16 v[74:77], v[170:173], v[206:209], v[74:77]
	v_mfma_f32_16x16x32_bf16 v[70:73], v[162:165], v[214:217], v[70:73]
	s_barrier
; #define PG8_STAGE(bufoff, gbase, voff) do { _Pragma("unroll") for (int _i = 0; _i < 2; ++_i) \
;         __builtin_amdgcn_global_load_lds((const unsigned*)((const char*)(gbase) + (voff)[_i]), (LAS unsigned*)(lds + (bufoff) + ldsw + _i * 8192), 16, 0, 0); } while (0)
; #define PG8_LDA(dst, b, h) do { _Pragma("unroll") for (int m = 0; m < 4; ++m) _Pragma("unroll") for (int k = 0; k < 2; ++k) dst[m][k] = *(const LAS bf16x8*)(lds + PG8_SA(b, h) + aoff + m * 2048 + k * 1024); } while (0)
; #define PG8_MMA(ai, bj, At, Bt) do { __builtin_amdgcn_s_setprio(1); _Pragma("unroll") for (int m = 0; m < 4; ++m) _Pragma("unroll") for (int n = 0; n < 2; ++n) _Pragma("unroll") for (int k = 0; k < 2; ++k) \
;         acc[ai][bj][m][n] = __builtin_amdgcn_mfma_f32_16x16x32_bf16(Bt[n][k], At[m][k], acc[ai][bj][m][n], 0, 0, 0); __builtin_amdgcn_s_setprio(0); } while (0)
; #define PG8_WAIT_V(n) asm volatile("s_waitcnt vmcnt(" #n ")" ::: "memory")
; #define PG8_WAIT_L(n) asm volatile("s_waitcnt lgkmcnt(" #n ")" ::: "memory")
; #define PG8_BAR __builtin_amdgcn_s_barrier()
; #define PG8_SCHED __builtin_amdgcn_sched_barrier(0)
; template <class Epi, bool ALIGN_EPI = true, bool SP2 = true>
; __device__ __forceinline__ void gemm_phase(LAS unsigned char* lds, const Gemm g, const StaticOrder& S, const Epi& E, unsigned long long& tacc, const int tmode) {
;     ...
;             PG8_WAIT_V(8); PG8_WAIT_L(0); PG8_BAR; PG8_MMA(0, 0, At, B0); PG8_MMA(0, 1, At, B1); PG8_BAR; PG8_SCHED;
;             PG8_LDA(At, 1, 1); PG8_STAGE(PG8_SB(1, 0), b3, voffB); PG8_STAGE(PG8_SB(1, 1), b3 + hstepB, voffB); PG8_STAGE(PG8_SA(1, 0), a3, voffA);
;             PG8_WAIT_V(8); PG8_WAIT_L(0); PG8_BAR; PG8_MMA(1, 0, At, B0); PG8_MMA(1, 1, At, B1); PG8_BAR; PG8_SCHED;
	v_mfma_f32_16x16x32_bf16 v[66:69], v[170:173], v[214:217], v[66:69]
	s_setprio 0
	s_add_u32 s0, s48, 0x4000
	s_addc_u32 s1, s49, 0
	s_add_i32 s33, s33, s57
	v_lshl_add_u64 v[190:191], s[0:1], 0, v[130:131]
	s_mov_b32 m0, s33
	ds_read_b128 v[174:177], v140 offset:49152
	ds_read_b128 v[178:181], v140 offset:50176
	ds_read_b128 v[182:185], v140 offset:51200
	ds_read_b128 v[186:189], v140 offset:52224
	ds_read_b128 v[194:197], v140 offset:53248
	ds_read_b128 v[206:209], v140 offset:54272
	ds_read_b128 v[210:213], v140 offset:55296
	ds_read_b128 v[214:217], v140 offset:56320
	global_load_lds_dwordx4 v[190:191], off
	s_add_i32 m0, s33, 0x2000
	v_lshl_add_u64 v[190:191], s[0:1], 0, v[126:127]
	s_add_u32 s0, s48, 0x204000
	s_addc_u32 s1, s49, 0
	s_add_i32 s33, s64, s57
	global_load_lds_dwordx4 v[190:191], off
	v_lshl_add_u64 v[190:191], s[0:1], 0, v[130:131]
	s_mov_b32 m0, s33
	s_nop 0
	global_load_lds_dwordx4 v[190:191], off
	v_lshl_add_u64 v[190:191], s[0:1], 0, v[126:127]
	s_add_i32 m0, s33, 0x2000
	s_nop 0
	global_load_lds_dwordx4 v[190:191], off
	v_lshl_add_u64 v[190:191], s[46:47], 0, v[130:131]
	s_mov_b32 m0, s73
	s_nop 0
	global_load_lds_dwordx4 v[190:191], off
	v_lshl_add_u64 v[190:191], s[46:47], 0, v[126:127]
	s_mov_b32 m0, s81
	s_nop 0
	global_load_lds_dwordx4 v[190:191], off
	s_waitcnt vmcnt(8)
	s_waitcnt lgkmcnt(0)
	s_barrier
	s_setprio 1
	s_waitcnt lgkmcnt(0)
	v_mfma_f32_16x16x32_bf16 v[62:65], v[142:145], v[174:177], v[62:65]
	v_mfma_f32_16x16x32_bf16 v[58:61], v[150:153], v[174:177], v[58:61]
	v_mfma_f32_16x16x32_bf16 v[54:57], v[142:145], v[182:185], v[54:57]
	v_mfma_f32_16x16x32_bf16 v[46:49], v[150:153], v[182:185], v[46:49]
	v_mfma_f32_16x16x32_bf16 v[38:41], v[142:145], v[194:197], v[38:41]
	v_mfma_f32_16x16x32_bf16 v[30:33], v[150:153], v[194:197], v[30:33]
	v_mfma_f32_16x16x32_bf16 v[22:25], v[142:145], v[210:213], v[22:25]
	v_mfma_f32_16x16x32_bf16 v[14:17], v[150:153], v[210:213], v[14:17]
	v_mfma_f32_16x16x32_bf16 v[62:65], v[146:149], v[178:181], v[62:65]
	v_mfma_f32_16x16x32_bf16 v[58:61], v[154:157], v[178:181], v[58:61]
	v_mfma_f32_16x16x32_bf16 v[54:57], v[146:149], v[186:189], v[54:57]
	v_mfma_f32_16x16x32_bf16 v[46:49], v[154:157], v[186:189], v[46:49]
	v_mfma_f32_16x16x32_bf16 v[38:41], v[146:149], v[206:209], v[38:41]
	v_mfma_f32_16x16x32_bf16 v[30:33], v[154:157], v[206:209], v[30:33]
	v_mfma_f32_16x16x32_bf16 v[22:25], v[146:149], v[214:217], v[22:25]
	v_mfma_f32_16x16x32_bf16 v[14:17], v[154:157], v[214:217], v[14:17]
	s_setprio 0
	s_setprio 1
	v_mfma_f32_16x16x32_bf16 v[50:53], v[158:161], v[174:177], v[50:53]
	v_mfma_f32_16x16x32_bf16 v[42:45], v[166:169], v[174:177], v[42:45]
	v_mfma_f32_16x16x32_bf16 v[34:37], v[158:161], v[182:185], v[34:37]
	v_mfma_f32_16x16x32_bf16 v[26:29], v[166:169], v[182:185], v[26:29]
	v_mfma_f32_16x16x32_bf16 v[18:21], v[158:161], v[194:197], v[18:21]
	v_mfma_f32_16x16x32_bf16 v[10:13], v[166:169], v[194:197], v[10:13]
	v_mfma_f32_16x16x32_bf16 v[6:9], v[158:161], v[210:213], v[6:9]
	v_mfma_f32_16x16x32_bf16 v[2:5], v[166:169], v[210:213], v[2:5]
	v_mfma_f32_16x16x32_bf16 v[50:53], v[162:165], v[178:181], v[50:53]
	v_mfma_f32_16x16x32_bf16 v[42:45], v[170:173], v[178:181], v[42:45]
	v_mfma_f32_16x16x32_bf16 v[34:37], v[162:165], v[186:189], v[34:37]
	v_mfma_f32_16x16x32_bf16 v[26:29], v[170:173], v[186:189], v[26:29]
	v_mfma_f32_16x16x32_bf16 v[18:21], v[162:165], v[206:209], v[18:21]
	v_mfma_f32_16x16x32_bf16 v[10:13], v[170:173], v[206:209], v[10:13]
	v_mfma_f32_16x16x32_bf16 v[6:9], v[162:165], v[214:217], v[6:9]
	s_barrier
	v_mfma_f32_16x16x32_bf16 v[2:5], v[170:173], v[214:217], v[2:5]
	s_setprio 0
	s_add_i32 s72, s72, 2
	s_add_u32 s40, s40, 0x8000
	s_addc_u32 s41, s41, 0
	s_cmpk_lt_u32 s72, 0x7e
	s_cbranch_scc1 .LBB0_1285
	s_andn2_b64 vcc, exec, s[20:21]
	s_cbranch_vccnz .LBB0_1288
	s_barrier
